# v66 + GEMM K-loop section edges: s_setprio 1 before the section barrier, satisfied lgkmcnt(0) after it removed, mid-block setprio flip pair removed, s_setprio 0 after the closing barrier (no SALU betw
# speedup vs baseline: 1.0166x; 1.0166x over previous
; #define PG8_STAGE(bufoff, gbase, voff) do { _Pragma("unroll") for (int _i = 0; _i < 2; ++_i) \
;         __builtin_amdgcn_global_load_lds((const unsigned*)((const char*)(gbase) + (voff)[_i]), (LAS unsigned*)(lds + (bufoff) + ldsw + _i * 8192), 16, 0, 0); } while (0)
; #define PG8_LDA(dst, b, h) do { _Pragma("unroll") for (int m = 0; m < 4; ++m) _Pragma("unroll") for (int k = 0; k < 2; ++k) dst[m][k] = *(const LAS bf16x8*)(lds + PG8_SA(b, h) + aoff + m * 2048 + k * 1024); } while (0)
; #define PG8_LDB(dst, b, h) do { _Pragma("unroll") for (int n = 0; n < 2; ++n) _Pragma("unroll") for (int k = 0; k < 2; ++k) dst[n][k] = *(const LAS bf16x8*)(lds + PG8_SB(b, h) + boff + n * 2048 + k * 1024); } while (0)
; #define PG8_MMA(ai, bj, At, Bt) do { __builtin_amdgcn_s_setprio(1); _Pragma("unroll") for (int m = 0; m < 4; ++m) _Pragma("unroll") for (int n = 0; n < 2; ++n) _Pragma("unroll") for (int k = 0; k < 2; ++k) \
;         acc[ai][bj][m][n] = __builtin_amdgcn_mfma_f32_16x16x32_bf16(Bt[n][k], At[m][k], acc[ai][bj][m][n], 0, 0, 0); __builtin_amdgcn_s_setprio(0); } while (0)
; #define PG8_WAIT_V(n) asm volatile("s_waitcnt vmcnt(" #n ")" ::: "memory")
; #define PG8_WAIT_L(n) asm volatile("s_waitcnt lgkmcnt(" #n ")" ::: "memory")
; #define PG8_BAR __builtin_amdgcn_s_barrier()
; #define PG8_SCHED __builtin_amdgcn_sched_barrier(0)
; template <class Epi, bool ALIGN_EPI = PG8_ALIGN, bool SP2 = PG8_SP2>
; __device__ __forceinline__ void gemm_phase(LAS uchar* lds, const Gemm g, const StaticOrder& S, const Epi& E) {
;     ...
;             PG8_LDB(B0, 0, 0); PG8_LDB(B1, 0, 1); PG8_SCHED; PG8_LDA(At, 0, 0); PG8_STAGE(PG8_SA(1, 1), a1 + hstepA, voffA);
;             PG8_WAIT_V(8); PG8_WAIT_L(0); PG8_BAR; PG8_MMA(0, 0, At, B0); PG8_MMA(0, 1, At, B1); PG8_BAR; PG8_SCHED;
;             PG8_LDA(At, 0, 1); PG8_STAGE(PG8_SB(0, 0), b2, voffB); PG8_STAGE(PG8_SB(0, 1), b2 + hstepB, voffB); PG8_STAGE(PG8_SA(0, 0), a2, voffA);
;             PG8_WAIT_V(8); PG8_WAIT_L(0); PG8_BAR; PG8_MMA(1, 0, At, B0); PG8_MMA(1, 1, At, B1); PG8_BAR; PG8_SCHED;
.Lrw_done_345_0_pl:
	s_waitcnt lgkmcnt(0)
	s_setprio 1
	s_barrier
	v_mfma_f32_16x16x32_bf16 v[126:129], v[164:167], v[204:207], 0
	v_mfma_f32_16x16x32_bf16 v[122:125], v[176:179], v[204:207], 0
	v_mfma_f32_16x16x32_bf16 v[118:121], v[164:167], v[212:215], 0
	v_mfma_f32_16x16x32_bf16 v[110:113], v[176:179], v[212:215], 0
	v_mfma_f32_16x16x32_bf16 v[102:105], v[164:167], v[220:223], 0
	v_mfma_f32_16x16x32_bf16 v[94:97], v[176:179], v[220:223], 0
	v_mfma_f32_16x16x32_bf16 v[86:89], v[164:167], v[228:231], 0
	v_mfma_f32_16x16x32_bf16 v[78:81], v[176:179], v[228:231], 0
	v_mfma_f32_16x16x32_bf16 v[126:129], v[172:175], v[208:211], v[126:129]
	v_mfma_f32_16x16x32_bf16 v[122:125], v[184:187], v[208:211], v[122:125]
	v_mfma_f32_16x16x32_bf16 v[118:121], v[172:175], v[216:219], v[118:121]
	v_mfma_f32_16x16x32_bf16 v[110:113], v[184:187], v[216:219], v[110:113]
	v_mfma_f32_16x16x32_bf16 v[102:105], v[172:175], v[224:227], v[102:105]
	v_mfma_f32_16x16x32_bf16 v[94:97], v[184:187], v[224:227], v[94:97]
	v_mfma_f32_16x16x32_bf16 v[86:89], v[172:175], v[232:235], v[86:89]
	v_mfma_f32_16x16x32_bf16 v[78:81], v[184:187], v[232:235], v[78:81]
	v_mfma_f32_16x16x32_bf16 v[114:117], v[188:191], v[204:207], 0
	v_mfma_f32_16x16x32_bf16 v[106:109], v[196:199], v[204:207], 0
	v_mfma_f32_16x16x32_bf16 v[98:101], v[188:191], v[212:215], 0
	v_mfma_f32_16x16x32_bf16 v[90:93], v[196:199], v[212:215], 0
	v_mfma_f32_16x16x32_bf16 v[82:85], v[188:191], v[220:223], 0
	v_mfma_f32_16x16x32_bf16 v[74:77], v[196:199], v[220:223], 0
	v_mfma_f32_16x16x32_bf16 v[70:73], v[188:191], v[228:231], 0
	v_mfma_f32_16x16x32_bf16 v[66:69], v[196:199], v[228:231], 0
	v_mfma_f32_16x16x32_bf16 v[114:117], v[192:195], v[208:211], v[114:117]
	v_mfma_f32_16x16x32_bf16 v[106:109], v[200:203], v[208:211], v[106:109]
	v_mfma_f32_16x16x32_bf16 v[98:101], v[192:195], v[216:219], v[98:101]
	v_mfma_f32_16x16x32_bf16 v[90:93], v[200:203], v[216:219], v[90:93]
	v_mfma_f32_16x16x32_bf16 v[82:85], v[192:195], v[224:227], v[82:85]
	v_mfma_f32_16x16x32_bf16 v[74:77], v[200:203], v[224:227], v[74:77]
	v_mfma_f32_16x16x32_bf16 v[70:73], v[192:195], v[232:235], v[70:73]
	v_mfma_f32_16x16x32_bf16 v[66:69], v[200:203], v[232:235], v[66:69]
	s_barrier
	s_setprio 0
	s_add_i32 s16, s41, s23
	v_lshl_add_u64 v[168:169], s[4:5], 0, v[134:135]
	s_mov_b32 m0, s16
	ds_read_b128 v[204:207], v171 offset:16384
	ds_read_b128 v[208:211], v171 offset:17408
	ds_read_b128 v[212:215], v171 offset:18432
	ds_read_b128 v[216:219], v171 offset:19456
	ds_read_b128 v[220:223], v171 offset:20480
	ds_read_b128 v[224:227], v171 offset:21504
	ds_read_b128 v[228:231], v171 offset:22528
	ds_read_b128 v[232:235], v171 offset:23552
	global_load_lds_dwordx4 v[168:169], off
	s_add_i32 m0, s16, 0x2000
	s_add_u32 s16, s4, 0x44000
	v_lshl_add_u64 v[180:181], s[4:5], 0, v[130:131]
	s_addc_u32 s17, s5, 0
	s_add_i32 s41, s42, s23
	global_load_lds_dwordx4 v[180:181], off
	v_lshl_add_u64 v[236:237], s[16:17], 0, v[134:135]
	s_mov_b32 m0, s41
	v_lshl_add_u64 v[238:239], s[20:21], 0, v[132:133]
	global_load_lds_dwordx4 v[236:237], off
	v_lshl_add_u64 v[236:237], s[16:17], 0, v[130:131]
	s_add_i32 m0, s41, 0x2000
	s_nop 0
	global_load_lds_dwordx4 v[236:237], off
	v_lshl_add_u64 v[236:237], s[20:21], 0, v[156:157]
	s_mov_b32 m0, s25
	s_nop 0
	global_load_lds_dwordx4 v[236:237], off
	s_mov_b32 m0, s26
	s_nop 0
	global_load_lds_dwordx4 v[238:239], off
	s_cmp_eq_u32 s97, 1
	s_cbranch_scc0 .Lrw_std_345_1_pl
	s_waitcnt vmcnt(24)
	s_branch .Lrw_done_345_1_pl

; #define PG8_STAGE(bufoff, gbase, voff) do { _Pragma("unroll") for (int _i = 0; _i < 2; ++_i) \
;         __builtin_amdgcn_global_load_lds((const unsigned*)((const char*)(gbase) + (voff)[_i]), (LAS unsigned*)(lds + (bufoff) + ldsw + _i * 8192), 16, 0, 0); } while (0)
; #define PG8_LDA(dst, b, h) do { _Pragma("unroll") for (int m = 0; m < 4; ++m) _Pragma("unroll") for (int k = 0; k < 2; ++k) dst[m][k] = *(const LAS bf16x8*)(lds + PG8_SA(b, h) + aoff + m * 2048 + k * 1024); } while (0)
; #define PG8_LDB(dst, b, h) do { _Pragma("unroll") for (int n = 0; n < 2; ++n) _Pragma("unroll") for (int k = 0; k < 2; ++k) dst[n][k] = *(const LAS bf16x8*)(lds + PG8_SB(b, h) + boff + n * 2048 + k * 1024); } while (0)
; #define PG8_MMA(ai, bj, At, Bt) do { __builtin_amdgcn_s_setprio(1); _Pragma("unroll") for (int m = 0; m < 4; ++m) _Pragma("unroll") for (int n = 0; n < 2; ++n) _Pragma("unroll") for (int k = 0; k < 2; ++k) \
;         acc[ai][bj][m][n] = __builtin_amdgcn_mfma_f32_16x16x32_bf16(Bt[n][k], At[m][k], acc[ai][bj][m][n], 0, 0, 0); __builtin_amdgcn_s_setprio(0); } while (0)
; #define PG8_WAIT_V(n) asm volatile("s_waitcnt vmcnt(" #n ")" ::: "memory")
; #define PG8_WAIT_L(n) asm volatile("s_waitcnt lgkmcnt(" #n ")" ::: "memory")
; #define PG8_BAR __builtin_amdgcn_s_barrier()
; #define PG8_SCHED __builtin_amdgcn_sched_barrier(0)
; template <class Epi, bool ALIGN_EPI = PG8_ALIGN, bool SP2 = PG8_SP2>
; __device__ __forceinline__ void gemm_phase(LAS uchar* lds, const Gemm g, const StaticOrder& S, const Epi& E) {
;     ...
;             PG8_WAIT_V(8); PG8_WAIT_L(0); PG8_BAR; PG8_MMA(1, 0, At, B0); PG8_MMA(1, 1, At, B1); PG8_BAR; PG8_SCHED;
;             PG8_LDB(B0, 1, 0); PG8_LDB(B1, 1, 1); PG8_SCHED; PG8_LDA(At, 1, 0); PG8_STAGE(PG8_SA(0, 1), a2 + hstepA, voffA);
;             PG8_WAIT_V(8); PG8_WAIT_L(0); PG8_BAR; PG8_MMA(0, 0, At, B0); PG8_MMA(0, 1, At, B1); PG8_BAR; PG8_SCHED;
.Lrw_done_345_1_pl:
	s_waitcnt lgkmcnt(0)
	s_setprio 1
	s_barrier
	v_mfma_f32_16x16x32_bf16 v[62:65], v[164:167], v[204:207], 0
	v_mfma_f32_16x16x32_bf16 v[58:61], v[176:179], v[204:207], 0
	v_mfma_f32_16x16x32_bf16 v[54:57], v[164:167], v[212:215], 0
	v_mfma_f32_16x16x32_bf16 v[46:49], v[176:179], v[212:215], 0
	v_mfma_f32_16x16x32_bf16 v[38:41], v[164:167], v[220:223], 0
	v_mfma_f32_16x16x32_bf16 v[30:33], v[176:179], v[220:223], 0
	v_mfma_f32_16x16x32_bf16 v[22:25], v[164:167], v[228:231], 0
	v_mfma_f32_16x16x32_bf16 v[14:17], v[176:179], v[228:231], 0
	v_mfma_f32_16x16x32_bf16 v[62:65], v[172:175], v[208:211], v[62:65]
	v_mfma_f32_16x16x32_bf16 v[58:61], v[184:187], v[208:211], v[58:61]
	v_mfma_f32_16x16x32_bf16 v[54:57], v[172:175], v[216:219], v[54:57]
	v_mfma_f32_16x16x32_bf16 v[46:49], v[184:187], v[216:219], v[46:49]
	v_mfma_f32_16x16x32_bf16 v[38:41], v[172:175], v[224:227], v[38:41]
	v_mfma_f32_16x16x32_bf16 v[30:33], v[184:187], v[224:227], v[30:33]
	v_mfma_f32_16x16x32_bf16 v[22:25], v[172:175], v[232:235], v[22:25]
	v_mfma_f32_16x16x32_bf16 v[14:17], v[184:187], v[232:235], v[14:17]
	v_mfma_f32_16x16x32_bf16 v[50:53], v[188:191], v[204:207], 0
	v_mfma_f32_16x16x32_bf16 v[42:45], v[196:199], v[204:207], 0
	v_mfma_f32_16x16x32_bf16 v[34:37], v[188:191], v[212:215], 0
	v_mfma_f32_16x16x32_bf16 v[26:29], v[196:199], v[212:215], 0
	v_mfma_f32_16x16x32_bf16 v[18:21], v[188:191], v[220:223], 0
	v_mfma_f32_16x16x32_bf16 v[10:13], v[196:199], v[220:223], 0
	v_mfma_f32_16x16x32_bf16 v[6:9], v[188:191], v[228:231], 0
	v_mfma_f32_16x16x32_bf16 v[2:5], v[196:199], v[228:231], 0
	v_mfma_f32_16x16x32_bf16 v[50:53], v[192:195], v[208:211], v[50:53]
	v_mfma_f32_16x16x32_bf16 v[42:45], v[200:203], v[208:211], v[42:45]
	v_mfma_f32_16x16x32_bf16 v[34:37], v[192:195], v[216:219], v[34:37]
	v_mfma_f32_16x16x32_bf16 v[26:29], v[200:203], v[216:219], v[26:29]
	v_mfma_f32_16x16x32_bf16 v[18:21], v[192:195], v[224:227], v[18:21]
	v_mfma_f32_16x16x32_bf16 v[10:13], v[200:203], v[224:227], v[10:13]
	v_mfma_f32_16x16x32_bf16 v[6:9], v[192:195], v[232:235], v[6:9]
	v_mfma_f32_16x16x32_bf16 v[2:5], v[200:203], v[232:235], v[2:5]
	s_barrier
	s_setprio 0
	s_add_i32 s41, 0, 0x18000
	s_add_i32 s42, 0, 0x1c000
	v_add_u32_e32 v184, s41, v139
	v_add_u32_e32 v200, s42, v139
	ds_read_b128 v[164:167], v184
	ds_read_b128 v[172:175], v184 offset:1024
	ds_read_b128 v[176:179], v184 offset:2048
	ds_read_b128 v[184:187], v184 offset:3072
	ds_read_b128 v[188:191], v200
	ds_read_b128 v[192:195], v200 offset:1024
	ds_read_b128 v[196:199], v200 offset:2048
	ds_read_b128 v[200:203], v200 offset:3072
	s_add_u32 s16, s20, 0x44000
	s_addc_u32 s17, s21, 0
	s_mov_b32 m0, s27
	v_lshl_add_u64 v[240:241], s[16:17], 0, v[156:157]
	ds_read_b128 v[204:207], v171 offset:32768
	ds_read_b128 v[208:211], v171 offset:33792
	ds_read_b128 v[212:215], v171 offset:34816
	ds_read_b128 v[216:219], v171 offset:35840
	ds_read_b128 v[220:223], v171 offset:36864
	ds_read_b128 v[224:227], v171 offset:37888
	ds_read_b128 v[228:231], v171 offset:38912
	ds_read_b128 v[232:235], v171 offset:39936
	global_load_lds_dwordx4 v[240:241], off
	v_lshl_add_u64 v[240:241], s[16:17], 0, v[132:133]
	s_mov_b32 m0, s28
	s_nop 0
	global_load_lds_dwordx4 v[240:241], off
	s_waitcnt vmcnt(8)
	s_waitcnt lgkmcnt(0)
	s_setprio 1
	s_barrier
	v_mfma_f32_16x16x32_bf16 v[126:129], v[164:167], v[204:207], v[126:129]
	v_mfma_f32_16x16x32_bf16 v[122:125], v[176:179], v[204:207], v[122:125]
	v_mfma_f32_16x16x32_bf16 v[118:121], v[164:167], v[212:215], v[118:121]
	v_mfma_f32_16x16x32_bf16 v[110:113], v[176:179], v[212:215], v[110:113]
	v_mfma_f32_16x16x32_bf16 v[102:105], v[164:167], v[220:223], v[102:105]
	v_mfma_f32_16x16x32_bf16 v[94:97], v[176:179], v[220:223], v[94:97]
	v_mfma_f32_16x16x32_bf16 v[86:89], v[164:167], v[228:231], v[86:89]
	v_mfma_f32_16x16x32_bf16 v[78:81], v[176:179], v[228:231], v[78:81]
	v_mfma_f32_16x16x32_bf16 v[126:129], v[172:175], v[208:211], v[126:129]
	v_mfma_f32_16x16x32_bf16 v[122:125], v[184:187], v[208:211], v[122:125]
	v_mfma_f32_16x16x32_bf16 v[118:121], v[172:175], v[216:219], v[118:121]
	v_mfma_f32_16x16x32_bf16 v[110:113], v[184:187], v[216:219], v[110:113]
	v_mfma_f32_16x16x32_bf16 v[102:105], v[172:175], v[224:227], v[102:105]
	v_mfma_f32_16x16x32_bf16 v[94:97], v[184:187], v[224:227], v[94:97]
	v_mfma_f32_16x16x32_bf16 v[86:89], v[172:175], v[232:235], v[86:89]
	v_mfma_f32_16x16x32_bf16 v[78:81], v[184:187], v[232:235], v[78:81]
	v_mfma_f32_16x16x32_bf16 v[114:117], v[188:191], v[204:207], v[114:117]
	v_mfma_f32_16x16x32_bf16 v[106:109], v[196:199], v[204:207], v[106:109]
	v_mfma_f32_16x16x32_bf16 v[98:101], v[188:191], v[212:215], v[98:101]
	v_mfma_f32_16x16x32_bf16 v[90:93], v[196:199], v[212:215], v[90:93]
	v_mfma_f32_16x16x32_bf16 v[82:85], v[188:191], v[220:223], v[82:85]
	v_mfma_f32_16x16x32_bf16 v[74:77], v[196:199], v[220:223], v[74:77]
	v_mfma_f32_16x16x32_bf16 v[70:73], v[188:191], v[228:231], v[70:73]
	v_mfma_f32_16x16x32_bf16 v[66:69], v[196:199], v[228:231], v[66:69]
	v_mfma_f32_16x16x32_bf16 v[114:117], v[192:195], v[208:211], v[114:117]
	v_mfma_f32_16x16x32_bf16 v[106:109], v[200:203], v[208:211], v[106:109]
	v_mfma_f32_16x16x32_bf16 v[98:101], v[192:195], v[216:219], v[98:101]
	v_mfma_f32_16x16x32_bf16 v[90:93], v[200:203], v[216:219], v[90:93]
	v_mfma_f32_16x16x32_bf16 v[82:85], v[192:195], v[224:227], v[82:85]
	v_mfma_f32_16x16x32_bf16 v[74:77], v[200:203], v[224:227], v[74:77]
	v_mfma_f32_16x16x32_bf16 v[70:73], v[192:195], v[232:235], v[70:73]
	v_mfma_f32_16x16x32_bf16 v[66:69], v[200:203], v[232:235], v[66:69]
	s_barrier
; #define PG8_STAGE(bufoff, gbase, voff) do { _Pragma("unroll") for (int _i = 0; _i < 2; ++_i) \
;         __builtin_amdgcn_global_load_lds((const unsigned*)((const char*)(gbase) + (voff)[_i]), (LAS unsigned*)(lds + (bufoff) + ldsw + _i * 8192), 16, 0, 0); } while (0)
; #define PG8_LDA(dst, b, h) do { _Pragma("unroll") for (int m = 0; m < 4; ++m) _Pragma("unroll") for (int k = 0; k < 2; ++k) dst[m][k] = *(const LAS bf16x8*)(lds + PG8_SA(b, h) + aoff + m * 2048 + k * 1024); } while (0)
; #define PG8_LDB(dst, b, h) do { _Pragma("unroll") for (int n = 0; n < 2; ++n) _Pragma("unroll") for (int k = 0; k < 2; ++k) dst[n][k] = *(const LAS bf16x8*)(lds + PG8_SB(b, h) + boff + n * 2048 + k * 1024); } while (0)
; #define PG8_BAR __builtin_amdgcn_s_barrier()
; template <class Epi, bool ALIGN_EPI = PG8_ALIGN, bool SP2 = PG8_SP2>
; __device__ __forceinline__ void gemm_phase(LAS uchar* lds, const Gemm g, const StaticOrder& S, const Epi& E) {
;     ...
;         for (int t = tb; t < tb + tblk; t += 2) {
;             const bool last = (t == nt - 2);
;             const char* a1 = cA + (size_t)(t + 1) * kstep;
;             const char* a2 = last ? nA : cA + (size_t)(t + 2) * kstep; const char* b2 = last ? nB : cB + (size_t)(t + 2) * kstep;
;             const char* a3 = a2 + kstep; const char* b3 = b2 + kstep;
;             if constexpr (SP2) {
;             PG8_LDB(B0, 0, 0); PG8_LDB(B1, 0, 1); PG8_SCHED; PG8_LDA(At, 0, 0); PG8_STAGE(PG8_SA(1, 1), a1 + hstepA, voffA);
;             PG8_WAIT_V(8); PG8_WAIT_L(0); PG8_BAR; PG8_MMA(0, 0, At, B0); PG8_MMA(0, 1, At, B1); PG8_BAR; PG8_SCHED;
;             PG8_LDA(At, 0, 1); PG8_STAGE(PG8_SB(0, 0), b2, voffB); PG8_STAGE(PG8_SB(0, 1), b2 + hstepB, voffB); PG8_STAGE(PG8_SA(0, 0), a2, voffA);
;             PG8_WAIT_V(8); PG8_WAIT_L(0); PG8_BAR; PG8_MMA(1, 0, At, B0); PG8_MMA(1, 1, At, B1); PG8_BAR; PG8_SCHED;
;             PG8_LDB(B0, 1, 0); PG8_LDB(B1, 1, 1); PG8_SCHED; PG8_LDA(At, 1, 0); PG8_STAGE(PG8_SA(0, 1), a2 + hstepA, voffA);
;             PG8_WAIT_V(8); PG8_WAIT_L(0); PG8_BAR; PG8_MMA(0, 0, At, B0); PG8_MMA(0, 1, At, B1); PG8_BAR; PG8_SCHED;
;             PG8_LDA(At, 1, 1); PG8_STAGE(PG8_SB(1, 0), b3, voffB); PG8_STAGE(PG8_SB(1, 1), b3 + hstepB, voffB); PG8_STAGE(PG8_SA(1, 0), a3, voffA);
;             PG8_WAIT_V(8); PG8_WAIT_L(0); PG8_BAR; PG8_MMA(1, 0, At, B0); PG8_MMA(1, 1, At, B1); PG8_BAR; PG8_SCHED;
	s_setprio 0
	s_add_i32 s16, s41, s23
	v_lshl_add_u64 v[168:169], v[168:169], 0, s[84:85]
	s_mov_b32 m0, s16
	ds_read_b128 v[204:207], v171 offset:49152
	ds_read_b128 v[208:211], v171 offset:50176
	ds_read_b128 v[212:215], v171 offset:51200
	ds_read_b128 v[216:219], v171 offset:52224
	ds_read_b128 v[220:223], v171 offset:53248
	ds_read_b128 v[224:227], v171 offset:54272
	ds_read_b128 v[228:231], v171 offset:55296
	ds_read_b128 v[232:235], v171 offset:56320
	global_load_lds_dwordx4 v[168:169], off
	s_add_i32 m0, s16, 0x2000
	s_add_u32 s4, s4, 0x44080
	v_lshl_add_u64 v[168:169], v[180:181], 0, s[84:85]
	s_addc_u32 s5, s5, 0
	s_add_i32 s16, s42, s23
	global_load_lds_dwordx4 v[168:169], off
	v_lshl_add_u64 v[168:169], s[4:5], 0, v[134:135]
	s_mov_b32 m0, s16
	s_nop 0
	global_load_lds_dwordx4 v[168:169], off
	v_lshl_add_u64 v[168:169], s[4:5], 0, v[130:131]
	s_add_i32 m0, s16, 0x2000
	s_nop 0
	global_load_lds_dwordx4 v[168:169], off
	v_lshl_add_u64 v[168:169], v[236:237], 0, s[84:85]
	s_mov_b32 m0, s29
	s_nop 0
	global_load_lds_dwordx4 v[168:169], off
	v_lshl_add_u64 v[168:169], v[238:239], 0, s[84:85]
	s_mov_b32 m0, s30
	s_nop 0
	global_load_lds_dwordx4 v[168:169], off
	s_waitcnt vmcnt(8)
	s_waitcnt lgkmcnt(0)
	s_setprio 1
	s_barrier
	v_mfma_f32_16x16x32_bf16 v[62:65], v[164:167], v[204:207], v[62:65]
	v_mfma_f32_16x16x32_bf16 v[58:61], v[176:179], v[204:207], v[58:61]
	v_mfma_f32_16x16x32_bf16 v[54:57], v[164:167], v[212:215], v[54:57]
	v_mfma_f32_16x16x32_bf16 v[46:49], v[176:179], v[212:215], v[46:49]
	v_mfma_f32_16x16x32_bf16 v[38:41], v[164:167], v[220:223], v[38:41]
	v_mfma_f32_16x16x32_bf16 v[30:33], v[176:179], v[220:223], v[30:33]
	v_mfma_f32_16x16x32_bf16 v[22:25], v[164:167], v[228:231], v[22:25]
	v_mfma_f32_16x16x32_bf16 v[14:17], v[176:179], v[228:231], v[14:17]
	v_mfma_f32_16x16x32_bf16 v[62:65], v[172:175], v[208:211], v[62:65]
	v_mfma_f32_16x16x32_bf16 v[58:61], v[184:187], v[208:211], v[58:61]
	v_mfma_f32_16x16x32_bf16 v[54:57], v[172:175], v[216:219], v[54:57]
	v_mfma_f32_16x16x32_bf16 v[46:49], v[184:187], v[216:219], v[46:49]
	v_mfma_f32_16x16x32_bf16 v[38:41], v[172:175], v[224:227], v[38:41]
	v_mfma_f32_16x16x32_bf16 v[30:33], v[184:187], v[224:227], v[30:33]
	v_mfma_f32_16x16x32_bf16 v[22:25], v[172:175], v[232:235], v[22:25]
	v_mfma_f32_16x16x32_bf16 v[14:17], v[184:187], v[232:235], v[14:17]
	v_mfma_f32_16x16x32_bf16 v[50:53], v[188:191], v[204:207], v[50:53]
	v_mfma_f32_16x16x32_bf16 v[42:45], v[196:199], v[204:207], v[42:45]
	v_mfma_f32_16x16x32_bf16 v[34:37], v[188:191], v[212:215], v[34:37]
	v_mfma_f32_16x16x32_bf16 v[26:29], v[196:199], v[212:215], v[26:29]
	v_mfma_f32_16x16x32_bf16 v[18:21], v[188:191], v[220:223], v[18:21]
	v_mfma_f32_16x16x32_bf16 v[10:13], v[196:199], v[220:223], v[10:13]
	v_mfma_f32_16x16x32_bf16 v[6:9], v[188:191], v[228:231], v[6:9]
	v_mfma_f32_16x16x32_bf16 v[2:5], v[196:199], v[228:231], v[2:5]
	v_mfma_f32_16x16x32_bf16 v[50:53], v[192:195], v[208:211], v[50:53]
	v_mfma_f32_16x16x32_bf16 v[42:45], v[200:203], v[208:211], v[42:45]
	v_mfma_f32_16x16x32_bf16 v[34:37], v[192:195], v[216:219], v[34:37]
	v_mfma_f32_16x16x32_bf16 v[26:29], v[200:203], v[216:219], v[26:29]
	v_mfma_f32_16x16x32_bf16 v[18:21], v[192:195], v[224:227], v[18:21]
	v_mfma_f32_16x16x32_bf16 v[10:13], v[200:203], v[224:227], v[10:13]
	v_mfma_f32_16x16x32_bf16 v[6:9], v[192:195], v[232:235], v[6:9]
	v_mfma_f32_16x16x32_bf16 v[2:5], v[200:203], v[232:235], v[2:5]
	s_barrier
	s_setprio 0
	s_add_i32 s40, s40, 2
	s_add_u32 s38, s38, 0x100
	s_addc_u32 s39, s39, 0
	s_cmp_gt_u32 s40, 13
	s_mov_b64 s[16:17], s[18:19]
.LBB0_345:
	s_add_u32 s18, s16, 0x100
	s_addc_u32 s19, s17, 0
	s_add_i32 s41, 0, 0x10000
	s_cmp_eq_u32 s40, 12
	s_cselect_b32 s21, s7, s19
	s_cselect_b32 s20, s6, s18
	v_add_u32_e32 v168, s41, v139
	s_cselect_b32 s5, s15, s39
	s_cselect_b32 s4, s14, s38
	s_add_i32 s42, 0, 0x14000
	ds_read_b128 v[164:167], v168
	ds_read_b128 v[172:175], v168 offset:1024
	ds_read_b128 v[176:179], v168 offset:2048
	ds_read_b128 v[184:187], v168 offset:3072
	v_add_u32_e32 v168, s42, v139
	ds_read_b128 v[188:191], v168
	ds_read_b128 v[192:195], v168 offset:1024
	ds_read_b128 v[196:199], v168 offset:2048
	ds_read_b128 v[200:203], v168 offset:3072
	v_lshl_add_u64 v[168:169], s[16:17], 0, v[160:161]
	s_add_i32 m0, s25, 0xc000
	ds_read_b128 v[204:207], v171
	ds_read_b128 v[208:211], v171 offset:1024
	ds_read_b128 v[212:215], v171 offset:2048
	ds_read_b128 v[216:219], v171 offset:3072
	ds_read_b128 v[220:223], v171 offset:4096
	ds_read_b128 v[224:227], v171 offset:5120
	ds_read_b128 v[228:231], v171 offset:6144
	ds_read_b128 v[232:235], v171 offset:7168
	global_load_lds_dwordx4 v[168:169], off
	v_lshl_add_u64 v[168:169], s[16:17], 0, v[162:163]
	s_add_i32 m0, s25, 0xe000
	s_nop 0
	global_load_lds_dwordx4 v[168:169], off
	s_waitcnt vmcnt(8)
	s_waitcnt lgkmcnt(0)
	s_setprio 1
	s_barrier
; #define PG8_STAGE(bufoff, gbase, voff) do { _Pragma("unroll") for (int _i = 0; _i < 2; ++_i) \
;         __builtin_amdgcn_global_load_lds((const unsigned*)((const char*)(gbase) + (voff)[_i]), (LAS unsigned*)(lds + (bufoff) + ldsw + _i * 8192), 16, 0, 0); } while (0)
; #define PG8_LDA(dst, b, h) do { _Pragma("unroll") for (int m = 0; m < 4; ++m) _Pragma("unroll") for (int k = 0; k < 2; ++k) dst[m][k] = *(const LAS bf16x8*)(lds + PG8_SA(b, h) + aoff + m * 2048 + k * 1024); } while (0)
; #define PG8_LDB(dst, b, h) do { _Pragma("unroll") for (int n = 0; n < 2; ++n) _Pragma("unroll") for (int k = 0; k < 2; ++k) dst[n][k] = *(const LAS bf16x8*)(lds + PG8_SB(b, h) + boff + n * 2048 + k * 1024); } while (0)
; #define PG8_MMA(ai, bj, At, Bt) do { __builtin_amdgcn_s_setprio(1); _Pragma("unroll") for (int m = 0; m < 4; ++m) _Pragma("unroll") for (int n = 0; n < 2; ++n) _Pragma("unroll") for (int k = 0; k < 2; ++k) \
;         acc[ai][bj][m][n] = __builtin_amdgcn_mfma_f32_16x16x32_bf16(Bt[n][k], At[m][k], acc[ai][bj][m][n], 0, 0, 0); __builtin_amdgcn_s_setprio(0); } while (0)
; #define PG8_WAIT_V(n) asm volatile("s_waitcnt vmcnt(" #n ")" ::: "memory")
; #define PG8_WAIT_L(n) asm volatile("s_waitcnt lgkmcnt(" #n ")" ::: "memory")
; #define PG8_BAR __builtin_amdgcn_s_barrier()
; #define PG8_SCHED __builtin_amdgcn_sched_barrier(0)
; template <class Epi, bool ALIGN_EPI = PG8_ALIGN, bool SP2 = PG8_SP2>
; __device__ __forceinline__ void gemm_phase(LAS uchar* lds, const Gemm g, const StaticOrder& S, const Epi& E) {
;     ...
;             PG8_LDB(B0, 0, 0); PG8_LDB(B1, 0, 1); PG8_SCHED; PG8_LDA(At, 0, 0); PG8_STAGE(PG8_SA(1, 1), a1 + hstepA, voffA);
;             PG8_WAIT_V(8); PG8_WAIT_L(0); PG8_BAR; PG8_MMA(0, 0, At, B0); PG8_MMA(0, 1, At, B1); PG8_BAR; PG8_SCHED;
;             PG8_LDA(At, 0, 1); PG8_STAGE(PG8_SB(0, 0), b2, voffB); PG8_STAGE(PG8_SB(0, 1), b2 + hstepB, voffB); PG8_STAGE(PG8_SA(0, 0), a2, voffA);
;             PG8_WAIT_V(8); PG8_WAIT_L(0); PG8_BAR; PG8_MMA(1, 0, At, B0); PG8_MMA(1, 1, At, B1); PG8_BAR; PG8_SCHED;
	v_mfma_f32_16x16x32_bf16 v[126:129], v[164:167], v[204:207], v[126:129]
	v_mfma_f32_16x16x32_bf16 v[122:125], v[176:179], v[204:207], v[122:125]
	v_mfma_f32_16x16x32_bf16 v[118:121], v[164:167], v[212:215], v[118:121]
	v_mfma_f32_16x16x32_bf16 v[110:113], v[176:179], v[212:215], v[110:113]
	v_mfma_f32_16x16x32_bf16 v[102:105], v[164:167], v[220:223], v[102:105]
	v_mfma_f32_16x16x32_bf16 v[94:97], v[176:179], v[220:223], v[94:97]
	v_mfma_f32_16x16x32_bf16 v[86:89], v[164:167], v[228:231], v[86:89]
	v_mfma_f32_16x16x32_bf16 v[78:81], v[176:179], v[228:231], v[78:81]
	v_mfma_f32_16x16x32_bf16 v[126:129], v[172:175], v[208:211], v[126:129]
	v_mfma_f32_16x16x32_bf16 v[122:125], v[184:187], v[208:211], v[122:125]
	v_mfma_f32_16x16x32_bf16 v[118:121], v[172:175], v[216:219], v[118:121]
	v_mfma_f32_16x16x32_bf16 v[110:113], v[184:187], v[216:219], v[110:113]
	v_mfma_f32_16x16x32_bf16 v[102:105], v[172:175], v[224:227], v[102:105]
	v_mfma_f32_16x16x32_bf16 v[94:97], v[184:187], v[224:227], v[94:97]
	v_mfma_f32_16x16x32_bf16 v[86:89], v[172:175], v[232:235], v[86:89]
	v_mfma_f32_16x16x32_bf16 v[78:81], v[184:187], v[232:235], v[78:81]
	v_mfma_f32_16x16x32_bf16 v[114:117], v[188:191], v[204:207], v[114:117]
	v_mfma_f32_16x16x32_bf16 v[106:109], v[196:199], v[204:207], v[106:109]
	v_mfma_f32_16x16x32_bf16 v[98:101], v[188:191], v[212:215], v[98:101]
	v_mfma_f32_16x16x32_bf16 v[90:93], v[196:199], v[212:215], v[90:93]
	v_mfma_f32_16x16x32_bf16 v[82:85], v[188:191], v[220:223], v[82:85]
	v_mfma_f32_16x16x32_bf16 v[74:77], v[196:199], v[220:223], v[74:77]
	v_mfma_f32_16x16x32_bf16 v[70:73], v[188:191], v[228:231], v[70:73]
	v_mfma_f32_16x16x32_bf16 v[66:69], v[196:199], v[228:231], v[66:69]
	v_mfma_f32_16x16x32_bf16 v[114:117], v[192:195], v[208:211], v[114:117]
	v_mfma_f32_16x16x32_bf16 v[106:109], v[200:203], v[208:211], v[106:109]
	v_mfma_f32_16x16x32_bf16 v[98:101], v[192:195], v[216:219], v[98:101]
	v_mfma_f32_16x16x32_bf16 v[90:93], v[200:203], v[216:219], v[90:93]
	v_mfma_f32_16x16x32_bf16 v[82:85], v[192:195], v[224:227], v[82:85]
	v_mfma_f32_16x16x32_bf16 v[74:77], v[200:203], v[224:227], v[74:77]
	v_mfma_f32_16x16x32_bf16 v[70:73], v[192:195], v[232:235], v[70:73]
	v_mfma_f32_16x16x32_bf16 v[66:69], v[200:203], v[232:235], v[66:69]
	s_barrier
	s_setprio 0
	s_add_i32 s16, s41, s23
	v_lshl_add_u64 v[168:169], s[4:5], 0, v[134:135]
	s_mov_b32 m0, s16
	ds_read_b128 v[204:207], v171 offset:16384
	ds_read_b128 v[208:211], v171 offset:17408
	ds_read_b128 v[212:215], v171 offset:18432
	ds_read_b128 v[216:219], v171 offset:19456
	ds_read_b128 v[220:223], v171 offset:20480
	ds_read_b128 v[224:227], v171 offset:21504
	ds_read_b128 v[228:231], v171 offset:22528
	ds_read_b128 v[232:235], v171 offset:23552
	global_load_lds_dwordx4 v[168:169], off
	s_add_i32 m0, s16, 0x2000
	s_add_u32 s16, s4, 0x44000
	v_lshl_add_u64 v[180:181], s[4:5], 0, v[130:131]
	s_addc_u32 s17, s5, 0
	s_add_i32 s41, s42, s23
	global_load_lds_dwordx4 v[180:181], off
	v_lshl_add_u64 v[236:237], s[16:17], 0, v[134:135]
	s_mov_b32 m0, s41
	v_lshl_add_u64 v[238:239], s[20:21], 0, v[132:133]
	global_load_lds_dwordx4 v[236:237], off
	v_lshl_add_u64 v[236:237], s[16:17], 0, v[130:131]
	s_add_i32 m0, s41, 0x2000
	s_nop 0
	global_load_lds_dwordx4 v[236:237], off
	v_lshl_add_u64 v[236:237], s[20:21], 0, v[156:157]
	s_mov_b32 m0, s25
	s_nop 0
	global_load_lds_dwordx4 v[236:237], off
	s_mov_b32 m0, s26
	s_nop 0
	global_load_lds_dwordx4 v[238:239], off
	s_waitcnt vmcnt(8)
	s_waitcnt lgkmcnt(0)
	s_setprio 1
	s_barrier
	v_mfma_f32_16x16x32_bf16 v[62:65], v[164:167], v[204:207], v[62:65]
	v_mfma_f32_16x16x32_bf16 v[58:61], v[176:179], v[204:207], v[58:61]
	v_mfma_f32_16x16x32_bf16 v[54:57], v[164:167], v[212:215], v[54:57]
	v_mfma_f32_16x16x32_bf16 v[46:49], v[176:179], v[212:215], v[46:49]
	v_mfma_f32_16x16x32_bf16 v[38:41], v[164:167], v[220:223], v[38:41]
	v_mfma_f32_16x16x32_bf16 v[30:33], v[176:179], v[220:223], v[30:33]
	v_mfma_f32_16x16x32_bf16 v[22:25], v[164:167], v[228:231], v[22:25]
	v_mfma_f32_16x16x32_bf16 v[14:17], v[176:179], v[228:231], v[14:17]
	v_mfma_f32_16x16x32_bf16 v[62:65], v[172:175], v[208:211], v[62:65]
	v_mfma_f32_16x16x32_bf16 v[58:61], v[184:187], v[208:211], v[58:61]
	v_mfma_f32_16x16x32_bf16 v[54:57], v[172:175], v[216:219], v[54:57]
	v_mfma_f32_16x16x32_bf16 v[46:49], v[184:187], v[216:219], v[46:49]
	v_mfma_f32_16x16x32_bf16 v[38:41], v[172:175], v[224:227], v[38:41]
	v_mfma_f32_16x16x32_bf16 v[30:33], v[184:187], v[224:227], v[30:33]
	v_mfma_f32_16x16x32_bf16 v[22:25], v[172:175], v[232:235], v[22:25]
	v_mfma_f32_16x16x32_bf16 v[14:17], v[184:187], v[232:235], v[14:17]
	v_mfma_f32_16x16x32_bf16 v[50:53], v[188:191], v[204:207], v[50:53]
	v_mfma_f32_16x16x32_bf16 v[42:45], v[196:199], v[204:207], v[42:45]
	v_mfma_f32_16x16x32_bf16 v[34:37], v[188:191], v[212:215], v[34:37]
	v_mfma_f32_16x16x32_bf16 v[26:29], v[196:199], v[212:215], v[26:29]
	v_mfma_f32_16x16x32_bf16 v[18:21], v[188:191], v[220:223], v[18:21]
	v_mfma_f32_16x16x32_bf16 v[10:13], v[196:199], v[220:223], v[10:13]
	v_mfma_f32_16x16x32_bf16 v[6:9], v[188:191], v[228:231], v[6:9]
	v_mfma_f32_16x16x32_bf16 v[2:5], v[196:199], v[228:231], v[2:5]
	v_mfma_f32_16x16x32_bf16 v[50:53], v[192:195], v[208:211], v[50:53]
	v_mfma_f32_16x16x32_bf16 v[42:45], v[200:203], v[208:211], v[42:45]
	v_mfma_f32_16x16x32_bf16 v[34:37], v[192:195], v[216:219], v[34:37]
	v_mfma_f32_16x16x32_bf16 v[26:29], v[200:203], v[216:219], v[26:29]
	v_mfma_f32_16x16x32_bf16 v[18:21], v[192:195], v[224:227], v[18:21]
	v_mfma_f32_16x16x32_bf16 v[10:13], v[200:203], v[224:227], v[10:13]
	v_mfma_f32_16x16x32_bf16 v[6:9], v[192:195], v[232:235], v[6:9]
	v_mfma_f32_16x16x32_bf16 v[2:5], v[200:203], v[232:235], v[2:5]
	s_barrier
; #define PG8_STAGE(bufoff, gbase, voff) do { _Pragma("unroll") for (int _i = 0; _i < 2; ++_i) \
;         __builtin_amdgcn_global_load_lds((const unsigned*)((const char*)(gbase) + (voff)[_i]), (LAS unsigned*)(lds + (bufoff) + ldsw + _i * 8192), 16, 0, 0); } while (0)
; #define PG8_LDA(dst, b, h) do { _Pragma("unroll") for (int m = 0; m < 4; ++m) _Pragma("unroll") for (int k = 0; k < 2; ++k) dst[m][k] = *(const LAS bf16x8*)(lds + PG8_SA(b, h) + aoff + m * 2048 + k * 1024); } while (0)
; #define PG8_LDB(dst, b, h) do { _Pragma("unroll") for (int n = 0; n < 2; ++n) _Pragma("unroll") for (int k = 0; k < 2; ++k) dst[n][k] = *(const LAS bf16x8*)(lds + PG8_SB(b, h) + boff + n * 2048 + k * 1024); } while (0)
; #define PG8_MMA(ai, bj, At, Bt) do { __builtin_amdgcn_s_setprio(1); _Pragma("unroll") for (int m = 0; m < 4; ++m) _Pragma("unroll") for (int n = 0; n < 2; ++n) _Pragma("unroll") for (int k = 0; k < 2; ++k) \
;         acc[ai][bj][m][n] = __builtin_amdgcn_mfma_f32_16x16x32_bf16(Bt[n][k], At[m][k], acc[ai][bj][m][n], 0, 0, 0); __builtin_amdgcn_s_setprio(0); } while (0)
; #define PG8_WAIT_V(n) asm volatile("s_waitcnt vmcnt(" #n ")" ::: "memory")
; #define PG8_WAIT_L(n) asm volatile("s_waitcnt lgkmcnt(" #n ")" ::: "memory")
; #define PG8_BAR __builtin_amdgcn_s_barrier()
; #define PG8_SCHED __builtin_amdgcn_sched_barrier(0)
; template <class Epi, bool ALIGN_EPI = PG8_ALIGN, bool SP2 = PG8_SP2>
; __device__ __forceinline__ void gemm_phase(LAS uchar* lds, const Gemm g, const StaticOrder& S, const Epi& E) {
;     ...
;             PG8_LDB(B0, 1, 0); PG8_LDB(B1, 1, 1); PG8_SCHED; PG8_LDA(At, 1, 0); PG8_STAGE(PG8_SA(0, 1), a2 + hstepA, voffA);
;             PG8_WAIT_V(8); PG8_WAIT_L(0); PG8_BAR; PG8_MMA(0, 0, At, B0); PG8_MMA(0, 1, At, B1); PG8_BAR; PG8_SCHED;
	s_setprio 0
	s_add_i32 s41, 0, 0x18000
	s_add_i32 s42, 0, 0x1c000
	v_add_u32_e32 v184, s41, v139
	v_add_u32_e32 v200, s42, v139
	ds_read_b128 v[164:167], v184
	ds_read_b128 v[172:175], v184 offset:1024
	ds_read_b128 v[176:179], v184 offset:2048
	ds_read_b128 v[184:187], v184 offset:3072
	ds_read_b128 v[188:191], v200
	ds_read_b128 v[192:195], v200 offset:1024
	ds_read_b128 v[196:199], v200 offset:2048
	ds_read_b128 v[200:203], v200 offset:3072
	s_add_u32 s16, s20, 0x44000
	s_addc_u32 s17, s21, 0
	s_mov_b32 m0, s27
	v_lshl_add_u64 v[240:241], s[16:17], 0, v[156:157]
	ds_read_b128 v[204:207], v171 offset:32768
	ds_read_b128 v[208:211], v171 offset:33792
	ds_read_b128 v[212:215], v171 offset:34816
	ds_read_b128 v[216:219], v171 offset:35840
	ds_read_b128 v[220:223], v171 offset:36864
	ds_read_b128 v[224:227], v171 offset:37888
	ds_read_b128 v[228:231], v171 offset:38912
	ds_read_b128 v[232:235], v171 offset:39936
	global_load_lds_dwordx4 v[240:241], off
	v_lshl_add_u64 v[240:241], s[16:17], 0, v[132:133]
	s_mov_b32 m0, s28
	s_nop 0
	global_load_lds_dwordx4 v[240:241], off
	s_waitcnt vmcnt(8)
	s_waitcnt lgkmcnt(0)
	s_setprio 1
	s_barrier
	v_mfma_f32_16x16x32_bf16 v[126:129], v[164:167], v[204:207], v[126:129]
	v_mfma_f32_16x16x32_bf16 v[122:125], v[176:179], v[204:207], v[122:125]
	v_mfma_f32_16x16x32_bf16 v[118:121], v[164:167], v[212:215], v[118:121]
	v_mfma_f32_16x16x32_bf16 v[110:113], v[176:179], v[212:215], v[110:113]
	v_mfma_f32_16x16x32_bf16 v[102:105], v[164:167], v[220:223], v[102:105]
	v_mfma_f32_16x16x32_bf16 v[94:97], v[176:179], v[220:223], v[94:97]
	v_mfma_f32_16x16x32_bf16 v[86:89], v[164:167], v[228:231], v[86:89]
	v_mfma_f32_16x16x32_bf16 v[78:81], v[176:179], v[228:231], v[78:81]
	v_mfma_f32_16x16x32_bf16 v[126:129], v[172:175], v[208:211], v[126:129]
	v_mfma_f32_16x16x32_bf16 v[122:125], v[184:187], v[208:211], v[122:125]
	v_mfma_f32_16x16x32_bf16 v[118:121], v[172:175], v[216:219], v[118:121]
	v_mfma_f32_16x16x32_bf16 v[110:113], v[184:187], v[216:219], v[110:113]
	v_mfma_f32_16x16x32_bf16 v[102:105], v[172:175], v[224:227], v[102:105]
	v_mfma_f32_16x16x32_bf16 v[94:97], v[184:187], v[224:227], v[94:97]
	v_mfma_f32_16x16x32_bf16 v[86:89], v[172:175], v[232:235], v[86:89]
	v_mfma_f32_16x16x32_bf16 v[78:81], v[184:187], v[232:235], v[78:81]
	v_mfma_f32_16x16x32_bf16 v[114:117], v[188:191], v[204:207], v[114:117]
	v_mfma_f32_16x16x32_bf16 v[106:109], v[196:199], v[204:207], v[106:109]
	v_mfma_f32_16x16x32_bf16 v[98:101], v[188:191], v[212:215], v[98:101]
	v_mfma_f32_16x16x32_bf16 v[90:93], v[196:199], v[212:215], v[90:93]
	v_mfma_f32_16x16x32_bf16 v[82:85], v[188:191], v[220:223], v[82:85]
	v_mfma_f32_16x16x32_bf16 v[74:77], v[196:199], v[220:223], v[74:77]
	v_mfma_f32_16x16x32_bf16 v[70:73], v[188:191], v[228:231], v[70:73]
	v_mfma_f32_16x16x32_bf16 v[66:69], v[196:199], v[228:231], v[66:69]
	v_mfma_f32_16x16x32_bf16 v[114:117], v[192:195], v[208:211], v[114:117]
	v_mfma_f32_16x16x32_bf16 v[106:109], v[200:203], v[208:211], v[106:109]
	v_mfma_f32_16x16x32_bf16 v[98:101], v[192:195], v[216:219], v[98:101]
	v_mfma_f32_16x16x32_bf16 v[90:93], v[200:203], v[216:219], v[90:93]
	v_mfma_f32_16x16x32_bf16 v[82:85], v[192:195], v[224:227], v[82:85]
	v_mfma_f32_16x16x32_bf16 v[74:77], v[200:203], v[224:227], v[74:77]
	v_mfma_f32_16x16x32_bf16 v[70:73], v[192:195], v[232:235], v[70:73]
	v_mfma_f32_16x16x32_bf16 v[66:69], v[200:203], v[232:235], v[66:69]
	s_barrier
; #define PG8_STAGE(bufoff, gbase, voff) do { _Pragma("unroll") for (int _i = 0; _i < 2; ++_i) \
;         __builtin_amdgcn_global_load_lds((const unsigned*)((const char*)(gbase) + (voff)[_i]), (LAS unsigned*)(lds + (bufoff) + ldsw + _i * 8192), 16, 0, 0); } while (0)
; #define PG8_LDA(dst, b, h) do { _Pragma("unroll") for (int m = 0; m < 4; ++m) _Pragma("unroll") for (int k = 0; k < 2; ++k) dst[m][k] = *(const LAS bf16x8*)(lds + PG8_SA(b, h) + aoff + m * 2048 + k * 1024); } while (0)
; #define PG8_MMA(ai, bj, At, Bt) do { __builtin_amdgcn_s_setprio(1); _Pragma("unroll") for (int m = 0; m < 4; ++m) _Pragma("unroll") for (int n = 0; n < 2; ++n) _Pragma("unroll") for (int k = 0; k < 2; ++k) \
;         acc[ai][bj][m][n] = __builtin_amdgcn_mfma_f32_16x16x32_bf16(Bt[n][k], At[m][k], acc[ai][bj][m][n], 0, 0, 0); __builtin_amdgcn_s_setprio(0); } while (0)
; #define PG8_WAIT_V(n) asm volatile("s_waitcnt vmcnt(" #n ")" ::: "memory")
; #define PG8_WAIT_L(n) asm volatile("s_waitcnt lgkmcnt(" #n ")" ::: "memory")
; #define PG8_BAR __builtin_amdgcn_s_barrier()
; #define PG8_SCHED __builtin_amdgcn_sched_barrier(0)
; template <class Epi, bool ALIGN_EPI = PG8_ALIGN, bool SP2 = PG8_SP2>
; __device__ __forceinline__ void gemm_phase(LAS uchar* lds, const Gemm g, const StaticOrder& S, const Epi& E) {
;     ...
;             PG8_LDA(At, 1, 1); PG8_STAGE(PG8_SB(1, 0), b3, voffB); PG8_STAGE(PG8_SB(1, 1), b3 + hstepB, voffB); PG8_STAGE(PG8_SA(1, 0), a3, voffA);
;             PG8_WAIT_V(8); PG8_WAIT_L(0); PG8_BAR; PG8_MMA(1, 0, At, B0); PG8_MMA(1, 1, At, B1); PG8_BAR; PG8_SCHED;
;     __device__ __forceinline__ void operator()(const f32x4 (&acc)[2][2][4][2], const pg8::Unit& u, int wr, int wc, int fr, int fq, int) const {
;         const int row0 = u.pm * 256 + wr * 64 + fr;
;         if (u.pn < 24) {
	s_setprio 0
	s_add_i32 s16, s41, s23
	v_lshl_add_u64 v[168:169], v[168:169], 0, s[84:85]
	s_mov_b32 m0, s16
	ds_read_b128 v[204:207], v171 offset:49152
	ds_read_b128 v[208:211], v171 offset:50176
	ds_read_b128 v[212:215], v171 offset:51200
	ds_read_b128 v[216:219], v171 offset:52224
	ds_read_b128 v[220:223], v171 offset:53248
	ds_read_b128 v[224:227], v171 offset:54272
	ds_read_b128 v[228:231], v171 offset:55296
	ds_read_b128 v[232:235], v171 offset:56320
	global_load_lds_dwordx4 v[168:169], off
	s_add_i32 m0, s16, 0x2000
	s_add_u32 s4, s4, 0x44080
	v_lshl_add_u64 v[168:169], v[180:181], 0, s[84:85]
	s_addc_u32 s5, s5, 0
	s_add_i32 s16, s42, s23
	global_load_lds_dwordx4 v[168:169], off
	v_lshl_add_u64 v[168:169], s[4:5], 0, v[134:135]
	s_mov_b32 m0, s16
	s_nop 0
	global_load_lds_dwordx4 v[168:169], off
	v_lshl_add_u64 v[168:169], s[4:5], 0, v[130:131]
	s_add_i32 m0, s16, 0x2000
	s_nop 0
	global_load_lds_dwordx4 v[168:169], off
	v_lshl_add_u64 v[168:169], v[236:237], 0, s[84:85]
	s_mov_b32 m0, s29
	s_nop 0
	global_load_lds_dwordx4 v[168:169], off
	v_lshl_add_u64 v[168:169], v[238:239], 0, s[84:85]
	s_mov_b32 m0, s30
	s_nop 0
	global_load_lds_dwordx4 v[168:169], off
	s_waitcnt vmcnt(8)
	s_waitcnt lgkmcnt(0)
	s_setprio 1
	s_barrier
	v_mfma_f32_16x16x32_bf16 v[62:65], v[164:167], v[204:207], v[62:65]
	v_mfma_f32_16x16x32_bf16 v[58:61], v[176:179], v[204:207], v[58:61]
	v_mfma_f32_16x16x32_bf16 v[54:57], v[164:167], v[212:215], v[54:57]
	v_mfma_f32_16x16x32_bf16 v[46:49], v[176:179], v[212:215], v[46:49]
	v_mfma_f32_16x16x32_bf16 v[38:41], v[164:167], v[220:223], v[38:41]
	v_mfma_f32_16x16x32_bf16 v[30:33], v[176:179], v[220:223], v[30:33]
	v_mfma_f32_16x16x32_bf16 v[22:25], v[164:167], v[228:231], v[22:25]
	v_mfma_f32_16x16x32_bf16 v[14:17], v[176:179], v[228:231], v[14:17]
	v_mfma_f32_16x16x32_bf16 v[62:65], v[172:175], v[208:211], v[62:65]
	v_mfma_f32_16x16x32_bf16 v[58:61], v[184:187], v[208:211], v[58:61]
	v_mfma_f32_16x16x32_bf16 v[54:57], v[172:175], v[216:219], v[54:57]
	v_mfma_f32_16x16x32_bf16 v[46:49], v[184:187], v[216:219], v[46:49]
	v_mfma_f32_16x16x32_bf16 v[38:41], v[172:175], v[224:227], v[38:41]
	v_mfma_f32_16x16x32_bf16 v[30:33], v[184:187], v[224:227], v[30:33]
	v_mfma_f32_16x16x32_bf16 v[22:25], v[172:175], v[232:235], v[22:25]
	v_mfma_f32_16x16x32_bf16 v[14:17], v[184:187], v[232:235], v[14:17]
	v_mfma_f32_16x16x32_bf16 v[50:53], v[188:191], v[204:207], v[50:53]
	v_mfma_f32_16x16x32_bf16 v[42:45], v[196:199], v[204:207], v[42:45]
	v_mfma_f32_16x16x32_bf16 v[34:37], v[188:191], v[212:215], v[34:37]
	v_mfma_f32_16x16x32_bf16 v[26:29], v[196:199], v[212:215], v[26:29]
	v_mfma_f32_16x16x32_bf16 v[18:21], v[188:191], v[220:223], v[18:21]
	v_mfma_f32_16x16x32_bf16 v[10:13], v[196:199], v[220:223], v[10:13]
	v_mfma_f32_16x16x32_bf16 v[6:9], v[188:191], v[228:231], v[6:9]
	v_mfma_f32_16x16x32_bf16 v[2:5], v[196:199], v[228:231], v[2:5]
	v_mfma_f32_16x16x32_bf16 v[50:53], v[192:195], v[208:211], v[50:53]
	v_mfma_f32_16x16x32_bf16 v[42:45], v[200:203], v[208:211], v[42:45]
	v_mfma_f32_16x16x32_bf16 v[34:37], v[192:195], v[216:219], v[34:37]
	v_mfma_f32_16x16x32_bf16 v[26:29], v[200:203], v[216:219], v[26:29]
	v_mfma_f32_16x16x32_bf16 v[18:21], v[192:195], v[224:227], v[18:21]
	v_mfma_f32_16x16x32_bf16 v[10:13], v[200:203], v[224:227], v[10:13]
	v_mfma_f32_16x16x32_bf16 v[6:9], v[192:195], v[232:235], v[6:9]
	v_mfma_f32_16x16x32_bf16 v[2:5], v[200:203], v[232:235], v[2:5]
	s_barrier
	s_setprio 0
	s_add_i32 s40, s40, 2
	s_add_u32 s38, s38, 0x100
	s_addc_u32 s39, s39, 0
	s_cmp_gt_u32 s40, 13
	s_mov_b64 s[16:17], s[18:19]
	s_cbranch_scc0 .LBB0_345
	s_mov_b32 s97, 0
	s_and_b64 vcc, exec, s[10:11]
	s_cbranch_vccnz .LBB0_350
	v_lshl_add_u32 v164, s37, 8, v1
	s_cmp_gt_i32 s36, 23
	s_mov_b64 s[4:5], -1
	s_cbranch_scc1 .LBB0_351

; #define PG8_STAGE(bufoff, gbase, voff) do { _Pragma("unroll") for (int _i = 0; _i < 2; ++_i) \
;         __builtin_amdgcn_global_load_lds((const unsigned*)((const char*)(gbase) + (voff)[_i]), (LAS unsigned*)(lds + (bufoff) + ldsw + _i * 8192), 16, 0, 0); } while (0)
; #define PG8_LDA(dst, b, h) do { _Pragma("unroll") for (int m = 0; m < 4; ++m) _Pragma("unroll") for (int k = 0; k < 2; ++k) dst[m][k] = *(const LAS bf16x8*)(lds + PG8_SA(b, h) + aoff + m * 2048 + k * 1024); } while (0)
; #define PG8_LDB(dst, b, h) do { _Pragma("unroll") for (int n = 0; n < 2; ++n) _Pragma("unroll") for (int k = 0; k < 2; ++k) dst[n][k] = *(const LAS bf16x8*)(lds + PG8_SB(b, h) + boff + n * 2048 + k * 1024); } while (0)
; #define PG8_MMA(ai, bj, At, Bt) do { __builtin_amdgcn_s_setprio(1); _Pragma("unroll") for (int m = 0; m < 4; ++m) _Pragma("unroll") for (int n = 0; n < 2; ++n) _Pragma("unroll") for (int k = 0; k < 2; ++k) \
;         acc[ai][bj][m][n] = __builtin_amdgcn_mfma_f32_16x16x32_bf16(Bt[n][k], At[m][k], acc[ai][bj][m][n], 0, 0, 0); __builtin_amdgcn_s_setprio(0); } while (0)
; #define PG8_WAIT_V(n) asm volatile("s_waitcnt vmcnt(" #n ")" ::: "memory")
; #define PG8_WAIT_L(n) asm volatile("s_waitcnt lgkmcnt(" #n ")" ::: "memory")
; #define PG8_BAR __builtin_amdgcn_s_barrier()
; template <class Epi, bool ALIGN_EPI = PG8_ALIGN, bool SP2 = PG8_SP2>
; __device__ __forceinline__ void gemm_phase(LAS uchar* lds, const Gemm g, const StaticOrder& S, const Epi& E) {
;     ...
;         for (int t = tb; t < tb + tblk; t += 2) {
;             const bool last = (t == nt - 2);
;             const char* a1 = cA + (size_t)(t + 1) * kstep;
;             const char* a2 = last ? nA : cA + (size_t)(t + 2) * kstep; const char* b2 = last ? nB : cB + (size_t)(t + 2) * kstep;
;             const char* a3 = a2 + kstep; const char* b3 = b2 + kstep;
;             if constexpr (SP2) {
;             PG8_LDB(B0, 0, 0); PG8_LDB(B1, 0, 1); PG8_SCHED; PG8_LDA(At, 0, 0); PG8_STAGE(PG8_SA(1, 1), a1 + hstepA, voffA);
;             PG8_WAIT_V(8); PG8_WAIT_L(0); PG8_BAR; PG8_MMA(0, 0, At, B0); PG8_MMA(0, 1, At, B1); PG8_BAR; PG8_SCHED;
;             PG8_LDA(At, 0, 1); PG8_STAGE(PG8_SB(0, 0), b2, voffB); PG8_STAGE(PG8_SB(0, 1), b2 + hstepB, voffB); PG8_STAGE(PG8_SA(0, 0), a2, voffA);
;             PG8_WAIT_V(8); PG8_WAIT_L(0); PG8_BAR; PG8_MMA(1, 0, At, B0); PG8_MMA(1, 1, At, B1); PG8_BAR; PG8_SCHED;
.LBB0_580:
	s_add_i32 s42, s42, 2
	s_add_u32 s4, s14, s18
	s_addc_u32 s5, s15, s19
	s_add_u32 s4, s4, 0x100
	s_addc_u32 s5, s5, 0
	s_add_u32 s43, s38, s18
	s_addc_u32 s44, s39, s19
	s_add_i32 s45, 0, 0x10000
	s_cmpk_eq_i32 s18, 0xf00
	s_cselect_b32 s21, s1, s5
	s_cselect_b32 s20, s0, s4
	v_add_u32_e32 v1, s45, v168
	s_cselect_b32 s5, s13, s44
	s_cselect_b32 s4, s12, s43
	s_add_i32 s43, 0, 0x14000
	ds_read_b128 v[174:177], v1
	ds_read_b128 v[178:181], v1 offset:1024
	ds_read_b128 v[184:187], v1 offset:2048
	ds_read_b128 v[188:191], v1 offset:3072
	v_add_u32_e32 v1, s43, v168
	ds_read_b128 v[192:195], v1
	ds_read_b128 v[196:199], v1 offset:1024
	ds_read_b128 v[200:203], v1 offset:2048
	ds_read_b128 v[204:207], v1 offset:3072
	v_lshl_add_u64 v[2:3], v[164:165], 0, s[18:19]
	s_add_i32 m0, s25, 0xc000
	ds_read_b128 v[208:211], v170
	ds_read_b128 v[212:215], v170 offset:1024
	ds_read_b128 v[216:219], v170 offset:2048
	ds_read_b128 v[220:223], v170 offset:3072
	ds_read_b128 v[224:227], v170 offset:4096
	ds_read_b128 v[228:231], v170 offset:5120
	ds_read_b128 v[232:235], v170 offset:6144
	ds_read_b128 v[236:239], v170 offset:7168
	global_load_lds_dwordx4 v[2:3], off
	v_lshl_add_u64 v[2:3], v[166:167], 0, s[18:19]
	s_add_i32 m0, s25, 0xe000
	s_nop 0
	global_load_lds_dwordx4 v[2:3], off
	s_waitcnt vmcnt(8)
	s_waitcnt lgkmcnt(0)
	s_setprio 1
	s_barrier
	v_mfma_f32_16x16x32_bf16 v[128:131], v[174:177], v[208:211], v[128:131]
	v_mfma_f32_16x16x32_bf16 v[124:127], v[184:187], v[208:211], v[124:127]
	v_mfma_f32_16x16x32_bf16 v[112:115], v[174:177], v[216:219], v[112:115]
	v_mfma_f32_16x16x32_bf16 v[108:111], v[184:187], v[216:219], v[108:111]
	v_mfma_f32_16x16x32_bf16 v[96:99], v[174:177], v[224:227], v[96:99]
	v_mfma_f32_16x16x32_bf16 v[92:95], v[184:187], v[224:227], v[92:95]
	v_mfma_f32_16x16x32_bf16 v[80:83], v[174:177], v[232:235], v[80:83]
	v_mfma_f32_16x16x32_bf16 v[76:79], v[184:187], v[232:235], v[76:79]
	v_mfma_f32_16x16x32_bf16 v[128:131], v[178:181], v[212:215], v[128:131]
	v_mfma_f32_16x16x32_bf16 v[124:127], v[188:191], v[212:215], v[124:127]
	v_mfma_f32_16x16x32_bf16 v[112:115], v[178:181], v[220:223], v[112:115]
	v_mfma_f32_16x16x32_bf16 v[108:111], v[188:191], v[220:223], v[108:111]
	v_mfma_f32_16x16x32_bf16 v[96:99], v[178:181], v[228:231], v[96:99]
	v_mfma_f32_16x16x32_bf16 v[92:95], v[188:191], v[228:231], v[92:95]
	v_mfma_f32_16x16x32_bf16 v[80:83], v[178:181], v[236:239], v[80:83]
	v_mfma_f32_16x16x32_bf16 v[76:79], v[188:191], v[236:239], v[76:79]
	v_mfma_f32_16x16x32_bf16 v[120:123], v[192:195], v[208:211], v[120:123]
	v_mfma_f32_16x16x32_bf16 v[116:119], v[200:203], v[208:211], v[116:119]
	v_mfma_f32_16x16x32_bf16 v[104:107], v[192:195], v[216:219], v[104:107]
	v_mfma_f32_16x16x32_bf16 v[100:103], v[200:203], v[216:219], v[100:103]
	v_mfma_f32_16x16x32_bf16 v[88:91], v[192:195], v[224:227], v[88:91]
	v_mfma_f32_16x16x32_bf16 v[84:87], v[200:203], v[224:227], v[84:87]
	v_mfma_f32_16x16x32_bf16 v[72:75], v[192:195], v[232:235], v[72:75]
	v_mfma_f32_16x16x32_bf16 v[68:71], v[200:203], v[232:235], v[68:71]
	v_mfma_f32_16x16x32_bf16 v[120:123], v[196:199], v[212:215], v[120:123]
	v_mfma_f32_16x16x32_bf16 v[116:119], v[204:207], v[212:215], v[116:119]
	v_mfma_f32_16x16x32_bf16 v[104:107], v[196:199], v[220:223], v[104:107]
	v_mfma_f32_16x16x32_bf16 v[100:103], v[204:207], v[220:223], v[100:103]
	v_mfma_f32_16x16x32_bf16 v[88:91], v[196:199], v[228:231], v[88:91]
	v_mfma_f32_16x16x32_bf16 v[84:87], v[204:207], v[228:231], v[84:87]
	v_mfma_f32_16x16x32_bf16 v[72:75], v[196:199], v[236:239], v[72:75]
	v_mfma_f32_16x16x32_bf16 v[68:71], v[204:207], v[236:239], v[68:71]
	s_barrier
	s_setprio 0
	s_add_i32 s44, s45, s24
	v_lshl_add_u64 v[240:241], s[4:5], 0, v[134:135]
	s_mov_b32 m0, s44
	ds_read_b128 v[208:211], v170 offset:16384
	ds_read_b128 v[212:215], v170 offset:17408
	ds_read_b128 v[216:219], v170 offset:18432
	ds_read_b128 v[220:223], v170 offset:19456
	ds_read_b128 v[224:227], v170 offset:20480
	ds_read_b128 v[228:231], v170 offset:21504
	ds_read_b128 v[232:235], v170 offset:22528
	ds_read_b128 v[236:239], v170 offset:23552
	global_load_lds_dwordx4 v[240:241], off
	s_add_i32 m0, s44, 0x2000
	s_add_u32 s44, s4, 0x84000
	v_lshl_add_u64 v[242:243], s[4:5], 0, v[158:159]
	s_addc_u32 s45, s5, 0
	s_add_i32 s43, s43, s24
	global_load_lds_dwordx4 v[242:243], off
	v_lshl_add_u64 v[2:3], s[44:45], 0, v[134:135]
	s_mov_b32 m0, s43
	v_lshl_add_u64 v[244:245], s[20:21], 0, v[132:133]
	global_load_lds_dwordx4 v[2:3], off
	v_lshl_add_u64 v[2:3], s[44:45], 0, v[158:159]
	s_add_i32 m0, s43, 0x2000
	v_lshl_add_u64 v[246:247], s[20:21], 0, v[156:157]
	global_load_lds_dwordx4 v[2:3], off
	s_mov_b32 m0, s25
	s_nop 0
	global_load_lds_dwordx4 v[244:245], off
	s_mov_b32 m0, s26
	s_nop 0
	global_load_lds_dwordx4 v[246:247], off
	s_waitcnt vmcnt(8)
	s_waitcnt lgkmcnt(0)
	s_setprio 1
	s_barrier
; #define PG8_STAGE(bufoff, gbase, voff) do { _Pragma("unroll") for (int _i = 0; _i < 2; ++_i) \
;         __builtin_amdgcn_global_load_lds((const unsigned*)((const char*)(gbase) + (voff)[_i]), (LAS unsigned*)(lds + (bufoff) + ldsw + _i * 8192), 16, 0, 0); } while (0)
; #define PG8_LDA(dst, b, h) do { _Pragma("unroll") for (int m = 0; m < 4; ++m) _Pragma("unroll") for (int k = 0; k < 2; ++k) dst[m][k] = *(const LAS bf16x8*)(lds + PG8_SA(b, h) + aoff + m * 2048 + k * 1024); } while (0)
; #define PG8_LDB(dst, b, h) do { _Pragma("unroll") for (int n = 0; n < 2; ++n) _Pragma("unroll") for (int k = 0; k < 2; ++k) dst[n][k] = *(const LAS bf16x8*)(lds + PG8_SB(b, h) + boff + n * 2048 + k * 1024); } while (0)
; #define PG8_MMA(ai, bj, At, Bt) do { __builtin_amdgcn_s_setprio(1); _Pragma("unroll") for (int m = 0; m < 4; ++m) _Pragma("unroll") for (int n = 0; n < 2; ++n) _Pragma("unroll") for (int k = 0; k < 2; ++k) \
;         acc[ai][bj][m][n] = __builtin_amdgcn_mfma_f32_16x16x32_bf16(Bt[n][k], At[m][k], acc[ai][bj][m][n], 0, 0, 0); __builtin_amdgcn_s_setprio(0); } while (0)
; #define PG8_WAIT_V(n) asm volatile("s_waitcnt vmcnt(" #n ")" ::: "memory")
; #define PG8_WAIT_L(n) asm volatile("s_waitcnt lgkmcnt(" #n ")" ::: "memory")
; #define PG8_BAR __builtin_amdgcn_s_barrier()
; #define PG8_SCHED __builtin_amdgcn_sched_barrier(0)
; template <class Epi, bool ALIGN_EPI = PG8_ALIGN, bool SP2 = PG8_SP2>
; __device__ __forceinline__ void gemm_phase(LAS uchar* lds, const Gemm g, const StaticOrder& S, const Epi& E) {
;     ...
;             PG8_WAIT_V(8); PG8_WAIT_L(0); PG8_BAR; PG8_MMA(1, 0, At, B0); PG8_MMA(1, 1, At, B1); PG8_BAR; PG8_SCHED;
;             PG8_LDB(B0, 1, 0); PG8_LDB(B1, 1, 1); PG8_SCHED; PG8_LDA(At, 1, 0); PG8_STAGE(PG8_SA(0, 1), a2 + hstepA, voffA);
;             PG8_WAIT_V(8); PG8_WAIT_L(0); PG8_BAR; PG8_MMA(0, 0, At, B0); PG8_MMA(0, 1, At, B1); PG8_BAR; PG8_SCHED;
	v_mfma_f32_16x16x32_bf16 v[64:67], v[174:177], v[208:211], v[64:67]
	v_mfma_f32_16x16x32_bf16 v[60:63], v[184:187], v[208:211], v[60:63]
	v_mfma_f32_16x16x32_bf16 v[48:51], v[174:177], v[216:219], v[48:51]
	v_mfma_f32_16x16x32_bf16 v[44:47], v[184:187], v[216:219], v[44:47]
	v_mfma_f32_16x16x32_bf16 v[32:35], v[174:177], v[224:227], v[32:35]
	v_mfma_f32_16x16x32_bf16 v[28:31], v[184:187], v[224:227], v[28:31]
	v_mfma_f32_16x16x32_bf16 v[16:19], v[174:177], v[232:235], v[16:19]
	v_mfma_f32_16x16x32_bf16 v[12:15], v[184:187], v[232:235], v[12:15]
	v_mfma_f32_16x16x32_bf16 v[64:67], v[178:181], v[212:215], v[64:67]
	v_mfma_f32_16x16x32_bf16 v[60:63], v[188:191], v[212:215], v[60:63]
	v_mfma_f32_16x16x32_bf16 v[48:51], v[178:181], v[220:223], v[48:51]
	v_mfma_f32_16x16x32_bf16 v[44:47], v[188:191], v[220:223], v[44:47]
	v_mfma_f32_16x16x32_bf16 v[32:35], v[178:181], v[228:231], v[32:35]
	v_mfma_f32_16x16x32_bf16 v[28:31], v[188:191], v[228:231], v[28:31]
	v_mfma_f32_16x16x32_bf16 v[16:19], v[178:181], v[236:239], v[16:19]
	v_mfma_f32_16x16x32_bf16 v[12:15], v[188:191], v[236:239], v[12:15]
	v_mfma_f32_16x16x32_bf16 v[56:59], v[192:195], v[208:211], v[56:59]
	v_mfma_f32_16x16x32_bf16 v[52:55], v[200:203], v[208:211], v[52:55]
	v_mfma_f32_16x16x32_bf16 v[40:43], v[192:195], v[216:219], v[40:43]
	v_mfma_f32_16x16x32_bf16 v[36:39], v[200:203], v[216:219], v[36:39]
	v_mfma_f32_16x16x32_bf16 v[24:27], v[192:195], v[224:227], v[24:27]
	v_mfma_f32_16x16x32_bf16 v[20:23], v[200:203], v[224:227], v[20:23]
	v_mfma_f32_16x16x32_bf16 v[8:11], v[192:195], v[232:235], v[8:11]
	v_mfma_f32_16x16x32_bf16 v[2:5], v[200:203], v[232:235], v[4:7]
	v_mfma_f32_16x16x32_bf16 v[56:59], v[196:199], v[212:215], v[56:59]
	v_mfma_f32_16x16x32_bf16 v[52:55], v[204:207], v[212:215], v[52:55]
	v_mfma_f32_16x16x32_bf16 v[40:43], v[196:199], v[220:223], v[40:43]
	v_mfma_f32_16x16x32_bf16 v[36:39], v[204:207], v[220:223], v[36:39]
	v_mfma_f32_16x16x32_bf16 v[24:27], v[196:199], v[228:231], v[24:27]
	v_mfma_f32_16x16x32_bf16 v[20:23], v[204:207], v[228:231], v[20:23]
	v_mfma_f32_16x16x32_bf16 v[8:11], v[196:199], v[236:239], v[8:11]
	v_mfma_f32_16x16x32_bf16 v[2:5], v[204:207], v[236:239], v[2:5]
	s_barrier
	s_setprio 0
	s_add_i32 s43, 0, 0x18000
	v_add_u32_e32 v1, s43, v168
	s_add_i32 s44, 0, 0x1c000
	ds_read_b128 v[174:177], v1
	ds_read_b128 v[178:181], v1 offset:1024
	ds_read_b128 v[184:187], v1 offset:2048
	ds_read_b128 v[188:191], v1 offset:3072
	v_add_u32_e32 v1, s44, v168
	ds_read_b128 v[192:195], v1
	ds_read_b128 v[196:199], v1 offset:1024
	ds_read_b128 v[200:203], v1 offset:2048
	ds_read_b128 v[204:207], v1 offset:3072
	s_add_u32 s20, s20, 0x184000
	s_addc_u32 s21, s21, 0
	s_mov_b32 m0, s27
	v_lshl_add_u64 v[6:7], s[20:21], 0, v[132:133]
	ds_read_b128 v[208:211], v170 offset:32768
	ds_read_b128 v[212:215], v170 offset:33792
	ds_read_b128 v[216:219], v170 offset:34816
	ds_read_b128 v[220:223], v170 offset:35840
	ds_read_b128 v[224:227], v170 offset:36864
	ds_read_b128 v[228:231], v170 offset:37888
	ds_read_b128 v[232:235], v170 offset:38912
	ds_read_b128 v[236:239], v170 offset:39936
	global_load_lds_dwordx4 v[6:7], off
	v_lshl_add_u64 v[6:7], s[20:21], 0, v[156:157]
	s_mov_b32 m0, s28
	s_nop 0
	global_load_lds_dwordx4 v[6:7], off
	s_waitcnt vmcnt(8)
	s_waitcnt lgkmcnt(0)
	s_setprio 1
	s_barrier
	v_mfma_f32_16x16x32_bf16 v[128:131], v[174:177], v[208:211], v[128:131]
	v_mfma_f32_16x16x32_bf16 v[124:127], v[184:187], v[208:211], v[124:127]
	v_mfma_f32_16x16x32_bf16 v[112:115], v[174:177], v[216:219], v[112:115]
	v_mfma_f32_16x16x32_bf16 v[108:111], v[184:187], v[216:219], v[108:111]
	v_mfma_f32_16x16x32_bf16 v[96:99], v[174:177], v[224:227], v[96:99]
	v_mfma_f32_16x16x32_bf16 v[92:95], v[184:187], v[224:227], v[92:95]
	v_mfma_f32_16x16x32_bf16 v[80:83], v[174:177], v[232:235], v[80:83]
	v_mfma_f32_16x16x32_bf16 v[76:79], v[184:187], v[232:235], v[76:79]
	v_mfma_f32_16x16x32_bf16 v[128:131], v[178:181], v[212:215], v[128:131]
	v_mfma_f32_16x16x32_bf16 v[124:127], v[188:191], v[212:215], v[124:127]
	v_mfma_f32_16x16x32_bf16 v[112:115], v[178:181], v[220:223], v[112:115]
	v_mfma_f32_16x16x32_bf16 v[108:111], v[188:191], v[220:223], v[108:111]
	v_mfma_f32_16x16x32_bf16 v[96:99], v[178:181], v[228:231], v[96:99]
	v_mfma_f32_16x16x32_bf16 v[92:95], v[188:191], v[228:231], v[92:95]
	v_mfma_f32_16x16x32_bf16 v[80:83], v[178:181], v[236:239], v[80:83]
	v_mfma_f32_16x16x32_bf16 v[76:79], v[188:191], v[236:239], v[76:79]
	v_mfma_f32_16x16x32_bf16 v[120:123], v[192:195], v[208:211], v[120:123]
	v_mfma_f32_16x16x32_bf16 v[116:119], v[200:203], v[208:211], v[116:119]
	v_mfma_f32_16x16x32_bf16 v[104:107], v[192:195], v[216:219], v[104:107]
	v_mfma_f32_16x16x32_bf16 v[100:103], v[200:203], v[216:219], v[100:103]
	v_mfma_f32_16x16x32_bf16 v[88:91], v[192:195], v[224:227], v[88:91]
	v_mfma_f32_16x16x32_bf16 v[84:87], v[200:203], v[224:227], v[84:87]
	v_mfma_f32_16x16x32_bf16 v[72:75], v[192:195], v[232:235], v[72:75]
	v_mfma_f32_16x16x32_bf16 v[68:71], v[200:203], v[232:235], v[68:71]
	v_mfma_f32_16x16x32_bf16 v[120:123], v[196:199], v[212:215], v[120:123]
	v_mfma_f32_16x16x32_bf16 v[116:119], v[204:207], v[212:215], v[116:119]
	v_mfma_f32_16x16x32_bf16 v[104:107], v[196:199], v[220:223], v[104:107]
	v_mfma_f32_16x16x32_bf16 v[100:103], v[204:207], v[220:223], v[100:103]
	v_mfma_f32_16x16x32_bf16 v[88:91], v[196:199], v[228:231], v[88:91]
	v_mfma_f32_16x16x32_bf16 v[84:87], v[204:207], v[228:231], v[84:87]
	v_mfma_f32_16x16x32_bf16 v[72:75], v[196:199], v[236:239], v[72:75]
	v_mfma_f32_16x16x32_bf16 v[68:71], v[204:207], v[236:239], v[68:71]
	s_barrier
; #define LAS __attribute__((address_space(3)))
; #define PG8_WAIT_V(n) asm volatile("s_waitcnt vmcnt(" #n ")" ::: "memory")
; #define PG8_WAIT_L(n) asm volatile("s_waitcnt lgkmcnt(" #n ")" ::: "memory")
; template <class Epi, bool ALIGN_EPI = PG8_ALIGN, bool SP2 = PG8_SP2>
; __device__ __forceinline__ void gemm_phase(LAS uchar* lds, const Gemm g, const StaticOrder& S, const Epi& E) {
;     ...
;         for (int tb = 0; tb < nt; tb += tblk) {
;         if constexpr (Epi::GROUPS) { if (tb > 0) {
;             const LAS float* rt = (const LAS float*)(lds + LDS_RT) + ((ui & 1) * 256 + wr * 64 + fr) * 8 + ((tb >> 2) - 1);
; #pragma unroll
;             for (int a = 0; a < 2; ++a)
; #pragma unroll
;                 for (int m = 0; m < 4; ++m) { const float f = rt[(a * 128 + m * 16) * 8];
; #pragma unroll
;                     for (int b = 0; b < 2; ++b)
; #pragma unroll
;                         for (int n = 0; n < 2; ++n) acc[a][b][m][n] *= f; } } }
; #pragma unroll 1
;         for (int t = tb; t < tb + tblk; t += 2) {
;             const bool last = (t == nt - 2);
;             const char* a1 = cA + (size_t)(t + 1) * kstep;
;             const char* a2 = last ? nA : cA + (size_t)(t + 2) * kstep; const char* b2 = last ? nB : cB + (size_t)(t + 2) * kstep;
;             const char* a3 = a2 + kstep; const char* b3 = b2 + kstep;
;             if constexpr (SP2) {
;             PG8_LDB(B0, 0, 0); PG8_LDB(B1, 0, 1); PG8_SCHED; PG8_LDA(At, 0, 0); PG8_STAGE(PG8_SA(1, 1), a1 + hstepA, voffA);
;             PG8_WAIT_V(8); PG8_WAIT_L(0); PG8_BAR; PG8_MMA(0, 0, At, B0); PG8_MMA(0, 1, At, B1); PG8_BAR; PG8_SCHED;
;             PG8_LDA(At, 0, 1); PG8_STAGE(PG8_SB(0, 0), b2, voffB); PG8_STAGE(PG8_SB(0, 1), b2 + hstepB, voffB); PG8_STAGE(PG8_SA(0, 0), a2, voffA);
;             PG8_WAIT_V(8); PG8_WAIT_L(0); PG8_BAR; PG8_MMA(1, 0, At, B0); PG8_MMA(1, 1, At, B1); PG8_BAR; PG8_SCHED;
;             PG8_LDB(B0, 1, 0); PG8_LDB(B1, 1, 1); PG8_SCHED; PG8_LDA(At, 1, 0); PG8_STAGE(PG8_SA(0, 1), a2 + hstepA, voffA);
;             PG8_WAIT_V(8); PG8_WAIT_L(0); PG8_BAR; PG8_MMA(0, 0, At, B0); PG8_MMA(0, 1, At, B1); PG8_BAR; PG8_SCHED;
;             PG8_LDA(At, 1, 1); PG8_STAGE(PG8_SB(1, 0), b3, voffB); PG8_STAGE(PG8_SB(1, 1), b3 + hstepB, voffB); PG8_STAGE(PG8_SA(1, 0), a3, voffA);
;             PG8_WAIT_V(8); PG8_WAIT_L(0); PG8_BAR; PG8_MMA(1, 0, At, B0); PG8_MMA(1, 1, At, B1); PG8_BAR; PG8_SCHED;
	s_setprio 0
	s_add_i32 s20, s43, s24
	v_lshl_add_u64 v[6:7], v[240:241], 0, s[84:85]
	s_mov_b32 m0, s20
	ds_read_b128 v[208:211], v170 offset:49152
	ds_read_b128 v[212:215], v170 offset:50176
	ds_read_b128 v[216:219], v170 offset:51200
	ds_read_b128 v[220:223], v170 offset:52224
	ds_read_b128 v[224:227], v170 offset:53248
	ds_read_b128 v[228:231], v170 offset:54272
	ds_read_b128 v[232:235], v170 offset:55296
	ds_read_b128 v[236:239], v170 offset:56320
	global_load_lds_dwordx4 v[6:7], off
	s_add_i32 m0, s20, 0x2000
	s_add_u32 s4, s4, 0x84080
	v_lshl_add_u64 v[6:7], v[242:243], 0, s[84:85]
	s_addc_u32 s5, s5, 0
	s_add_i32 s20, s44, s24
	global_load_lds_dwordx4 v[6:7], off
	v_lshl_add_u64 v[6:7], s[4:5], 0, v[134:135]
	s_mov_b32 m0, s20
	s_nop 0
	global_load_lds_dwordx4 v[6:7], off
	v_lshl_add_u64 v[6:7], s[4:5], 0, v[158:159]
	s_add_i32 m0, s20, 0x2000
	s_nop 0
	global_load_lds_dwordx4 v[6:7], off
	v_lshl_add_u64 v[6:7], v[244:245], 0, s[84:85]
	s_mov_b32 m0, s29
	s_nop 0
	global_load_lds_dwordx4 v[6:7], off
	v_lshl_add_u64 v[6:7], v[246:247], 0, s[84:85]
	s_mov_b32 m0, s30
	s_nop 0
	global_load_lds_dwordx4 v[6:7], off
	s_waitcnt vmcnt(8)
	s_waitcnt lgkmcnt(0)
	s_setprio 1
	s_barrier
	v_mfma_f32_16x16x32_bf16 v[64:67], v[174:177], v[208:211], v[64:67]
	v_mfma_f32_16x16x32_bf16 v[60:63], v[184:187], v[208:211], v[60:63]
	v_mfma_f32_16x16x32_bf16 v[48:51], v[174:177], v[216:219], v[48:51]
	v_mfma_f32_16x16x32_bf16 v[44:47], v[184:187], v[216:219], v[44:47]
	v_mfma_f32_16x16x32_bf16 v[32:35], v[174:177], v[224:227], v[32:35]
	v_mfma_f32_16x16x32_bf16 v[28:31], v[184:187], v[224:227], v[28:31]
	v_mfma_f32_16x16x32_bf16 v[16:19], v[174:177], v[232:235], v[16:19]
	v_mfma_f32_16x16x32_bf16 v[12:15], v[184:187], v[232:235], v[12:15]
	v_mfma_f32_16x16x32_bf16 v[64:67], v[178:181], v[212:215], v[64:67]
	v_mfma_f32_16x16x32_bf16 v[60:63], v[188:191], v[212:215], v[60:63]
	v_mfma_f32_16x16x32_bf16 v[48:51], v[178:181], v[220:223], v[48:51]
	v_mfma_f32_16x16x32_bf16 v[44:47], v[188:191], v[220:223], v[44:47]
	v_mfma_f32_16x16x32_bf16 v[32:35], v[178:181], v[228:231], v[32:35]
	v_mfma_f32_16x16x32_bf16 v[28:31], v[188:191], v[228:231], v[28:31]
	v_mfma_f32_16x16x32_bf16 v[16:19], v[178:181], v[236:239], v[16:19]
	v_mfma_f32_16x16x32_bf16 v[12:15], v[188:191], v[236:239], v[12:15]
	v_mfma_f32_16x16x32_bf16 v[56:59], v[192:195], v[208:211], v[56:59]
	v_mfma_f32_16x16x32_bf16 v[52:55], v[200:203], v[208:211], v[52:55]
	v_mfma_f32_16x16x32_bf16 v[40:43], v[192:195], v[216:219], v[40:43]
	v_mfma_f32_16x16x32_bf16 v[36:39], v[200:203], v[216:219], v[36:39]
	v_mfma_f32_16x16x32_bf16 v[24:27], v[192:195], v[224:227], v[24:27]
	v_mfma_f32_16x16x32_bf16 v[20:23], v[200:203], v[224:227], v[20:23]
	v_mfma_f32_16x16x32_bf16 v[6:9], v[192:195], v[232:235], v[8:11]
	v_mfma_f32_16x16x32_bf16 v[2:5], v[200:203], v[232:235], v[2:5]
	v_mfma_f32_16x16x32_bf16 v[56:59], v[196:199], v[212:215], v[56:59]
	v_mfma_f32_16x16x32_bf16 v[52:55], v[204:207], v[212:215], v[52:55]
	v_mfma_f32_16x16x32_bf16 v[40:43], v[196:199], v[220:223], v[40:43]
	v_mfma_f32_16x16x32_bf16 v[36:39], v[204:207], v[220:223], v[36:39]
	v_mfma_f32_16x16x32_bf16 v[24:27], v[196:199], v[228:231], v[24:27]
	v_mfma_f32_16x16x32_bf16 v[20:23], v[204:207], v[228:231], v[20:23]
	v_mfma_f32_16x16x32_bf16 v[8:11], v[196:199], v[236:239], v[6:9]
	v_mfma_f32_16x16x32_bf16 v[4:7], v[204:207], v[236:239], v[2:5]
	s_barrier
	s_setprio 0
	s_add_u32 s18, s18, 0x100
	s_addc_u32 s19, s19, 0
	s_cmp_ge_u32 s42, s41
	s_cbranch_scc0 .LBB0_580
	s_add_u32 s16, s16, 0x200
	s_addc_u32 s17, s17, 0
	s_cmp_lt_u32 s40, 28
	s_cbranch_scc0 .LBB0_583
	s_mov_b32 s40, s41
	s_cmp_eq_u32 s40, 0
	s_cbranch_scc0 .LBB0_578
	s_branch .LBB0_579

; #define PG8_STAGE(bufoff, gbase, voff) do { _Pragma("unroll") for (int _i = 0; _i < 2; ++_i) \
;         __builtin_amdgcn_global_load_lds((const unsigned*)((const char*)(gbase) + (voff)[_i]), (LAS unsigned*)(lds + (bufoff) + ldsw + _i * 8192), 16, 0, 0); } while (0)
; #define PG8_LDA(dst, b, h) do { _Pragma("unroll") for (int m = 0; m < 4; ++m) _Pragma("unroll") for (int k = 0; k < 2; ++k) dst[m][k] = *(const LAS bf16x8*)(lds + PG8_SA(b, h) + aoff + m * 2048 + k * 1024); } while (0)
; #define PG8_LDB(dst, b, h) do { _Pragma("unroll") for (int n = 0; n < 2; ++n) _Pragma("unroll") for (int k = 0; k < 2; ++k) dst[n][k] = *(const LAS bf16x8*)(lds + PG8_SB(b, h) + boff + n * 2048 + k * 1024); } while (0)
; #define PG8_MMA(ai, bj, At, Bt) do { __builtin_amdgcn_s_setprio(1); _Pragma("unroll") for (int m = 0; m < 4; ++m) _Pragma("unroll") for (int n = 0; n < 2; ++n) _Pragma("unroll") for (int k = 0; k < 2; ++k) \
;         acc[ai][bj][m][n] = __builtin_amdgcn_mfma_f32_16x16x32_bf16(Bt[n][k], At[m][k], acc[ai][bj][m][n], 0, 0, 0); __builtin_amdgcn_s_setprio(0); } while (0)
; #define PG8_WAIT_V(n) asm volatile("s_waitcnt vmcnt(" #n ")" ::: "memory")
; #define PG8_WAIT_L(n) asm volatile("s_waitcnt lgkmcnt(" #n ")" ::: "memory")
; #define PG8_BAR __builtin_amdgcn_s_barrier()
; #define PG8_SCHED __builtin_amdgcn_sched_barrier(0)
; template <class Epi, bool ALIGN_EPI = PG8_ALIGN, bool SP2 = PG8_SP2>
; __device__ __forceinline__ void gemm_phase(LAS uchar* lds, const Gemm g, const StaticOrder& S, const Epi& E) {
;     ...
;             const bool last = (t == nt - 2);
;             const char* a1 = cA + (size_t)(t + 1) * kstep;
;             const char* a2 = last ? nA : cA + (size_t)(t + 2) * kstep; const char* b2 = last ? nB : cB + (size_t)(t + 2) * kstep;
;             const char* a3 = a2 + kstep; const char* b3 = b2 + kstep;
;             if constexpr (SP2) {
;             PG8_LDB(B0, 0, 0); PG8_LDB(B1, 0, 1); PG8_SCHED; PG8_LDA(At, 0, 0); PG8_STAGE(PG8_SA(1, 1), a1 + hstepA, voffA);
;             PG8_WAIT_V(8); PG8_WAIT_L(0); PG8_BAR; PG8_MMA(0, 0, At, B0); PG8_MMA(0, 1, At, B1); PG8_BAR; PG8_SCHED;
;             PG8_LDA(At, 0, 1); PG8_STAGE(PG8_SB(0, 0), b2, voffB); PG8_STAGE(PG8_SB(0, 1), b2 + hstepB, voffB); PG8_STAGE(PG8_SA(0, 0), a2, voffA);
;             PG8_WAIT_V(8); PG8_WAIT_L(0); PG8_BAR; PG8_MMA(1, 0, At, B0); PG8_MMA(1, 1, At, B1); PG8_BAR; PG8_SCHED;
.LBB0_668:
	s_add_u32 s36, s14, 0x100
	s_addc_u32 s37, s15, 0
	s_mov_b32 s38, -2
	s_add_u32 s14, s12, 0x100
	s_addc_u32 s15, s13, 0
	s_add_i32 s39, 0, 0x10000
	s_cmp_eq_u32 s38, 12
	s_cselect_b32 s19, s5, s15
	s_cselect_b32 s18, s4, s14
	s_cselect_b32 s17, s11, s37
	s_cselect_b32 s16, s10, s36
	s_add_i32 s40, 0, 0x14000
	v_add_u32_e32 v174, s39, v139
	v_add_u32_e32 v192, s40, v139
	ds_read_b128 v[160:163], v174
	ds_read_b128 v[164:167], v174 offset:1024
	ds_read_b128 v[168:171], v174 offset:2048
	ds_read_b128 v[174:177], v174 offset:3072
	ds_read_b128 v[178:181], v192
	ds_read_b128 v[184:187], v192 offset:1024
	ds_read_b128 v[188:191], v192 offset:2048
	ds_read_b128 v[192:195], v192 offset:3072
	v_lshl_add_u64 v[228:229], s[12:13], 0, v[156:157]
	s_add_i32 m0, s23, 0xc000
	ds_read_b128 v[196:199], v173
	ds_read_b128 v[200:203], v173 offset:1024
	ds_read_b128 v[204:207], v173 offset:2048
	ds_read_b128 v[208:211], v173 offset:3072
	ds_read_b128 v[212:215], v173 offset:4096
	ds_read_b128 v[216:219], v173 offset:5120
	ds_read_b128 v[220:223], v173 offset:6144
	ds_read_b128 v[224:227], v173 offset:7168
	global_load_lds_dwordx4 v[228:229], off
	v_lshl_add_u64 v[228:229], s[12:13], 0, v[158:159]
	s_add_i32 m0, s23, 0xe000
	s_nop 0
	global_load_lds_dwordx4 v[228:229], off
	s_waitcnt vmcnt(8)
	s_waitcnt lgkmcnt(0)
	s_setprio 1
	s_barrier
	v_mfma_f32_16x16x32_bf16 v[126:129], v[160:163], v[196:199], 0
	v_mfma_f32_16x16x32_bf16 v[122:125], v[168:171], v[196:199], 0
	v_mfma_f32_16x16x32_bf16 v[118:121], v[160:163], v[204:207], 0
	v_mfma_f32_16x16x32_bf16 v[110:113], v[168:171], v[204:207], 0
	v_mfma_f32_16x16x32_bf16 v[102:105], v[160:163], v[212:215], 0
	v_mfma_f32_16x16x32_bf16 v[94:97], v[168:171], v[212:215], 0
	v_mfma_f32_16x16x32_bf16 v[86:89], v[160:163], v[220:223], 0
	v_mfma_f32_16x16x32_bf16 v[78:81], v[168:171], v[220:223], 0
	v_mfma_f32_16x16x32_bf16 v[126:129], v[164:167], v[200:203], v[126:129]
	v_mfma_f32_16x16x32_bf16 v[122:125], v[174:177], v[200:203], v[122:125]
	v_mfma_f32_16x16x32_bf16 v[118:121], v[164:167], v[208:211], v[118:121]
	v_mfma_f32_16x16x32_bf16 v[110:113], v[174:177], v[208:211], v[110:113]
	v_mfma_f32_16x16x32_bf16 v[102:105], v[164:167], v[216:219], v[102:105]
	v_mfma_f32_16x16x32_bf16 v[94:97], v[174:177], v[216:219], v[94:97]
	v_mfma_f32_16x16x32_bf16 v[86:89], v[164:167], v[224:227], v[86:89]
	v_mfma_f32_16x16x32_bf16 v[78:81], v[174:177], v[224:227], v[78:81]
	v_mfma_f32_16x16x32_bf16 v[114:117], v[178:181], v[196:199], 0
	v_mfma_f32_16x16x32_bf16 v[106:109], v[188:191], v[196:199], 0
	v_mfma_f32_16x16x32_bf16 v[98:101], v[178:181], v[204:207], 0
	v_mfma_f32_16x16x32_bf16 v[90:93], v[188:191], v[204:207], 0
	v_mfma_f32_16x16x32_bf16 v[82:85], v[178:181], v[212:215], 0
	v_mfma_f32_16x16x32_bf16 v[74:77], v[188:191], v[212:215], 0
	v_mfma_f32_16x16x32_bf16 v[70:73], v[178:181], v[220:223], 0
	v_mfma_f32_16x16x32_bf16 v[66:69], v[188:191], v[220:223], 0
	v_mfma_f32_16x16x32_bf16 v[114:117], v[184:187], v[200:203], v[114:117]
	v_mfma_f32_16x16x32_bf16 v[106:109], v[192:195], v[200:203], v[106:109]
	v_mfma_f32_16x16x32_bf16 v[98:101], v[184:187], v[208:211], v[98:101]
	v_mfma_f32_16x16x32_bf16 v[90:93], v[192:195], v[208:211], v[90:93]
	v_mfma_f32_16x16x32_bf16 v[82:85], v[184:187], v[216:219], v[82:85]
	v_mfma_f32_16x16x32_bf16 v[74:77], v[192:195], v[216:219], v[74:77]
	v_mfma_f32_16x16x32_bf16 v[70:73], v[184:187], v[224:227], v[70:73]
	v_mfma_f32_16x16x32_bf16 v[66:69], v[192:195], v[224:227], v[66:69]
	s_barrier
	s_setprio 0
	s_add_i32 s12, s39, s21
	v_lshl_add_u64 v[228:229], s[16:17], 0, v[134:135]
	s_mov_b32 m0, s12
	ds_read_b128 v[196:199], v173 offset:16384
	ds_read_b128 v[200:203], v173 offset:17408
	ds_read_b128 v[204:207], v173 offset:18432
	ds_read_b128 v[208:211], v173 offset:19456
	ds_read_b128 v[212:215], v173 offset:20480
	ds_read_b128 v[216:219], v173 offset:21504
	ds_read_b128 v[220:223], v173 offset:22528
	ds_read_b128 v[224:227], v173 offset:23552
	global_load_lds_dwordx4 v[228:229], off
	s_add_i32 m0, s12, 0x2000
	s_add_u32 s12, s16, 0x44000
	v_lshl_add_u64 v[230:231], s[16:17], 0, v[130:131]
	s_addc_u32 s13, s17, 0
	s_add_i32 s39, s40, s21
	global_load_lds_dwordx4 v[230:231], off
	v_lshl_add_u64 v[232:233], s[12:13], 0, v[134:135]
	s_mov_b32 m0, s39
	v_lshl_add_u64 v[234:235], s[18:19], 0, v[132:133]
	global_load_lds_dwordx4 v[232:233], off
	v_lshl_add_u64 v[232:233], s[12:13], 0, v[130:131]
	s_add_i32 m0, s39, 0x2000
	s_nop 0
	global_load_lds_dwordx4 v[232:233], off
	v_lshl_add_u64 v[232:233], s[18:19], 0, v[152:153]
	s_mov_b32 m0, s23
	s_nop 0
	global_load_lds_dwordx4 v[232:233], off
	s_mov_b32 m0, s24
	s_nop 0
	global_load_lds_dwordx4 v[234:235], off
	s_waitcnt vmcnt(8)
	s_waitcnt lgkmcnt(0)
	s_setprio 1
	s_barrier
; #define PG8_STAGE(bufoff, gbase, voff) do { _Pragma("unroll") for (int _i = 0; _i < 2; ++_i) \
;         __builtin_amdgcn_global_load_lds((const unsigned*)((const char*)(gbase) + (voff)[_i]), (LAS unsigned*)(lds + (bufoff) + ldsw + _i * 8192), 16, 0, 0); } while (0)
; #define PG8_LDA(dst, b, h) do { _Pragma("unroll") for (int m = 0; m < 4; ++m) _Pragma("unroll") for (int k = 0; k < 2; ++k) dst[m][k] = *(const LAS bf16x8*)(lds + PG8_SA(b, h) + aoff + m * 2048 + k * 1024); } while (0)
; #define PG8_LDB(dst, b, h) do { _Pragma("unroll") for (int n = 0; n < 2; ++n) _Pragma("unroll") for (int k = 0; k < 2; ++k) dst[n][k] = *(const LAS bf16x8*)(lds + PG8_SB(b, h) + boff + n * 2048 + k * 1024); } while (0)
; #define PG8_MMA(ai, bj, At, Bt) do { __builtin_amdgcn_s_setprio(1); _Pragma("unroll") for (int m = 0; m < 4; ++m) _Pragma("unroll") for (int n = 0; n < 2; ++n) _Pragma("unroll") for (int k = 0; k < 2; ++k) \
;         acc[ai][bj][m][n] = __builtin_amdgcn_mfma_f32_16x16x32_bf16(Bt[n][k], At[m][k], acc[ai][bj][m][n], 0, 0, 0); __builtin_amdgcn_s_setprio(0); } while (0)
; #define PG8_WAIT_V(n) asm volatile("s_waitcnt vmcnt(" #n ")" ::: "memory")
; #define PG8_WAIT_L(n) asm volatile("s_waitcnt lgkmcnt(" #n ")" ::: "memory")
; #define PG8_BAR __builtin_amdgcn_s_barrier()
; #define PG8_SCHED __builtin_amdgcn_sched_barrier(0)
; template <class Epi, bool ALIGN_EPI = PG8_ALIGN, bool SP2 = PG8_SP2>
; __device__ __forceinline__ void gemm_phase(LAS uchar* lds, const Gemm g, const StaticOrder& S, const Epi& E) {
;     ...
;             PG8_WAIT_V(8); PG8_WAIT_L(0); PG8_BAR; PG8_MMA(1, 0, At, B0); PG8_MMA(1, 1, At, B1); PG8_BAR; PG8_SCHED;
;             PG8_LDB(B0, 1, 0); PG8_LDB(B1, 1, 1); PG8_SCHED; PG8_LDA(At, 1, 0); PG8_STAGE(PG8_SA(0, 1), a2 + hstepA, voffA);
;             PG8_WAIT_V(8); PG8_WAIT_L(0); PG8_BAR; PG8_MMA(0, 0, At, B0); PG8_MMA(0, 1, At, B1); PG8_BAR; PG8_SCHED;
	v_mfma_f32_16x16x32_bf16 v[62:65], v[160:163], v[196:199], 0
	v_mfma_f32_16x16x32_bf16 v[58:61], v[168:171], v[196:199], 0
	v_mfma_f32_16x16x32_bf16 v[54:57], v[160:163], v[204:207], 0
	v_mfma_f32_16x16x32_bf16 v[46:49], v[168:171], v[204:207], 0
	v_mfma_f32_16x16x32_bf16 v[38:41], v[160:163], v[212:215], 0
	v_mfma_f32_16x16x32_bf16 v[30:33], v[168:171], v[212:215], 0
	v_mfma_f32_16x16x32_bf16 v[22:25], v[160:163], v[220:223], 0
	v_mfma_f32_16x16x32_bf16 v[14:17], v[168:171], v[220:223], 0
	v_mfma_f32_16x16x32_bf16 v[62:65], v[164:167], v[200:203], v[62:65]
	v_mfma_f32_16x16x32_bf16 v[58:61], v[174:177], v[200:203], v[58:61]
	v_mfma_f32_16x16x32_bf16 v[54:57], v[164:167], v[208:211], v[54:57]
	v_mfma_f32_16x16x32_bf16 v[46:49], v[174:177], v[208:211], v[46:49]
	v_mfma_f32_16x16x32_bf16 v[38:41], v[164:167], v[216:219], v[38:41]
	v_mfma_f32_16x16x32_bf16 v[30:33], v[174:177], v[216:219], v[30:33]
	v_mfma_f32_16x16x32_bf16 v[22:25], v[164:167], v[224:227], v[22:25]
	v_mfma_f32_16x16x32_bf16 v[14:17], v[174:177], v[224:227], v[14:17]
	v_mfma_f32_16x16x32_bf16 v[50:53], v[178:181], v[196:199], 0
	v_mfma_f32_16x16x32_bf16 v[42:45], v[188:191], v[196:199], 0
	v_mfma_f32_16x16x32_bf16 v[34:37], v[178:181], v[204:207], 0
	v_mfma_f32_16x16x32_bf16 v[26:29], v[188:191], v[204:207], 0
	v_mfma_f32_16x16x32_bf16 v[18:21], v[178:181], v[212:215], 0
	v_mfma_f32_16x16x32_bf16 v[10:13], v[188:191], v[212:215], 0
	v_mfma_f32_16x16x32_bf16 v[6:9], v[178:181], v[220:223], 0
	v_mfma_f32_16x16x32_bf16 v[2:5], v[188:191], v[220:223], 0
	v_mfma_f32_16x16x32_bf16 v[50:53], v[184:187], v[200:203], v[50:53]
	v_mfma_f32_16x16x32_bf16 v[42:45], v[192:195], v[200:203], v[42:45]
	v_mfma_f32_16x16x32_bf16 v[34:37], v[184:187], v[208:211], v[34:37]
	v_mfma_f32_16x16x32_bf16 v[26:29], v[192:195], v[208:211], v[26:29]
	v_mfma_f32_16x16x32_bf16 v[18:21], v[184:187], v[216:219], v[18:21]
	v_mfma_f32_16x16x32_bf16 v[10:13], v[192:195], v[216:219], v[10:13]
	v_mfma_f32_16x16x32_bf16 v[6:9], v[184:187], v[224:227], v[6:9]
	v_mfma_f32_16x16x32_bf16 v[2:5], v[192:195], v[224:227], v[2:5]
	s_barrier
	s_setprio 0
	s_add_i32 s39, 0, 0x18000
	s_add_i32 s40, 0, 0x1c000
	v_add_u32_e32 v174, s39, v139
	v_add_u32_e32 v192, s40, v139
	ds_read_b128 v[160:163], v174
	ds_read_b128 v[164:167], v174 offset:1024
	ds_read_b128 v[168:171], v174 offset:2048
	ds_read_b128 v[174:177], v174 offset:3072
	ds_read_b128 v[178:181], v192
	ds_read_b128 v[184:187], v192 offset:1024
	ds_read_b128 v[188:191], v192 offset:2048
	ds_read_b128 v[192:195], v192 offset:3072
	s_add_u32 s12, s18, 0x44000
	s_addc_u32 s13, s19, 0
	s_mov_b32 m0, s25
	v_lshl_add_u64 v[236:237], s[12:13], 0, v[152:153]
	ds_read_b128 v[196:199], v173 offset:32768
	ds_read_b128 v[200:203], v173 offset:33792
	ds_read_b128 v[204:207], v173 offset:34816
	ds_read_b128 v[208:211], v173 offset:35840
	ds_read_b128 v[212:215], v173 offset:36864
	ds_read_b128 v[216:219], v173 offset:37888
	ds_read_b128 v[220:223], v173 offset:38912
	ds_read_b128 v[224:227], v173 offset:39936
	global_load_lds_dwordx4 v[236:237], off
	v_lshl_add_u64 v[236:237], s[12:13], 0, v[132:133]
	s_mov_b32 m0, s26
	s_nop 0
	global_load_lds_dwordx4 v[236:237], off
	s_waitcnt vmcnt(8)
	s_waitcnt lgkmcnt(0)
	s_setprio 1
	s_barrier
	v_mfma_f32_16x16x32_bf16 v[126:129], v[160:163], v[196:199], v[126:129]
	v_mfma_f32_16x16x32_bf16 v[122:125], v[168:171], v[196:199], v[122:125]
	v_mfma_f32_16x16x32_bf16 v[118:121], v[160:163], v[204:207], v[118:121]
	v_mfma_f32_16x16x32_bf16 v[110:113], v[168:171], v[204:207], v[110:113]
	v_mfma_f32_16x16x32_bf16 v[102:105], v[160:163], v[212:215], v[102:105]
	v_mfma_f32_16x16x32_bf16 v[94:97], v[168:171], v[212:215], v[94:97]
	v_mfma_f32_16x16x32_bf16 v[86:89], v[160:163], v[220:223], v[86:89]
	v_mfma_f32_16x16x32_bf16 v[78:81], v[168:171], v[220:223], v[78:81]
	v_mfma_f32_16x16x32_bf16 v[126:129], v[164:167], v[200:203], v[126:129]
	v_mfma_f32_16x16x32_bf16 v[122:125], v[174:177], v[200:203], v[122:125]
	v_mfma_f32_16x16x32_bf16 v[118:121], v[164:167], v[208:211], v[118:121]
	v_mfma_f32_16x16x32_bf16 v[110:113], v[174:177], v[208:211], v[110:113]
	v_mfma_f32_16x16x32_bf16 v[102:105], v[164:167], v[216:219], v[102:105]
	v_mfma_f32_16x16x32_bf16 v[94:97], v[174:177], v[216:219], v[94:97]
	v_mfma_f32_16x16x32_bf16 v[86:89], v[164:167], v[224:227], v[86:89]
	v_mfma_f32_16x16x32_bf16 v[78:81], v[174:177], v[224:227], v[78:81]
	v_mfma_f32_16x16x32_bf16 v[114:117], v[178:181], v[196:199], v[114:117]
	v_mfma_f32_16x16x32_bf16 v[106:109], v[188:191], v[196:199], v[106:109]
	v_mfma_f32_16x16x32_bf16 v[98:101], v[178:181], v[204:207], v[98:101]
	v_mfma_f32_16x16x32_bf16 v[90:93], v[188:191], v[204:207], v[90:93]
	v_mfma_f32_16x16x32_bf16 v[82:85], v[178:181], v[212:215], v[82:85]
	v_mfma_f32_16x16x32_bf16 v[74:77], v[188:191], v[212:215], v[74:77]
	v_mfma_f32_16x16x32_bf16 v[70:73], v[178:181], v[220:223], v[70:73]
	v_mfma_f32_16x16x32_bf16 v[66:69], v[188:191], v[220:223], v[66:69]
	v_mfma_f32_16x16x32_bf16 v[114:117], v[184:187], v[200:203], v[114:117]
	v_mfma_f32_16x16x32_bf16 v[106:109], v[192:195], v[200:203], v[106:109]
	v_mfma_f32_16x16x32_bf16 v[98:101], v[184:187], v[208:211], v[98:101]
	v_mfma_f32_16x16x32_bf16 v[90:93], v[192:195], v[208:211], v[90:93]
	v_mfma_f32_16x16x32_bf16 v[82:85], v[184:187], v[216:219], v[82:85]
	v_mfma_f32_16x16x32_bf16 v[74:77], v[192:195], v[216:219], v[74:77]
	v_mfma_f32_16x16x32_bf16 v[70:73], v[184:187], v[224:227], v[70:73]
	v_mfma_f32_16x16x32_bf16 v[66:69], v[192:195], v[224:227], v[66:69]
	s_barrier
; #define PG8_STAGE(bufoff, gbase, voff) do { _Pragma("unroll") for (int _i = 0; _i < 2; ++_i) \
;         __builtin_amdgcn_global_load_lds((const unsigned*)((const char*)(gbase) + (voff)[_i]), (LAS unsigned*)(lds + (bufoff) + ldsw + _i * 8192), 16, 0, 0); } while (0)
; #define PG8_LDA(dst, b, h) do { _Pragma("unroll") for (int m = 0; m < 4; ++m) _Pragma("unroll") for (int k = 0; k < 2; ++k) dst[m][k] = *(const LAS bf16x8*)(lds + PG8_SA(b, h) + aoff + m * 2048 + k * 1024); } while (0)
; #define PG8_LDB(dst, b, h) do { _Pragma("unroll") for (int n = 0; n < 2; ++n) _Pragma("unroll") for (int k = 0; k < 2; ++k) dst[n][k] = *(const LAS bf16x8*)(lds + PG8_SB(b, h) + boff + n * 2048 + k * 1024); } while (0)
; #define PG8_BAR __builtin_amdgcn_s_barrier()
; template <class Epi, bool ALIGN_EPI = PG8_ALIGN, bool SP2 = PG8_SP2>
; __device__ __forceinline__ void gemm_phase(LAS uchar* lds, const Gemm g, const StaticOrder& S, const Epi& E) {
;     ...
;         for (int t = tb; t < tb + tblk; t += 2) {
;             const bool last = (t == nt - 2);
;             const char* a1 = cA + (size_t)(t + 1) * kstep;
;             const char* a2 = last ? nA : cA + (size_t)(t + 2) * kstep; const char* b2 = last ? nB : cB + (size_t)(t + 2) * kstep;
;             const char* a3 = a2 + kstep; const char* b3 = b2 + kstep;
;             if constexpr (SP2) {
;             PG8_LDB(B0, 0, 0); PG8_LDB(B1, 0, 1); PG8_SCHED; PG8_LDA(At, 0, 0); PG8_STAGE(PG8_SA(1, 1), a1 + hstepA, voffA);
;             PG8_WAIT_V(8); PG8_WAIT_L(0); PG8_BAR; PG8_MMA(0, 0, At, B0); PG8_MMA(0, 1, At, B1); PG8_BAR; PG8_SCHED;
;             PG8_LDA(At, 0, 1); PG8_STAGE(PG8_SB(0, 0), b2, voffB); PG8_STAGE(PG8_SB(0, 1), b2 + hstepB, voffB); PG8_STAGE(PG8_SA(0, 0), a2, voffA);
;             PG8_WAIT_V(8); PG8_WAIT_L(0); PG8_BAR; PG8_MMA(1, 0, At, B0); PG8_MMA(1, 1, At, B1); PG8_BAR; PG8_SCHED;
;             PG8_LDB(B0, 1, 0); PG8_LDB(B1, 1, 1); PG8_SCHED; PG8_LDA(At, 1, 0); PG8_STAGE(PG8_SA(0, 1), a2 + hstepA, voffA);
;             PG8_WAIT_V(8); PG8_WAIT_L(0); PG8_BAR; PG8_MMA(0, 0, At, B0); PG8_MMA(0, 1, At, B1); PG8_BAR; PG8_SCHED;
;             PG8_LDA(At, 1, 1); PG8_STAGE(PG8_SB(1, 0), b3, voffB); PG8_STAGE(PG8_SB(1, 1), b3 + hstepB, voffB); PG8_STAGE(PG8_SA(1, 0), a3, voffA);
;             PG8_WAIT_V(8); PG8_WAIT_L(0); PG8_BAR; PG8_MMA(1, 0, At, B0); PG8_MMA(1, 1, At, B1); PG8_BAR; PG8_SCHED;
	s_setprio 0
	s_add_i32 s12, s39, s21
	v_lshl_add_u64 v[228:229], v[228:229], 0, s[84:85]
	s_mov_b32 m0, s12
	ds_read_b128 v[196:199], v173 offset:49152
	ds_read_b128 v[200:203], v173 offset:50176
	ds_read_b128 v[204:207], v173 offset:51200
	ds_read_b128 v[208:211], v173 offset:52224
	ds_read_b128 v[212:215], v173 offset:53248
	ds_read_b128 v[216:219], v173 offset:54272
	ds_read_b128 v[220:223], v173 offset:55296
	ds_read_b128 v[224:227], v173 offset:56320
	global_load_lds_dwordx4 v[228:229], off
	s_add_i32 m0, s12, 0x2000
	s_add_u32 s12, s16, 0x44080
	v_lshl_add_u64 v[228:229], v[230:231], 0, s[84:85]
	s_addc_u32 s13, s17, 0
	s_add_i32 s16, s40, s21
	global_load_lds_dwordx4 v[228:229], off
	v_lshl_add_u64 v[228:229], s[12:13], 0, v[134:135]
	s_mov_b32 m0, s16
	s_nop 0
	global_load_lds_dwordx4 v[228:229], off
	v_lshl_add_u64 v[228:229], s[12:13], 0, v[130:131]
	s_add_i32 m0, s16, 0x2000
	s_nop 0
	global_load_lds_dwordx4 v[228:229], off
	v_lshl_add_u64 v[228:229], v[232:233], 0, s[84:85]
	s_mov_b32 m0, s27
	s_nop 0
	global_load_lds_dwordx4 v[228:229], off
	v_lshl_add_u64 v[228:229], v[234:235], 0, s[84:85]
	s_mov_b32 m0, s28
	s_nop 0
	global_load_lds_dwordx4 v[228:229], off
	s_waitcnt vmcnt(8)
	s_waitcnt lgkmcnt(0)
	s_setprio 1
	s_barrier
	v_mfma_f32_16x16x32_bf16 v[62:65], v[160:163], v[196:199], v[62:65]
	v_mfma_f32_16x16x32_bf16 v[58:61], v[168:171], v[196:199], v[58:61]
	v_mfma_f32_16x16x32_bf16 v[54:57], v[160:163], v[204:207], v[54:57]
	v_mfma_f32_16x16x32_bf16 v[46:49], v[168:171], v[204:207], v[46:49]
	v_mfma_f32_16x16x32_bf16 v[38:41], v[160:163], v[212:215], v[38:41]
	v_mfma_f32_16x16x32_bf16 v[30:33], v[168:171], v[212:215], v[30:33]
	v_mfma_f32_16x16x32_bf16 v[22:25], v[160:163], v[220:223], v[22:25]
	v_mfma_f32_16x16x32_bf16 v[14:17], v[168:171], v[220:223], v[14:17]
	v_mfma_f32_16x16x32_bf16 v[62:65], v[164:167], v[200:203], v[62:65]
	v_mfma_f32_16x16x32_bf16 v[58:61], v[174:177], v[200:203], v[58:61]
	v_mfma_f32_16x16x32_bf16 v[54:57], v[164:167], v[208:211], v[54:57]
	v_mfma_f32_16x16x32_bf16 v[46:49], v[174:177], v[208:211], v[46:49]
	v_mfma_f32_16x16x32_bf16 v[38:41], v[164:167], v[216:219], v[38:41]
	v_mfma_f32_16x16x32_bf16 v[30:33], v[174:177], v[216:219], v[30:33]
	v_mfma_f32_16x16x32_bf16 v[22:25], v[164:167], v[224:227], v[22:25]
	v_mfma_f32_16x16x32_bf16 v[14:17], v[174:177], v[224:227], v[14:17]
	v_mfma_f32_16x16x32_bf16 v[50:53], v[178:181], v[196:199], v[50:53]
	v_mfma_f32_16x16x32_bf16 v[42:45], v[188:191], v[196:199], v[42:45]
	v_mfma_f32_16x16x32_bf16 v[34:37], v[178:181], v[204:207], v[34:37]
	v_mfma_f32_16x16x32_bf16 v[26:29], v[188:191], v[204:207], v[26:29]
	v_mfma_f32_16x16x32_bf16 v[18:21], v[178:181], v[212:215], v[18:21]
	v_mfma_f32_16x16x32_bf16 v[10:13], v[188:191], v[212:215], v[10:13]
	v_mfma_f32_16x16x32_bf16 v[6:9], v[178:181], v[220:223], v[6:9]
	v_mfma_f32_16x16x32_bf16 v[2:5], v[188:191], v[220:223], v[2:5]
	v_mfma_f32_16x16x32_bf16 v[50:53], v[184:187], v[200:203], v[50:53]
	v_mfma_f32_16x16x32_bf16 v[42:45], v[192:195], v[200:203], v[42:45]
	v_mfma_f32_16x16x32_bf16 v[34:37], v[184:187], v[208:211], v[34:37]
	v_mfma_f32_16x16x32_bf16 v[26:29], v[192:195], v[208:211], v[26:29]
	v_mfma_f32_16x16x32_bf16 v[18:21], v[184:187], v[216:219], v[18:21]
	v_mfma_f32_16x16x32_bf16 v[10:13], v[192:195], v[216:219], v[10:13]
	v_mfma_f32_16x16x32_bf16 v[6:9], v[184:187], v[224:227], v[6:9]
	v_mfma_f32_16x16x32_bf16 v[2:5], v[192:195], v[224:227], v[2:5]
	s_barrier
	s_setprio 0
	s_add_i32 s38, s38, 2
	s_add_u32 s36, s36, 0x100
	s_addc_u32 s37, s37, 0
	s_cmp_gt_u32 s38, 13
	s_mov_b64 s[12:13], s[14:15]
.LBB0_669:
	s_add_u32 s14, s12, 0x100
	s_addc_u32 s15, s13, 0
	s_add_i32 s39, 0, 0x10000
	s_cmp_eq_u32 s38, 12
	s_cselect_b32 s19, s5, s15
	s_cselect_b32 s18, s4, s14
	s_cselect_b32 s17, s11, s37
	s_cselect_b32 s16, s10, s36
	s_add_i32 s40, 0, 0x14000
	v_add_u32_e32 v174, s39, v139
	v_add_u32_e32 v192, s40, v139
	ds_read_b128 v[160:163], v174
	ds_read_b128 v[164:167], v174 offset:1024
	ds_read_b128 v[168:171], v174 offset:2048
	ds_read_b128 v[174:177], v174 offset:3072
	ds_read_b128 v[178:181], v192
	ds_read_b128 v[184:187], v192 offset:1024
	ds_read_b128 v[188:191], v192 offset:2048
	ds_read_b128 v[192:195], v192 offset:3072
	v_lshl_add_u64 v[228:229], s[12:13], 0, v[156:157]
	s_add_i32 m0, s23, 0xc000
	ds_read_b128 v[196:199], v173
	ds_read_b128 v[200:203], v173 offset:1024
	ds_read_b128 v[204:207], v173 offset:2048
	ds_read_b128 v[208:211], v173 offset:3072
	ds_read_b128 v[212:215], v173 offset:4096
	ds_read_b128 v[216:219], v173 offset:5120
	ds_read_b128 v[220:223], v173 offset:6144
	ds_read_b128 v[224:227], v173 offset:7168
	global_load_lds_dwordx4 v[228:229], off
	v_lshl_add_u64 v[228:229], s[12:13], 0, v[158:159]
	s_add_i32 m0, s23, 0xe000
	s_nop 0
	global_load_lds_dwordx4 v[228:229], off
	s_waitcnt vmcnt(8)
	s_waitcnt lgkmcnt(0)
	s_setprio 1
	s_barrier
; #define PG8_STAGE(bufoff, gbase, voff) do { _Pragma("unroll") for (int _i = 0; _i < 2; ++_i) \
;         __builtin_amdgcn_global_load_lds((const unsigned*)((const char*)(gbase) + (voff)[_i]), (LAS unsigned*)(lds + (bufoff) + ldsw + _i * 8192), 16, 0, 0); } while (0)
; #define PG8_LDA(dst, b, h) do { _Pragma("unroll") for (int m = 0; m < 4; ++m) _Pragma("unroll") for (int k = 0; k < 2; ++k) dst[m][k] = *(const LAS bf16x8*)(lds + PG8_SA(b, h) + aoff + m * 2048 + k * 1024); } while (0)
; #define PG8_LDB(dst, b, h) do { _Pragma("unroll") for (int n = 0; n < 2; ++n) _Pragma("unroll") for (int k = 0; k < 2; ++k) dst[n][k] = *(const LAS bf16x8*)(lds + PG8_SB(b, h) + boff + n * 2048 + k * 1024); } while (0)
; #define PG8_MMA(ai, bj, At, Bt) do { __builtin_amdgcn_s_setprio(1); _Pragma("unroll") for (int m = 0; m < 4; ++m) _Pragma("unroll") for (int n = 0; n < 2; ++n) _Pragma("unroll") for (int k = 0; k < 2; ++k) \
;         acc[ai][bj][m][n] = __builtin_amdgcn_mfma_f32_16x16x32_bf16(Bt[n][k], At[m][k], acc[ai][bj][m][n], 0, 0, 0); __builtin_amdgcn_s_setprio(0); } while (0)
; #define PG8_WAIT_V(n) asm volatile("s_waitcnt vmcnt(" #n ")" ::: "memory")
; #define PG8_WAIT_L(n) asm volatile("s_waitcnt lgkmcnt(" #n ")" ::: "memory")
; #define PG8_BAR __builtin_amdgcn_s_barrier()
; #define PG8_SCHED __builtin_amdgcn_sched_barrier(0)
; template <class Epi, bool ALIGN_EPI = PG8_ALIGN, bool SP2 = PG8_SP2>
; __device__ __forceinline__ void gemm_phase(LAS uchar* lds, const Gemm g, const StaticOrder& S, const Epi& E) {
;     ...
;             PG8_LDB(B0, 0, 0); PG8_LDB(B1, 0, 1); PG8_SCHED; PG8_LDA(At, 0, 0); PG8_STAGE(PG8_SA(1, 1), a1 + hstepA, voffA);
;             PG8_WAIT_V(8); PG8_WAIT_L(0); PG8_BAR; PG8_MMA(0, 0, At, B0); PG8_MMA(0, 1, At, B1); PG8_BAR; PG8_SCHED;
;             PG8_LDA(At, 0, 1); PG8_STAGE(PG8_SB(0, 0), b2, voffB); PG8_STAGE(PG8_SB(0, 1), b2 + hstepB, voffB); PG8_STAGE(PG8_SA(0, 0), a2, voffA);
;             PG8_WAIT_V(8); PG8_WAIT_L(0); PG8_BAR; PG8_MMA(1, 0, At, B0); PG8_MMA(1, 1, At, B1); PG8_BAR; PG8_SCHED;
	v_mfma_f32_16x16x32_bf16 v[126:129], v[160:163], v[196:199], v[126:129]
	v_mfma_f32_16x16x32_bf16 v[122:125], v[168:171], v[196:199], v[122:125]
	v_mfma_f32_16x16x32_bf16 v[118:121], v[160:163], v[204:207], v[118:121]
	v_mfma_f32_16x16x32_bf16 v[110:113], v[168:171], v[204:207], v[110:113]
	v_mfma_f32_16x16x32_bf16 v[102:105], v[160:163], v[212:215], v[102:105]
	v_mfma_f32_16x16x32_bf16 v[94:97], v[168:171], v[212:215], v[94:97]
	v_mfma_f32_16x16x32_bf16 v[86:89], v[160:163], v[220:223], v[86:89]
	v_mfma_f32_16x16x32_bf16 v[78:81], v[168:171], v[220:223], v[78:81]
	v_mfma_f32_16x16x32_bf16 v[126:129], v[164:167], v[200:203], v[126:129]
	v_mfma_f32_16x16x32_bf16 v[122:125], v[174:177], v[200:203], v[122:125]
	v_mfma_f32_16x16x32_bf16 v[118:121], v[164:167], v[208:211], v[118:121]
	v_mfma_f32_16x16x32_bf16 v[110:113], v[174:177], v[208:211], v[110:113]
	v_mfma_f32_16x16x32_bf16 v[102:105], v[164:167], v[216:219], v[102:105]
	v_mfma_f32_16x16x32_bf16 v[94:97], v[174:177], v[216:219], v[94:97]
	v_mfma_f32_16x16x32_bf16 v[86:89], v[164:167], v[224:227], v[86:89]
	v_mfma_f32_16x16x32_bf16 v[78:81], v[174:177], v[224:227], v[78:81]
	v_mfma_f32_16x16x32_bf16 v[114:117], v[178:181], v[196:199], v[114:117]
	v_mfma_f32_16x16x32_bf16 v[106:109], v[188:191], v[196:199], v[106:109]
	v_mfma_f32_16x16x32_bf16 v[98:101], v[178:181], v[204:207], v[98:101]
	v_mfma_f32_16x16x32_bf16 v[90:93], v[188:191], v[204:207], v[90:93]
	v_mfma_f32_16x16x32_bf16 v[82:85], v[178:181], v[212:215], v[82:85]
	v_mfma_f32_16x16x32_bf16 v[74:77], v[188:191], v[212:215], v[74:77]
	v_mfma_f32_16x16x32_bf16 v[70:73], v[178:181], v[220:223], v[70:73]
	v_mfma_f32_16x16x32_bf16 v[66:69], v[188:191], v[220:223], v[66:69]
	v_mfma_f32_16x16x32_bf16 v[114:117], v[184:187], v[200:203], v[114:117]
	v_mfma_f32_16x16x32_bf16 v[106:109], v[192:195], v[200:203], v[106:109]
	v_mfma_f32_16x16x32_bf16 v[98:101], v[184:187], v[208:211], v[98:101]
	v_mfma_f32_16x16x32_bf16 v[90:93], v[192:195], v[208:211], v[90:93]
	v_mfma_f32_16x16x32_bf16 v[82:85], v[184:187], v[216:219], v[82:85]
	v_mfma_f32_16x16x32_bf16 v[74:77], v[192:195], v[216:219], v[74:77]
	v_mfma_f32_16x16x32_bf16 v[70:73], v[184:187], v[224:227], v[70:73]
	v_mfma_f32_16x16x32_bf16 v[66:69], v[192:195], v[224:227], v[66:69]
	s_barrier
	s_setprio 0
	s_add_i32 s12, s39, s21
	v_lshl_add_u64 v[228:229], s[16:17], 0, v[134:135]
	s_mov_b32 m0, s12
	ds_read_b128 v[196:199], v173 offset:16384
	ds_read_b128 v[200:203], v173 offset:17408
	ds_read_b128 v[204:207], v173 offset:18432
	ds_read_b128 v[208:211], v173 offset:19456
	ds_read_b128 v[212:215], v173 offset:20480
	ds_read_b128 v[216:219], v173 offset:21504
	ds_read_b128 v[220:223], v173 offset:22528
	ds_read_b128 v[224:227], v173 offset:23552
	global_load_lds_dwordx4 v[228:229], off
	s_add_i32 m0, s12, 0x2000
	s_add_u32 s12, s16, 0x44000
	v_lshl_add_u64 v[230:231], s[16:17], 0, v[130:131]
	s_addc_u32 s13, s17, 0
	s_add_i32 s39, s40, s21
	global_load_lds_dwordx4 v[230:231], off
	v_lshl_add_u64 v[232:233], s[12:13], 0, v[134:135]
	s_mov_b32 m0, s39
	v_lshl_add_u64 v[234:235], s[18:19], 0, v[132:133]
	global_load_lds_dwordx4 v[232:233], off
	v_lshl_add_u64 v[232:233], s[12:13], 0, v[130:131]
	s_add_i32 m0, s39, 0x2000
	s_nop 0
	global_load_lds_dwordx4 v[232:233], off
	v_lshl_add_u64 v[232:233], s[18:19], 0, v[152:153]
	s_mov_b32 m0, s23
	s_nop 0
	global_load_lds_dwordx4 v[232:233], off
	s_mov_b32 m0, s24
	s_nop 0
	global_load_lds_dwordx4 v[234:235], off
	s_waitcnt vmcnt(8)
	s_waitcnt lgkmcnt(0)
	s_setprio 1
	s_barrier
	v_mfma_f32_16x16x32_bf16 v[62:65], v[160:163], v[196:199], v[62:65]
	v_mfma_f32_16x16x32_bf16 v[58:61], v[168:171], v[196:199], v[58:61]
	v_mfma_f32_16x16x32_bf16 v[54:57], v[160:163], v[204:207], v[54:57]
	v_mfma_f32_16x16x32_bf16 v[46:49], v[168:171], v[204:207], v[46:49]
	v_mfma_f32_16x16x32_bf16 v[38:41], v[160:163], v[212:215], v[38:41]
	v_mfma_f32_16x16x32_bf16 v[30:33], v[168:171], v[212:215], v[30:33]
	v_mfma_f32_16x16x32_bf16 v[22:25], v[160:163], v[220:223], v[22:25]
	v_mfma_f32_16x16x32_bf16 v[14:17], v[168:171], v[220:223], v[14:17]
	v_mfma_f32_16x16x32_bf16 v[62:65], v[164:167], v[200:203], v[62:65]
	v_mfma_f32_16x16x32_bf16 v[58:61], v[174:177], v[200:203], v[58:61]
	v_mfma_f32_16x16x32_bf16 v[54:57], v[164:167], v[208:211], v[54:57]
	v_mfma_f32_16x16x32_bf16 v[46:49], v[174:177], v[208:211], v[46:49]
	v_mfma_f32_16x16x32_bf16 v[38:41], v[164:167], v[216:219], v[38:41]
	v_mfma_f32_16x16x32_bf16 v[30:33], v[174:177], v[216:219], v[30:33]
	v_mfma_f32_16x16x32_bf16 v[22:25], v[164:167], v[224:227], v[22:25]
	v_mfma_f32_16x16x32_bf16 v[14:17], v[174:177], v[224:227], v[14:17]
	v_mfma_f32_16x16x32_bf16 v[50:53], v[178:181], v[196:199], v[50:53]
	v_mfma_f32_16x16x32_bf16 v[42:45], v[188:191], v[196:199], v[42:45]
	v_mfma_f32_16x16x32_bf16 v[34:37], v[178:181], v[204:207], v[34:37]
	v_mfma_f32_16x16x32_bf16 v[26:29], v[188:191], v[204:207], v[26:29]
	v_mfma_f32_16x16x32_bf16 v[18:21], v[178:181], v[212:215], v[18:21]
	v_mfma_f32_16x16x32_bf16 v[10:13], v[188:191], v[212:215], v[10:13]
	v_mfma_f32_16x16x32_bf16 v[6:9], v[178:181], v[220:223], v[6:9]
	v_mfma_f32_16x16x32_bf16 v[2:5], v[188:191], v[220:223], v[2:5]
	v_mfma_f32_16x16x32_bf16 v[50:53], v[184:187], v[200:203], v[50:53]
	v_mfma_f32_16x16x32_bf16 v[42:45], v[192:195], v[200:203], v[42:45]
	v_mfma_f32_16x16x32_bf16 v[34:37], v[184:187], v[208:211], v[34:37]
	v_mfma_f32_16x16x32_bf16 v[26:29], v[192:195], v[208:211], v[26:29]
	v_mfma_f32_16x16x32_bf16 v[18:21], v[184:187], v[216:219], v[18:21]
	v_mfma_f32_16x16x32_bf16 v[10:13], v[192:195], v[216:219], v[10:13]
	v_mfma_f32_16x16x32_bf16 v[6:9], v[184:187], v[224:227], v[6:9]
	v_mfma_f32_16x16x32_bf16 v[2:5], v[192:195], v[224:227], v[2:5]
	s_barrier
; #define PG8_STAGE(bufoff, gbase, voff) do { _Pragma("unroll") for (int _i = 0; _i < 2; ++_i) \
;         __builtin_amdgcn_global_load_lds((const unsigned*)((const char*)(gbase) + (voff)[_i]), (LAS unsigned*)(lds + (bufoff) + ldsw + _i * 8192), 16, 0, 0); } while (0)
; #define PG8_LDA(dst, b, h) do { _Pragma("unroll") for (int m = 0; m < 4; ++m) _Pragma("unroll") for (int k = 0; k < 2; ++k) dst[m][k] = *(const LAS bf16x8*)(lds + PG8_SA(b, h) + aoff + m * 2048 + k * 1024); } while (0)
; #define PG8_LDB(dst, b, h) do { _Pragma("unroll") for (int n = 0; n < 2; ++n) _Pragma("unroll") for (int k = 0; k < 2; ++k) dst[n][k] = *(const LAS bf16x8*)(lds + PG8_SB(b, h) + boff + n * 2048 + k * 1024); } while (0)
; #define PG8_MMA(ai, bj, At, Bt) do { __builtin_amdgcn_s_setprio(1); _Pragma("unroll") for (int m = 0; m < 4; ++m) _Pragma("unroll") for (int n = 0; n < 2; ++n) _Pragma("unroll") for (int k = 0; k < 2; ++k) \
;         acc[ai][bj][m][n] = __builtin_amdgcn_mfma_f32_16x16x32_bf16(Bt[n][k], At[m][k], acc[ai][bj][m][n], 0, 0, 0); __builtin_amdgcn_s_setprio(0); } while (0)
; #define PG8_WAIT_V(n) asm volatile("s_waitcnt vmcnt(" #n ")" ::: "memory")
; #define PG8_WAIT_L(n) asm volatile("s_waitcnt lgkmcnt(" #n ")" ::: "memory")
; #define PG8_BAR __builtin_amdgcn_s_barrier()
; #define PG8_SCHED __builtin_amdgcn_sched_barrier(0)
; template <class Epi, bool ALIGN_EPI = PG8_ALIGN, bool SP2 = PG8_SP2>
; __device__ __forceinline__ void gemm_phase(LAS uchar* lds, const Gemm g, const StaticOrder& S, const Epi& E) {
;     ...
;             PG8_LDB(B0, 1, 0); PG8_LDB(B1, 1, 1); PG8_SCHED; PG8_LDA(At, 1, 0); PG8_STAGE(PG8_SA(0, 1), a2 + hstepA, voffA);
;             PG8_WAIT_V(8); PG8_WAIT_L(0); PG8_BAR; PG8_MMA(0, 0, At, B0); PG8_MMA(0, 1, At, B1); PG8_BAR; PG8_SCHED;
	s_setprio 0
	s_add_i32 s39, 0, 0x18000
	s_add_i32 s40, 0, 0x1c000
	v_add_u32_e32 v174, s39, v139
	v_add_u32_e32 v192, s40, v139
	ds_read_b128 v[160:163], v174
	ds_read_b128 v[164:167], v174 offset:1024
	ds_read_b128 v[168:171], v174 offset:2048
	ds_read_b128 v[174:177], v174 offset:3072
	ds_read_b128 v[178:181], v192
	ds_read_b128 v[184:187], v192 offset:1024
	ds_read_b128 v[188:191], v192 offset:2048
	ds_read_b128 v[192:195], v192 offset:3072
	s_add_u32 s12, s18, 0x44000
	s_addc_u32 s13, s19, 0
	s_mov_b32 m0, s25
	v_lshl_add_u64 v[236:237], s[12:13], 0, v[152:153]
	ds_read_b128 v[196:199], v173 offset:32768
	ds_read_b128 v[200:203], v173 offset:33792
	ds_read_b128 v[204:207], v173 offset:34816
	ds_read_b128 v[208:211], v173 offset:35840
	ds_read_b128 v[212:215], v173 offset:36864
	ds_read_b128 v[216:219], v173 offset:37888
	ds_read_b128 v[220:223], v173 offset:38912
	ds_read_b128 v[224:227], v173 offset:39936
	global_load_lds_dwordx4 v[236:237], off
	v_lshl_add_u64 v[236:237], s[12:13], 0, v[132:133]
	s_mov_b32 m0, s26
	s_nop 0
	global_load_lds_dwordx4 v[236:237], off
	s_waitcnt vmcnt(8)
	s_waitcnt lgkmcnt(0)
	s_setprio 1
	s_barrier
	v_mfma_f32_16x16x32_bf16 v[126:129], v[160:163], v[196:199], v[126:129]
	v_mfma_f32_16x16x32_bf16 v[122:125], v[168:171], v[196:199], v[122:125]
	v_mfma_f32_16x16x32_bf16 v[118:121], v[160:163], v[204:207], v[118:121]
	v_mfma_f32_16x16x32_bf16 v[110:113], v[168:171], v[204:207], v[110:113]
	v_mfma_f32_16x16x32_bf16 v[102:105], v[160:163], v[212:215], v[102:105]
	v_mfma_f32_16x16x32_bf16 v[94:97], v[168:171], v[212:215], v[94:97]
	v_mfma_f32_16x16x32_bf16 v[86:89], v[160:163], v[220:223], v[86:89]
	v_mfma_f32_16x16x32_bf16 v[78:81], v[168:171], v[220:223], v[78:81]
	v_mfma_f32_16x16x32_bf16 v[126:129], v[164:167], v[200:203], v[126:129]
	v_mfma_f32_16x16x32_bf16 v[122:125], v[174:177], v[200:203], v[122:125]
	v_mfma_f32_16x16x32_bf16 v[118:121], v[164:167], v[208:211], v[118:121]
	v_mfma_f32_16x16x32_bf16 v[110:113], v[174:177], v[208:211], v[110:113]
	v_mfma_f32_16x16x32_bf16 v[102:105], v[164:167], v[216:219], v[102:105]
	v_mfma_f32_16x16x32_bf16 v[94:97], v[174:177], v[216:219], v[94:97]
	v_mfma_f32_16x16x32_bf16 v[86:89], v[164:167], v[224:227], v[86:89]
	v_mfma_f32_16x16x32_bf16 v[78:81], v[174:177], v[224:227], v[78:81]
	v_mfma_f32_16x16x32_bf16 v[114:117], v[178:181], v[196:199], v[114:117]
	v_mfma_f32_16x16x32_bf16 v[106:109], v[188:191], v[196:199], v[106:109]
	v_mfma_f32_16x16x32_bf16 v[98:101], v[178:181], v[204:207], v[98:101]
	v_mfma_f32_16x16x32_bf16 v[90:93], v[188:191], v[204:207], v[90:93]
	v_mfma_f32_16x16x32_bf16 v[82:85], v[178:181], v[212:215], v[82:85]
	v_mfma_f32_16x16x32_bf16 v[74:77], v[188:191], v[212:215], v[74:77]
	v_mfma_f32_16x16x32_bf16 v[70:73], v[178:181], v[220:223], v[70:73]
	v_mfma_f32_16x16x32_bf16 v[66:69], v[188:191], v[220:223], v[66:69]
	v_mfma_f32_16x16x32_bf16 v[114:117], v[184:187], v[200:203], v[114:117]
	v_mfma_f32_16x16x32_bf16 v[106:109], v[192:195], v[200:203], v[106:109]
	v_mfma_f32_16x16x32_bf16 v[98:101], v[184:187], v[208:211], v[98:101]
	v_mfma_f32_16x16x32_bf16 v[90:93], v[192:195], v[208:211], v[90:93]
	v_mfma_f32_16x16x32_bf16 v[82:85], v[184:187], v[216:219], v[82:85]
	v_mfma_f32_16x16x32_bf16 v[74:77], v[192:195], v[216:219], v[74:77]
	v_mfma_f32_16x16x32_bf16 v[70:73], v[184:187], v[224:227], v[70:73]
	v_mfma_f32_16x16x32_bf16 v[66:69], v[192:195], v[224:227], v[66:69]
	s_barrier
; #define PG8_STAGE(bufoff, gbase, voff) do { _Pragma("unroll") for (int _i = 0; _i < 2; ++_i) \
;         __builtin_amdgcn_global_load_lds((const unsigned*)((const char*)(gbase) + (voff)[_i]), (LAS unsigned*)(lds + (bufoff) + ldsw + _i * 8192), 16, 0, 0); } while (0)
; #define PG8_LDA(dst, b, h) do { _Pragma("unroll") for (int m = 0; m < 4; ++m) _Pragma("unroll") for (int k = 0; k < 2; ++k) dst[m][k] = *(const LAS bf16x8*)(lds + PG8_SA(b, h) + aoff + m * 2048 + k * 1024); } while (0)
; #define PG8_MMA(ai, bj, At, Bt) do { __builtin_amdgcn_s_setprio(1); _Pragma("unroll") for (int m = 0; m < 4; ++m) _Pragma("unroll") for (int n = 0; n < 2; ++n) _Pragma("unroll") for (int k = 0; k < 2; ++k) \
;         acc[ai][bj][m][n] = __builtin_amdgcn_mfma_f32_16x16x32_bf16(Bt[n][k], At[m][k], acc[ai][bj][m][n], 0, 0, 0); __builtin_amdgcn_s_setprio(0); } while (0)
; #define PG8_WAIT_V(n) asm volatile("s_waitcnt vmcnt(" #n ")" ::: "memory")
; #define PG8_WAIT_L(n) asm volatile("s_waitcnt lgkmcnt(" #n ")" ::: "memory")
; #define PG8_BAR __builtin_amdgcn_s_barrier()
; #define PG8_SCHED __builtin_amdgcn_sched_barrier(0)
; template <class Epi, bool ALIGN_EPI = PG8_ALIGN, bool SP2 = PG8_SP2>
; __device__ __forceinline__ void gemm_phase(LAS uchar* lds, const Gemm g, const StaticOrder& S, const Epi& E) {
;     ...
;             PG8_LDA(At, 1, 1); PG8_STAGE(PG8_SB(1, 0), b3, voffB); PG8_STAGE(PG8_SB(1, 1), b3 + hstepB, voffB); PG8_STAGE(PG8_SA(1, 0), a3, voffA);
;             PG8_WAIT_V(8); PG8_WAIT_L(0); PG8_BAR; PG8_MMA(1, 0, At, B0); PG8_MMA(1, 1, At, B1); PG8_BAR; PG8_SCHED;
;     ...
;         if constexpr (ALIGN_EPI) { if (wr == 0) PG8_BAR; }
	s_setprio 0
	s_add_i32 s12, s39, s21
	v_lshl_add_u64 v[228:229], v[228:229], 0, s[84:85]
	s_mov_b32 m0, s12
	ds_read_b128 v[196:199], v173 offset:49152
	ds_read_b128 v[200:203], v173 offset:50176
	ds_read_b128 v[204:207], v173 offset:51200
	ds_read_b128 v[208:211], v173 offset:52224
	ds_read_b128 v[212:215], v173 offset:53248
	ds_read_b128 v[216:219], v173 offset:54272
	ds_read_b128 v[220:223], v173 offset:55296
	ds_read_b128 v[224:227], v173 offset:56320
	global_load_lds_dwordx4 v[228:229], off
	s_add_i32 m0, s12, 0x2000
	s_add_u32 s12, s16, 0x44080
	v_lshl_add_u64 v[228:229], v[230:231], 0, s[84:85]
	s_addc_u32 s13, s17, 0
	s_add_i32 s16, s40, s21
	global_load_lds_dwordx4 v[228:229], off
	v_lshl_add_u64 v[228:229], s[12:13], 0, v[134:135]
	s_mov_b32 m0, s16
	s_nop 0
	global_load_lds_dwordx4 v[228:229], off
	v_lshl_add_u64 v[228:229], s[12:13], 0, v[130:131]
	s_add_i32 m0, s16, 0x2000
	s_nop 0
	global_load_lds_dwordx4 v[228:229], off
	v_lshl_add_u64 v[228:229], v[232:233], 0, s[84:85]
	s_mov_b32 m0, s27
	s_nop 0
	global_load_lds_dwordx4 v[228:229], off
	v_lshl_add_u64 v[228:229], v[234:235], 0, s[84:85]
	s_mov_b32 m0, s28
	s_nop 0
	global_load_lds_dwordx4 v[228:229], off
	s_waitcnt vmcnt(8)
	s_waitcnt lgkmcnt(0)
	s_setprio 1
	s_barrier
	v_mfma_f32_16x16x32_bf16 v[62:65], v[160:163], v[196:199], v[62:65]
	v_mfma_f32_16x16x32_bf16 v[58:61], v[168:171], v[196:199], v[58:61]
	v_mfma_f32_16x16x32_bf16 v[54:57], v[160:163], v[204:207], v[54:57]
	v_mfma_f32_16x16x32_bf16 v[46:49], v[168:171], v[204:207], v[46:49]
	v_mfma_f32_16x16x32_bf16 v[38:41], v[160:163], v[212:215], v[38:41]
	v_mfma_f32_16x16x32_bf16 v[30:33], v[168:171], v[212:215], v[30:33]
	v_mfma_f32_16x16x32_bf16 v[22:25], v[160:163], v[220:223], v[22:25]
	v_mfma_f32_16x16x32_bf16 v[14:17], v[168:171], v[220:223], v[14:17]
	v_mfma_f32_16x16x32_bf16 v[62:65], v[164:167], v[200:203], v[62:65]
	v_mfma_f32_16x16x32_bf16 v[58:61], v[174:177], v[200:203], v[58:61]
	v_mfma_f32_16x16x32_bf16 v[54:57], v[164:167], v[208:211], v[54:57]
	v_mfma_f32_16x16x32_bf16 v[46:49], v[174:177], v[208:211], v[46:49]
	v_mfma_f32_16x16x32_bf16 v[38:41], v[164:167], v[216:219], v[38:41]
	v_mfma_f32_16x16x32_bf16 v[30:33], v[174:177], v[216:219], v[30:33]
	v_mfma_f32_16x16x32_bf16 v[22:25], v[164:167], v[224:227], v[22:25]
	v_mfma_f32_16x16x32_bf16 v[14:17], v[174:177], v[224:227], v[14:17]
	v_mfma_f32_16x16x32_bf16 v[50:53], v[178:181], v[196:199], v[50:53]
	v_mfma_f32_16x16x32_bf16 v[42:45], v[188:191], v[196:199], v[42:45]
	v_mfma_f32_16x16x32_bf16 v[34:37], v[178:181], v[204:207], v[34:37]
	v_mfma_f32_16x16x32_bf16 v[26:29], v[188:191], v[204:207], v[26:29]
	v_mfma_f32_16x16x32_bf16 v[18:21], v[178:181], v[212:215], v[18:21]
	v_mfma_f32_16x16x32_bf16 v[10:13], v[188:191], v[212:215], v[10:13]
	v_mfma_f32_16x16x32_bf16 v[6:9], v[178:181], v[220:223], v[6:9]
	v_mfma_f32_16x16x32_bf16 v[2:5], v[188:191], v[220:223], v[2:5]
	v_mfma_f32_16x16x32_bf16 v[50:53], v[184:187], v[200:203], v[50:53]
	v_mfma_f32_16x16x32_bf16 v[42:45], v[192:195], v[200:203], v[42:45]
	v_mfma_f32_16x16x32_bf16 v[34:37], v[184:187], v[208:211], v[34:37]
	v_mfma_f32_16x16x32_bf16 v[26:29], v[192:195], v[208:211], v[26:29]
	v_mfma_f32_16x16x32_bf16 v[18:21], v[184:187], v[216:219], v[18:21]
	v_mfma_f32_16x16x32_bf16 v[10:13], v[192:195], v[216:219], v[10:13]
	v_mfma_f32_16x16x32_bf16 v[6:9], v[184:187], v[224:227], v[6:9]
	v_mfma_f32_16x16x32_bf16 v[2:5], v[192:195], v[224:227], v[2:5]
	s_barrier
	s_setprio 0
	s_add_i32 s38, s38, 2
	s_add_u32 s36, s36, 0x100
	s_addc_u32 s37, s37, 0
	s_cmp_gt_u32 s38, 13
	s_mov_b64 s[12:13], s[14:15]
	s_cbranch_scc0 .LBB0_669
	s_and_b64 vcc, exec, s[8:9]
	s_cbranch_vccz .LBB0_672
	s_barrier

; #define PG8_STAGE(bufoff, gbase, voff) do { _Pragma("unroll") for (int _i = 0; _i < 2; ++_i) \
;         __builtin_amdgcn_global_load_lds((const unsigned*)((const char*)(gbase) + (voff)[_i]), (LAS unsigned*)(lds + (bufoff) + ldsw + _i * 8192), 16, 0, 0); } while (0)
; #define PG8_LDA(dst, b, h) do { _Pragma("unroll") for (int m = 0; m < 4; ++m) _Pragma("unroll") for (int k = 0; k < 2; ++k) dst[m][k] = *(const LAS bf16x8*)(lds + PG8_SA(b, h) + aoff + m * 2048 + k * 1024); } while (0)
; #define PG8_LDB(dst, b, h) do { _Pragma("unroll") for (int n = 0; n < 2; ++n) _Pragma("unroll") for (int k = 0; k < 2; ++k) dst[n][k] = *(const LAS bf16x8*)(lds + PG8_SB(b, h) + boff + n * 2048 + k * 1024); } while (0)
; #define PG8_MMA(ai, bj, At, Bt) do { __builtin_amdgcn_s_setprio(1); _Pragma("unroll") for (int m = 0; m < 4; ++m) _Pragma("unroll") for (int n = 0; n < 2; ++n) _Pragma("unroll") for (int k = 0; k < 2; ++k) \
;         acc[ai][bj][m][n] = __builtin_amdgcn_mfma_f32_16x16x32_bf16(Bt[n][k], At[m][k], acc[ai][bj][m][n], 0, 0, 0); __builtin_amdgcn_s_setprio(0); } while (0)
; #define PG8_WAIT_V(n) asm volatile("s_waitcnt vmcnt(" #n ")" ::: "memory")
; #define PG8_WAIT_L(n) asm volatile("s_waitcnt lgkmcnt(" #n ")" ::: "memory")
; #define PG8_BAR __builtin_amdgcn_s_barrier()
; #define PG8_SCHED __builtin_amdgcn_sched_barrier(0)
; template <class Epi, bool ALIGN_EPI = PG8_ALIGN, bool SP2 = PG8_SP2>
; __device__ __forceinline__ void gemm_phase(LAS uchar* lds, const Gemm g, const StaticOrder& S, const Epi& E) {
;     ...
;             const bool last = (t == nt - 2);
;             const char* a1 = cA + (size_t)(t + 1) * kstep;
;             const char* a2 = last ? nA : cA + (size_t)(t + 2) * kstep; const char* b2 = last ? nB : cB + (size_t)(t + 2) * kstep;
;             const char* a3 = a2 + kstep; const char* b3 = b2 + kstep;
;             if constexpr (SP2) {
;             PG8_LDB(B0, 0, 0); PG8_LDB(B1, 0, 1); PG8_SCHED; PG8_LDA(At, 0, 0); PG8_STAGE(PG8_SA(1, 1), a1 + hstepA, voffA);
;             PG8_WAIT_V(8); PG8_WAIT_L(0); PG8_BAR; PG8_MMA(0, 0, At, B0); PG8_MMA(0, 1, At, B1); PG8_BAR; PG8_SCHED;
;             PG8_LDA(At, 0, 1); PG8_STAGE(PG8_SB(0, 0), b2, voffB); PG8_STAGE(PG8_SB(0, 1), b2 + hstepB, voffB); PG8_STAGE(PG8_SA(0, 0), a2, voffA);
;             PG8_WAIT_V(8); PG8_WAIT_L(0); PG8_BAR; PG8_MMA(1, 0, At, B0); PG8_MMA(1, 1, At, B1); PG8_BAR; PG8_SCHED;
.LBB0_836:
	s_add_u32 s36, s14, 0x100
	s_addc_u32 s37, s15, 0
	s_mov_b32 s38, -2
	s_add_u32 s14, s12, 0x100
	s_addc_u32 s15, s13, 0
	s_add_i32 s39, 0, 0x10000
	s_cmp_eq_u32 s38, 12
	s_cselect_b32 s19, s5, s15
	s_cselect_b32 s18, s4, s14
	s_cselect_b32 s17, s11, s37
	s_cselect_b32 s16, s10, s36
	s_add_i32 s40, 0, 0x14000
	v_add_u32_e32 v174, s39, v139
	v_add_u32_e32 v192, s40, v139
	ds_read_b128 v[160:163], v174
	ds_read_b128 v[166:169], v174 offset:1024
	ds_read_b128 v[170:173], v174 offset:2048
	ds_read_b128 v[174:177], v174 offset:3072
	ds_read_b128 v[178:181], v192
	ds_read_b128 v[184:187], v192 offset:1024
	ds_read_b128 v[188:191], v192 offset:2048
	ds_read_b128 v[192:195], v192 offset:3072
	v_lshl_add_u64 v[228:229], s[12:13], 0, v[156:157]
	s_add_i32 m0, s23, 0xc000
	ds_read_b128 v[196:199], v165
	ds_read_b128 v[200:203], v165 offset:1024
	ds_read_b128 v[204:207], v165 offset:2048
	ds_read_b128 v[208:211], v165 offset:3072
	ds_read_b128 v[212:215], v165 offset:4096
	ds_read_b128 v[216:219], v165 offset:5120
	ds_read_b128 v[220:223], v165 offset:6144
	ds_read_b128 v[224:227], v165 offset:7168
	global_load_lds_dwordx4 v[228:229], off
	v_lshl_add_u64 v[228:229], s[12:13], 0, v[158:159]
	s_add_i32 m0, s23, 0xe000
	s_nop 0
	global_load_lds_dwordx4 v[228:229], off
	s_waitcnt vmcnt(8)
	s_waitcnt lgkmcnt(0)
	s_setprio 1
	s_barrier
	v_mfma_f32_16x16x32_bf16 v[126:129], v[160:163], v[196:199], 0
	v_mfma_f32_16x16x32_bf16 v[122:125], v[170:173], v[196:199], 0
	v_mfma_f32_16x16x32_bf16 v[118:121], v[160:163], v[204:207], 0
	v_mfma_f32_16x16x32_bf16 v[110:113], v[170:173], v[204:207], 0
	v_mfma_f32_16x16x32_bf16 v[102:105], v[160:163], v[212:215], 0
	v_mfma_f32_16x16x32_bf16 v[94:97], v[170:173], v[212:215], 0
	v_mfma_f32_16x16x32_bf16 v[86:89], v[160:163], v[220:223], 0
	v_mfma_f32_16x16x32_bf16 v[78:81], v[170:173], v[220:223], 0
	v_mfma_f32_16x16x32_bf16 v[126:129], v[166:169], v[200:203], v[126:129]
	v_mfma_f32_16x16x32_bf16 v[122:125], v[174:177], v[200:203], v[122:125]
	v_mfma_f32_16x16x32_bf16 v[118:121], v[166:169], v[208:211], v[118:121]
	v_mfma_f32_16x16x32_bf16 v[110:113], v[174:177], v[208:211], v[110:113]
	v_mfma_f32_16x16x32_bf16 v[102:105], v[166:169], v[216:219], v[102:105]
	v_mfma_f32_16x16x32_bf16 v[94:97], v[174:177], v[216:219], v[94:97]
	v_mfma_f32_16x16x32_bf16 v[86:89], v[166:169], v[224:227], v[86:89]
	v_mfma_f32_16x16x32_bf16 v[78:81], v[174:177], v[224:227], v[78:81]
	v_mfma_f32_16x16x32_bf16 v[114:117], v[178:181], v[196:199], 0
	v_mfma_f32_16x16x32_bf16 v[106:109], v[188:191], v[196:199], 0
	v_mfma_f32_16x16x32_bf16 v[98:101], v[178:181], v[204:207], 0
	v_mfma_f32_16x16x32_bf16 v[90:93], v[188:191], v[204:207], 0
	v_mfma_f32_16x16x32_bf16 v[82:85], v[178:181], v[212:215], 0
	v_mfma_f32_16x16x32_bf16 v[74:77], v[188:191], v[212:215], 0
	v_mfma_f32_16x16x32_bf16 v[70:73], v[178:181], v[220:223], 0
	v_mfma_f32_16x16x32_bf16 v[66:69], v[188:191], v[220:223], 0
	v_mfma_f32_16x16x32_bf16 v[114:117], v[184:187], v[200:203], v[114:117]
	v_mfma_f32_16x16x32_bf16 v[106:109], v[192:195], v[200:203], v[106:109]
	v_mfma_f32_16x16x32_bf16 v[98:101], v[184:187], v[208:211], v[98:101]
	v_mfma_f32_16x16x32_bf16 v[90:93], v[192:195], v[208:211], v[90:93]
	v_mfma_f32_16x16x32_bf16 v[82:85], v[184:187], v[216:219], v[82:85]
	v_mfma_f32_16x16x32_bf16 v[74:77], v[192:195], v[216:219], v[74:77]
	v_mfma_f32_16x16x32_bf16 v[70:73], v[184:187], v[224:227], v[70:73]
	v_mfma_f32_16x16x32_bf16 v[66:69], v[192:195], v[224:227], v[66:69]
	s_barrier
	s_setprio 0
	s_add_i32 s12, s39, s22
	v_lshl_add_u64 v[228:229], s[16:17], 0, v[132:133]
	s_mov_b32 m0, s12
	ds_read_b128 v[196:199], v165 offset:16384
	ds_read_b128 v[200:203], v165 offset:17408
	ds_read_b128 v[204:207], v165 offset:18432
	ds_read_b128 v[208:211], v165 offset:19456
	ds_read_b128 v[212:215], v165 offset:20480
	ds_read_b128 v[216:219], v165 offset:21504
	ds_read_b128 v[220:223], v165 offset:22528
	ds_read_b128 v[224:227], v165 offset:23552
	global_load_lds_dwordx4 v[228:229], off
	s_add_i32 m0, s12, 0x2000
	s_add_u32 s12, s16, 0x44000
	v_lshl_add_u64 v[230:231], s[16:17], 0, v[152:153]
	s_addc_u32 s13, s17, 0
	s_add_i32 s39, s40, s22
	global_load_lds_dwordx4 v[230:231], off
	v_lshl_add_u64 v[232:233], s[12:13], 0, v[132:133]
	s_mov_b32 m0, s39
	v_lshl_add_u64 v[234:235], s[18:19], 0, v[134:135]
	global_load_lds_dwordx4 v[232:233], off
	v_lshl_add_u64 v[232:233], s[12:13], 0, v[152:153]
	s_add_i32 m0, s39, 0x2000
	s_nop 0
	global_load_lds_dwordx4 v[232:233], off
	v_lshl_add_u64 v[232:233], s[18:19], 0, v[130:131]
	s_mov_b32 m0, s23
	s_nop 0
	global_load_lds_dwordx4 v[232:233], off
	s_mov_b32 m0, s24
	s_nop 0
	global_load_lds_dwordx4 v[234:235], off
	s_waitcnt vmcnt(8)
	s_waitcnt lgkmcnt(0)
	s_setprio 1
	s_barrier
; #define PG8_STAGE(bufoff, gbase, voff) do { _Pragma("unroll") for (int _i = 0; _i < 2; ++_i) \
;         __builtin_amdgcn_global_load_lds((const unsigned*)((const char*)(gbase) + (voff)[_i]), (LAS unsigned*)(lds + (bufoff) + ldsw + _i * 8192), 16, 0, 0); } while (0)
; #define PG8_LDA(dst, b, h) do { _Pragma("unroll") for (int m = 0; m < 4; ++m) _Pragma("unroll") for (int k = 0; k < 2; ++k) dst[m][k] = *(const LAS bf16x8*)(lds + PG8_SA(b, h) + aoff + m * 2048 + k * 1024); } while (0)
; #define PG8_LDB(dst, b, h) do { _Pragma("unroll") for (int n = 0; n < 2; ++n) _Pragma("unroll") for (int k = 0; k < 2; ++k) dst[n][k] = *(const LAS bf16x8*)(lds + PG8_SB(b, h) + boff + n * 2048 + k * 1024); } while (0)
; #define PG8_MMA(ai, bj, At, Bt) do { __builtin_amdgcn_s_setprio(1); _Pragma("unroll") for (int m = 0; m < 4; ++m) _Pragma("unroll") for (int n = 0; n < 2; ++n) _Pragma("unroll") for (int k = 0; k < 2; ++k) \
;         acc[ai][bj][m][n] = __builtin_amdgcn_mfma_f32_16x16x32_bf16(Bt[n][k], At[m][k], acc[ai][bj][m][n], 0, 0, 0); __builtin_amdgcn_s_setprio(0); } while (0)
; #define PG8_WAIT_V(n) asm volatile("s_waitcnt vmcnt(" #n ")" ::: "memory")
; #define PG8_WAIT_L(n) asm volatile("s_waitcnt lgkmcnt(" #n ")" ::: "memory")
; #define PG8_BAR __builtin_amdgcn_s_barrier()
; #define PG8_SCHED __builtin_amdgcn_sched_barrier(0)
; template <class Epi, bool ALIGN_EPI = PG8_ALIGN, bool SP2 = PG8_SP2>
; __device__ __forceinline__ void gemm_phase(LAS uchar* lds, const Gemm g, const StaticOrder& S, const Epi& E) {
;     ...
;             PG8_WAIT_V(8); PG8_WAIT_L(0); PG8_BAR; PG8_MMA(1, 0, At, B0); PG8_MMA(1, 1, At, B1); PG8_BAR; PG8_SCHED;
;             PG8_LDB(B0, 1, 0); PG8_LDB(B1, 1, 1); PG8_SCHED; PG8_LDA(At, 1, 0); PG8_STAGE(PG8_SA(0, 1), a2 + hstepA, voffA);
;             PG8_WAIT_V(8); PG8_WAIT_L(0); PG8_BAR; PG8_MMA(0, 0, At, B0); PG8_MMA(0, 1, At, B1); PG8_BAR; PG8_SCHED;
	v_mfma_f32_16x16x32_bf16 v[62:65], v[160:163], v[196:199], 0
	v_mfma_f32_16x16x32_bf16 v[58:61], v[170:173], v[196:199], 0
	v_mfma_f32_16x16x32_bf16 v[54:57], v[160:163], v[204:207], 0
	v_mfma_f32_16x16x32_bf16 v[46:49], v[170:173], v[204:207], 0
	v_mfma_f32_16x16x32_bf16 v[38:41], v[160:163], v[212:215], 0
	v_mfma_f32_16x16x32_bf16 v[30:33], v[170:173], v[212:215], 0
	v_mfma_f32_16x16x32_bf16 v[22:25], v[160:163], v[220:223], 0
	v_mfma_f32_16x16x32_bf16 v[14:17], v[170:173], v[220:223], 0
	v_mfma_f32_16x16x32_bf16 v[62:65], v[166:169], v[200:203], v[62:65]
	v_mfma_f32_16x16x32_bf16 v[58:61], v[174:177], v[200:203], v[58:61]
	v_mfma_f32_16x16x32_bf16 v[54:57], v[166:169], v[208:211], v[54:57]
	v_mfma_f32_16x16x32_bf16 v[46:49], v[174:177], v[208:211], v[46:49]
	v_mfma_f32_16x16x32_bf16 v[38:41], v[166:169], v[216:219], v[38:41]
	v_mfma_f32_16x16x32_bf16 v[30:33], v[174:177], v[216:219], v[30:33]
	v_mfma_f32_16x16x32_bf16 v[22:25], v[166:169], v[224:227], v[22:25]
	v_mfma_f32_16x16x32_bf16 v[14:17], v[174:177], v[224:227], v[14:17]
	v_mfma_f32_16x16x32_bf16 v[50:53], v[178:181], v[196:199], 0
	v_mfma_f32_16x16x32_bf16 v[42:45], v[188:191], v[196:199], 0
	v_mfma_f32_16x16x32_bf16 v[34:37], v[178:181], v[204:207], 0
	v_mfma_f32_16x16x32_bf16 v[26:29], v[188:191], v[204:207], 0
	v_mfma_f32_16x16x32_bf16 v[18:21], v[178:181], v[212:215], 0
	v_mfma_f32_16x16x32_bf16 v[10:13], v[188:191], v[212:215], 0
	v_mfma_f32_16x16x32_bf16 v[6:9], v[178:181], v[220:223], 0
	v_mfma_f32_16x16x32_bf16 v[2:5], v[188:191], v[220:223], 0
	v_mfma_f32_16x16x32_bf16 v[50:53], v[184:187], v[200:203], v[50:53]
	v_mfma_f32_16x16x32_bf16 v[42:45], v[192:195], v[200:203], v[42:45]
	v_mfma_f32_16x16x32_bf16 v[34:37], v[184:187], v[208:211], v[34:37]
	v_mfma_f32_16x16x32_bf16 v[26:29], v[192:195], v[208:211], v[26:29]
	v_mfma_f32_16x16x32_bf16 v[18:21], v[184:187], v[216:219], v[18:21]
	v_mfma_f32_16x16x32_bf16 v[10:13], v[192:195], v[216:219], v[10:13]
	v_mfma_f32_16x16x32_bf16 v[6:9], v[184:187], v[224:227], v[6:9]
	v_mfma_f32_16x16x32_bf16 v[2:5], v[192:195], v[224:227], v[2:5]
	s_barrier
	s_setprio 0
	s_add_i32 s39, 0, 0x18000
	s_add_i32 s40, 0, 0x1c000
	v_add_u32_e32 v174, s39, v139
	v_add_u32_e32 v192, s40, v139
	ds_read_b128 v[160:163], v174
	ds_read_b128 v[166:169], v174 offset:1024
	ds_read_b128 v[170:173], v174 offset:2048
	ds_read_b128 v[174:177], v174 offset:3072
	ds_read_b128 v[178:181], v192
	ds_read_b128 v[184:187], v192 offset:1024
	ds_read_b128 v[188:191], v192 offset:2048
	ds_read_b128 v[192:195], v192 offset:3072
	s_add_u32 s12, s18, 0x44000
	s_addc_u32 s13, s19, 0
	s_mov_b32 m0, s25
	v_lshl_add_u64 v[236:237], s[12:13], 0, v[130:131]
	ds_read_b128 v[196:199], v165 offset:32768
	ds_read_b128 v[200:203], v165 offset:33792
	ds_read_b128 v[204:207], v165 offset:34816
	ds_read_b128 v[208:211], v165 offset:35840
	ds_read_b128 v[212:215], v165 offset:36864
	ds_read_b128 v[216:219], v165 offset:37888
	ds_read_b128 v[220:223], v165 offset:38912
	ds_read_b128 v[224:227], v165 offset:39936
	global_load_lds_dwordx4 v[236:237], off
	v_lshl_add_u64 v[236:237], s[12:13], 0, v[134:135]
	s_mov_b32 m0, s26
	s_nop 0
	global_load_lds_dwordx4 v[236:237], off
	s_waitcnt vmcnt(8)
	s_waitcnt lgkmcnt(0)
	s_setprio 1
	s_barrier
	v_mfma_f32_16x16x32_bf16 v[126:129], v[160:163], v[196:199], v[126:129]
	v_mfma_f32_16x16x32_bf16 v[122:125], v[170:173], v[196:199], v[122:125]
	v_mfma_f32_16x16x32_bf16 v[118:121], v[160:163], v[204:207], v[118:121]
	v_mfma_f32_16x16x32_bf16 v[110:113], v[170:173], v[204:207], v[110:113]
	v_mfma_f32_16x16x32_bf16 v[102:105], v[160:163], v[212:215], v[102:105]
	v_mfma_f32_16x16x32_bf16 v[94:97], v[170:173], v[212:215], v[94:97]
	v_mfma_f32_16x16x32_bf16 v[86:89], v[160:163], v[220:223], v[86:89]
	v_mfma_f32_16x16x32_bf16 v[78:81], v[170:173], v[220:223], v[78:81]
	v_mfma_f32_16x16x32_bf16 v[126:129], v[166:169], v[200:203], v[126:129]
	v_mfma_f32_16x16x32_bf16 v[122:125], v[174:177], v[200:203], v[122:125]
	v_mfma_f32_16x16x32_bf16 v[118:121], v[166:169], v[208:211], v[118:121]
	v_mfma_f32_16x16x32_bf16 v[110:113], v[174:177], v[208:211], v[110:113]
	v_mfma_f32_16x16x32_bf16 v[102:105], v[166:169], v[216:219], v[102:105]
	v_mfma_f32_16x16x32_bf16 v[94:97], v[174:177], v[216:219], v[94:97]
	v_mfma_f32_16x16x32_bf16 v[86:89], v[166:169], v[224:227], v[86:89]
	v_mfma_f32_16x16x32_bf16 v[78:81], v[174:177], v[224:227], v[78:81]
	v_mfma_f32_16x16x32_bf16 v[114:117], v[178:181], v[196:199], v[114:117]
	v_mfma_f32_16x16x32_bf16 v[106:109], v[188:191], v[196:199], v[106:109]
	v_mfma_f32_16x16x32_bf16 v[98:101], v[178:181], v[204:207], v[98:101]
	v_mfma_f32_16x16x32_bf16 v[90:93], v[188:191], v[204:207], v[90:93]
	v_mfma_f32_16x16x32_bf16 v[82:85], v[178:181], v[212:215], v[82:85]
	v_mfma_f32_16x16x32_bf16 v[74:77], v[188:191], v[212:215], v[74:77]
	v_mfma_f32_16x16x32_bf16 v[70:73], v[178:181], v[220:223], v[70:73]
	v_mfma_f32_16x16x32_bf16 v[66:69], v[188:191], v[220:223], v[66:69]
	v_mfma_f32_16x16x32_bf16 v[114:117], v[184:187], v[200:203], v[114:117]
	v_mfma_f32_16x16x32_bf16 v[106:109], v[192:195], v[200:203], v[106:109]
	v_mfma_f32_16x16x32_bf16 v[98:101], v[184:187], v[208:211], v[98:101]
	v_mfma_f32_16x16x32_bf16 v[90:93], v[192:195], v[208:211], v[90:93]
	v_mfma_f32_16x16x32_bf16 v[82:85], v[184:187], v[216:219], v[82:85]
	v_mfma_f32_16x16x32_bf16 v[74:77], v[192:195], v[216:219], v[74:77]
	v_mfma_f32_16x16x32_bf16 v[70:73], v[184:187], v[224:227], v[70:73]
	v_mfma_f32_16x16x32_bf16 v[66:69], v[192:195], v[224:227], v[66:69]
	s_barrier
; #define PG8_STAGE(bufoff, gbase, voff) do { _Pragma("unroll") for (int _i = 0; _i < 2; ++_i) \
;         __builtin_amdgcn_global_load_lds((const unsigned*)((const char*)(gbase) + (voff)[_i]), (LAS unsigned*)(lds + (bufoff) + ldsw + _i * 8192), 16, 0, 0); } while (0)
; #define PG8_LDA(dst, b, h) do { _Pragma("unroll") for (int m = 0; m < 4; ++m) _Pragma("unroll") for (int k = 0; k < 2; ++k) dst[m][k] = *(const LAS bf16x8*)(lds + PG8_SA(b, h) + aoff + m * 2048 + k * 1024); } while (0)
; #define PG8_LDB(dst, b, h) do { _Pragma("unroll") for (int n = 0; n < 2; ++n) _Pragma("unroll") for (int k = 0; k < 2; ++k) dst[n][k] = *(const LAS bf16x8*)(lds + PG8_SB(b, h) + boff + n * 2048 + k * 1024); } while (0)
; #define PG8_BAR __builtin_amdgcn_s_barrier()
; template <class Epi, bool ALIGN_EPI = PG8_ALIGN, bool SP2 = PG8_SP2>
; __device__ __forceinline__ void gemm_phase(LAS uchar* lds, const Gemm g, const StaticOrder& S, const Epi& E) {
;     ...
;         for (int t = tb; t < tb + tblk; t += 2) {
;             const bool last = (t == nt - 2);
;             const char* a1 = cA + (size_t)(t + 1) * kstep;
;             const char* a2 = last ? nA : cA + (size_t)(t + 2) * kstep; const char* b2 = last ? nB : cB + (size_t)(t + 2) * kstep;
;             const char* a3 = a2 + kstep; const char* b3 = b2 + kstep;
;             if constexpr (SP2) {
;             PG8_LDB(B0, 0, 0); PG8_LDB(B1, 0, 1); PG8_SCHED; PG8_LDA(At, 0, 0); PG8_STAGE(PG8_SA(1, 1), a1 + hstepA, voffA);
;             PG8_WAIT_V(8); PG8_WAIT_L(0); PG8_BAR; PG8_MMA(0, 0, At, B0); PG8_MMA(0, 1, At, B1); PG8_BAR; PG8_SCHED;
;             PG8_LDA(At, 0, 1); PG8_STAGE(PG8_SB(0, 0), b2, voffB); PG8_STAGE(PG8_SB(0, 1), b2 + hstepB, voffB); PG8_STAGE(PG8_SA(0, 0), a2, voffA);
;             PG8_WAIT_V(8); PG8_WAIT_L(0); PG8_BAR; PG8_MMA(1, 0, At, B0); PG8_MMA(1, 1, At, B1); PG8_BAR; PG8_SCHED;
;             PG8_LDB(B0, 1, 0); PG8_LDB(B1, 1, 1); PG8_SCHED; PG8_LDA(At, 1, 0); PG8_STAGE(PG8_SA(0, 1), a2 + hstepA, voffA);
;             PG8_WAIT_V(8); PG8_WAIT_L(0); PG8_BAR; PG8_MMA(0, 0, At, B0); PG8_MMA(0, 1, At, B1); PG8_BAR; PG8_SCHED;
;             PG8_LDA(At, 1, 1); PG8_STAGE(PG8_SB(1, 0), b3, voffB); PG8_STAGE(PG8_SB(1, 1), b3 + hstepB, voffB); PG8_STAGE(PG8_SA(1, 0), a3, voffA);
;             PG8_WAIT_V(8); PG8_WAIT_L(0); PG8_BAR; PG8_MMA(1, 0, At, B0); PG8_MMA(1, 1, At, B1); PG8_BAR; PG8_SCHED;
	s_setprio 0
	s_add_i32 s12, s39, s22
	v_lshl_add_u64 v[228:229], v[228:229], 0, s[84:85]
	s_mov_b32 m0, s12
	ds_read_b128 v[196:199], v165 offset:49152
	ds_read_b128 v[200:203], v165 offset:50176
	ds_read_b128 v[204:207], v165 offset:51200
	ds_read_b128 v[208:211], v165 offset:52224
	ds_read_b128 v[212:215], v165 offset:53248
	ds_read_b128 v[216:219], v165 offset:54272
	ds_read_b128 v[220:223], v165 offset:55296
	ds_read_b128 v[224:227], v165 offset:56320
	global_load_lds_dwordx4 v[228:229], off
	s_add_i32 m0, s12, 0x2000
	s_add_u32 s12, s16, 0x44080
	v_lshl_add_u64 v[228:229], v[230:231], 0, s[84:85]
	s_addc_u32 s13, s17, 0
	s_add_i32 s16, s40, s22
	global_load_lds_dwordx4 v[228:229], off
	v_lshl_add_u64 v[228:229], s[12:13], 0, v[132:133]
	s_mov_b32 m0, s16
	s_nop 0
	global_load_lds_dwordx4 v[228:229], off
	v_lshl_add_u64 v[228:229], s[12:13], 0, v[152:153]
	s_add_i32 m0, s16, 0x2000
	s_nop 0
	global_load_lds_dwordx4 v[228:229], off
	v_lshl_add_u64 v[228:229], v[232:233], 0, s[84:85]
	s_mov_b32 m0, s27
	s_nop 0
	global_load_lds_dwordx4 v[228:229], off
	v_lshl_add_u64 v[228:229], v[234:235], 0, s[84:85]
	s_mov_b32 m0, s28
	s_nop 0
	global_load_lds_dwordx4 v[228:229], off
	s_waitcnt vmcnt(8)
	s_waitcnt lgkmcnt(0)
	s_setprio 1
	s_barrier
	v_mfma_f32_16x16x32_bf16 v[62:65], v[160:163], v[196:199], v[62:65]
	v_mfma_f32_16x16x32_bf16 v[58:61], v[170:173], v[196:199], v[58:61]
	v_mfma_f32_16x16x32_bf16 v[54:57], v[160:163], v[204:207], v[54:57]
	v_mfma_f32_16x16x32_bf16 v[46:49], v[170:173], v[204:207], v[46:49]
	v_mfma_f32_16x16x32_bf16 v[38:41], v[160:163], v[212:215], v[38:41]
	v_mfma_f32_16x16x32_bf16 v[30:33], v[170:173], v[212:215], v[30:33]
	v_mfma_f32_16x16x32_bf16 v[22:25], v[160:163], v[220:223], v[22:25]
	v_mfma_f32_16x16x32_bf16 v[14:17], v[170:173], v[220:223], v[14:17]
	v_mfma_f32_16x16x32_bf16 v[62:65], v[166:169], v[200:203], v[62:65]
	v_mfma_f32_16x16x32_bf16 v[58:61], v[174:177], v[200:203], v[58:61]
	v_mfma_f32_16x16x32_bf16 v[54:57], v[166:169], v[208:211], v[54:57]
	v_mfma_f32_16x16x32_bf16 v[46:49], v[174:177], v[208:211], v[46:49]
	v_mfma_f32_16x16x32_bf16 v[38:41], v[166:169], v[216:219], v[38:41]
	v_mfma_f32_16x16x32_bf16 v[30:33], v[174:177], v[216:219], v[30:33]
	v_mfma_f32_16x16x32_bf16 v[22:25], v[166:169], v[224:227], v[22:25]
	v_mfma_f32_16x16x32_bf16 v[14:17], v[174:177], v[224:227], v[14:17]
	v_mfma_f32_16x16x32_bf16 v[50:53], v[178:181], v[196:199], v[50:53]
	v_mfma_f32_16x16x32_bf16 v[42:45], v[188:191], v[196:199], v[42:45]
	v_mfma_f32_16x16x32_bf16 v[34:37], v[178:181], v[204:207], v[34:37]
	v_mfma_f32_16x16x32_bf16 v[26:29], v[188:191], v[204:207], v[26:29]
	v_mfma_f32_16x16x32_bf16 v[18:21], v[178:181], v[212:215], v[18:21]
	v_mfma_f32_16x16x32_bf16 v[10:13], v[188:191], v[212:215], v[10:13]
	v_mfma_f32_16x16x32_bf16 v[6:9], v[178:181], v[220:223], v[6:9]
	v_mfma_f32_16x16x32_bf16 v[2:5], v[188:191], v[220:223], v[2:5]
	v_mfma_f32_16x16x32_bf16 v[50:53], v[184:187], v[200:203], v[50:53]
	v_mfma_f32_16x16x32_bf16 v[42:45], v[192:195], v[200:203], v[42:45]
	v_mfma_f32_16x16x32_bf16 v[34:37], v[184:187], v[208:211], v[34:37]
	v_mfma_f32_16x16x32_bf16 v[26:29], v[192:195], v[208:211], v[26:29]
	v_mfma_f32_16x16x32_bf16 v[18:21], v[184:187], v[216:219], v[18:21]
	v_mfma_f32_16x16x32_bf16 v[10:13], v[192:195], v[216:219], v[10:13]
	v_mfma_f32_16x16x32_bf16 v[6:9], v[184:187], v[224:227], v[6:9]
	v_mfma_f32_16x16x32_bf16 v[2:5], v[192:195], v[224:227], v[2:5]
	s_barrier
	s_setprio 0
	s_add_i32 s38, s38, 2
	s_add_u32 s36, s36, 0x100
	s_addc_u32 s37, s37, 0
	s_cmp_gt_u32 s38, 13
	s_mov_b64 s[12:13], s[14:15]
.LBB0_837:
	s_add_u32 s14, s12, 0x100
	s_addc_u32 s15, s13, 0
	s_add_i32 s39, 0, 0x10000
	s_cmp_eq_u32 s38, 12
	s_cselect_b32 s19, s5, s15
	s_cselect_b32 s18, s4, s14
	s_cselect_b32 s17, s11, s37
	s_cselect_b32 s16, s10, s36
	s_add_i32 s40, 0, 0x14000
	v_add_u32_e32 v174, s39, v139
	v_add_u32_e32 v192, s40, v139
	ds_read_b128 v[160:163], v174
	ds_read_b128 v[166:169], v174 offset:1024
	ds_read_b128 v[170:173], v174 offset:2048
	ds_read_b128 v[174:177], v174 offset:3072
	ds_read_b128 v[178:181], v192
	ds_read_b128 v[184:187], v192 offset:1024
	ds_read_b128 v[188:191], v192 offset:2048
	ds_read_b128 v[192:195], v192 offset:3072
	v_lshl_add_u64 v[228:229], s[12:13], 0, v[156:157]
	s_add_i32 m0, s23, 0xc000
	ds_read_b128 v[196:199], v165
	ds_read_b128 v[200:203], v165 offset:1024
	ds_read_b128 v[204:207], v165 offset:2048
	ds_read_b128 v[208:211], v165 offset:3072
	ds_read_b128 v[212:215], v165 offset:4096
	ds_read_b128 v[216:219], v165 offset:5120
	ds_read_b128 v[220:223], v165 offset:6144
	ds_read_b128 v[224:227], v165 offset:7168
	global_load_lds_dwordx4 v[228:229], off
	v_lshl_add_u64 v[228:229], s[12:13], 0, v[158:159]
	s_add_i32 m0, s23, 0xe000
	s_nop 0
	global_load_lds_dwordx4 v[228:229], off
	s_waitcnt vmcnt(8)
	s_waitcnt lgkmcnt(0)
	s_setprio 1
	s_barrier
; #define PG8_STAGE(bufoff, gbase, voff) do { _Pragma("unroll") for (int _i = 0; _i < 2; ++_i) \
;         __builtin_amdgcn_global_load_lds((const unsigned*)((const char*)(gbase) + (voff)[_i]), (LAS unsigned*)(lds + (bufoff) + ldsw + _i * 8192), 16, 0, 0); } while (0)
; #define PG8_LDA(dst, b, h) do { _Pragma("unroll") for (int m = 0; m < 4; ++m) _Pragma("unroll") for (int k = 0; k < 2; ++k) dst[m][k] = *(const LAS bf16x8*)(lds + PG8_SA(b, h) + aoff + m * 2048 + k * 1024); } while (0)
; #define PG8_LDB(dst, b, h) do { _Pragma("unroll") for (int n = 0; n < 2; ++n) _Pragma("unroll") for (int k = 0; k < 2; ++k) dst[n][k] = *(const LAS bf16x8*)(lds + PG8_SB(b, h) + boff + n * 2048 + k * 1024); } while (0)
; #define PG8_MMA(ai, bj, At, Bt) do { __builtin_amdgcn_s_setprio(1); _Pragma("unroll") for (int m = 0; m < 4; ++m) _Pragma("unroll") for (int n = 0; n < 2; ++n) _Pragma("unroll") for (int k = 0; k < 2; ++k) \
;         acc[ai][bj][m][n] = __builtin_amdgcn_mfma_f32_16x16x32_bf16(Bt[n][k], At[m][k], acc[ai][bj][m][n], 0, 0, 0); __builtin_amdgcn_s_setprio(0); } while (0)
; #define PG8_WAIT_V(n) asm volatile("s_waitcnt vmcnt(" #n ")" ::: "memory")
; #define PG8_WAIT_L(n) asm volatile("s_waitcnt lgkmcnt(" #n ")" ::: "memory")
; #define PG8_BAR __builtin_amdgcn_s_barrier()
; #define PG8_SCHED __builtin_amdgcn_sched_barrier(0)
; template <class Epi, bool ALIGN_EPI = PG8_ALIGN, bool SP2 = PG8_SP2>
; __device__ __forceinline__ void gemm_phase(LAS uchar* lds, const Gemm g, const StaticOrder& S, const Epi& E) {
;     ...
;             PG8_LDB(B0, 0, 0); PG8_LDB(B1, 0, 1); PG8_SCHED; PG8_LDA(At, 0, 0); PG8_STAGE(PG8_SA(1, 1), a1 + hstepA, voffA);
;             PG8_WAIT_V(8); PG8_WAIT_L(0); PG8_BAR; PG8_MMA(0, 0, At, B0); PG8_MMA(0, 1, At, B1); PG8_BAR; PG8_SCHED;
;             PG8_LDA(At, 0, 1); PG8_STAGE(PG8_SB(0, 0), b2, voffB); PG8_STAGE(PG8_SB(0, 1), b2 + hstepB, voffB); PG8_STAGE(PG8_SA(0, 0), a2, voffA);
;             PG8_WAIT_V(8); PG8_WAIT_L(0); PG8_BAR; PG8_MMA(1, 0, At, B0); PG8_MMA(1, 1, At, B1); PG8_BAR; PG8_SCHED;
	v_mfma_f32_16x16x32_bf16 v[126:129], v[160:163], v[196:199], v[126:129]
	v_mfma_f32_16x16x32_bf16 v[122:125], v[170:173], v[196:199], v[122:125]
	v_mfma_f32_16x16x32_bf16 v[118:121], v[160:163], v[204:207], v[118:121]
	v_mfma_f32_16x16x32_bf16 v[110:113], v[170:173], v[204:207], v[110:113]
	v_mfma_f32_16x16x32_bf16 v[102:105], v[160:163], v[212:215], v[102:105]
	v_mfma_f32_16x16x32_bf16 v[94:97], v[170:173], v[212:215], v[94:97]
	v_mfma_f32_16x16x32_bf16 v[86:89], v[160:163], v[220:223], v[86:89]
	v_mfma_f32_16x16x32_bf16 v[78:81], v[170:173], v[220:223], v[78:81]
	v_mfma_f32_16x16x32_bf16 v[126:129], v[166:169], v[200:203], v[126:129]
	v_mfma_f32_16x16x32_bf16 v[122:125], v[174:177], v[200:203], v[122:125]
	v_mfma_f32_16x16x32_bf16 v[118:121], v[166:169], v[208:211], v[118:121]
	v_mfma_f32_16x16x32_bf16 v[110:113], v[174:177], v[208:211], v[110:113]
	v_mfma_f32_16x16x32_bf16 v[102:105], v[166:169], v[216:219], v[102:105]
	v_mfma_f32_16x16x32_bf16 v[94:97], v[174:177], v[216:219], v[94:97]
	v_mfma_f32_16x16x32_bf16 v[86:89], v[166:169], v[224:227], v[86:89]
	v_mfma_f32_16x16x32_bf16 v[78:81], v[174:177], v[224:227], v[78:81]
	v_mfma_f32_16x16x32_bf16 v[114:117], v[178:181], v[196:199], v[114:117]
	v_mfma_f32_16x16x32_bf16 v[106:109], v[188:191], v[196:199], v[106:109]
	v_mfma_f32_16x16x32_bf16 v[98:101], v[178:181], v[204:207], v[98:101]
	v_mfma_f32_16x16x32_bf16 v[90:93], v[188:191], v[204:207], v[90:93]
	v_mfma_f32_16x16x32_bf16 v[82:85], v[178:181], v[212:215], v[82:85]
	v_mfma_f32_16x16x32_bf16 v[74:77], v[188:191], v[212:215], v[74:77]
	v_mfma_f32_16x16x32_bf16 v[70:73], v[178:181], v[220:223], v[70:73]
	v_mfma_f32_16x16x32_bf16 v[66:69], v[188:191], v[220:223], v[66:69]
	v_mfma_f32_16x16x32_bf16 v[114:117], v[184:187], v[200:203], v[114:117]
	v_mfma_f32_16x16x32_bf16 v[106:109], v[192:195], v[200:203], v[106:109]
	v_mfma_f32_16x16x32_bf16 v[98:101], v[184:187], v[208:211], v[98:101]
	v_mfma_f32_16x16x32_bf16 v[90:93], v[192:195], v[208:211], v[90:93]
	v_mfma_f32_16x16x32_bf16 v[82:85], v[184:187], v[216:219], v[82:85]
	v_mfma_f32_16x16x32_bf16 v[74:77], v[192:195], v[216:219], v[74:77]
	v_mfma_f32_16x16x32_bf16 v[70:73], v[184:187], v[224:227], v[70:73]
	v_mfma_f32_16x16x32_bf16 v[66:69], v[192:195], v[224:227], v[66:69]
	s_barrier
	s_setprio 0
	s_add_i32 s12, s39, s22
	v_lshl_add_u64 v[228:229], s[16:17], 0, v[132:133]
	s_mov_b32 m0, s12
	ds_read_b128 v[196:199], v165 offset:16384
	ds_read_b128 v[200:203], v165 offset:17408
	ds_read_b128 v[204:207], v165 offset:18432
	ds_read_b128 v[208:211], v165 offset:19456
	ds_read_b128 v[212:215], v165 offset:20480
	ds_read_b128 v[216:219], v165 offset:21504
	ds_read_b128 v[220:223], v165 offset:22528
	ds_read_b128 v[224:227], v165 offset:23552
	global_load_lds_dwordx4 v[228:229], off
	s_add_i32 m0, s12, 0x2000
	s_add_u32 s12, s16, 0x44000
	v_lshl_add_u64 v[230:231], s[16:17], 0, v[152:153]
	s_addc_u32 s13, s17, 0
	s_add_i32 s39, s40, s22
	global_load_lds_dwordx4 v[230:231], off
	v_lshl_add_u64 v[232:233], s[12:13], 0, v[132:133]
	s_mov_b32 m0, s39
	v_lshl_add_u64 v[234:235], s[18:19], 0, v[134:135]
	global_load_lds_dwordx4 v[232:233], off
	v_lshl_add_u64 v[232:233], s[12:13], 0, v[152:153]
	s_add_i32 m0, s39, 0x2000
	s_nop 0
	global_load_lds_dwordx4 v[232:233], off
	v_lshl_add_u64 v[232:233], s[18:19], 0, v[130:131]
	s_mov_b32 m0, s23
	s_nop 0
	global_load_lds_dwordx4 v[232:233], off
	s_mov_b32 m0, s24
	s_nop 0
	global_load_lds_dwordx4 v[234:235], off
	s_waitcnt vmcnt(8)
	s_waitcnt lgkmcnt(0)
	s_setprio 1
	s_barrier
	v_mfma_f32_16x16x32_bf16 v[62:65], v[160:163], v[196:199], v[62:65]
	v_mfma_f32_16x16x32_bf16 v[58:61], v[170:173], v[196:199], v[58:61]
	v_mfma_f32_16x16x32_bf16 v[54:57], v[160:163], v[204:207], v[54:57]
	v_mfma_f32_16x16x32_bf16 v[46:49], v[170:173], v[204:207], v[46:49]
	v_mfma_f32_16x16x32_bf16 v[38:41], v[160:163], v[212:215], v[38:41]
	v_mfma_f32_16x16x32_bf16 v[30:33], v[170:173], v[212:215], v[30:33]
	v_mfma_f32_16x16x32_bf16 v[22:25], v[160:163], v[220:223], v[22:25]
	v_mfma_f32_16x16x32_bf16 v[14:17], v[170:173], v[220:223], v[14:17]
	v_mfma_f32_16x16x32_bf16 v[62:65], v[166:169], v[200:203], v[62:65]
	v_mfma_f32_16x16x32_bf16 v[58:61], v[174:177], v[200:203], v[58:61]
	v_mfma_f32_16x16x32_bf16 v[54:57], v[166:169], v[208:211], v[54:57]
	v_mfma_f32_16x16x32_bf16 v[46:49], v[174:177], v[208:211], v[46:49]
	v_mfma_f32_16x16x32_bf16 v[38:41], v[166:169], v[216:219], v[38:41]
	v_mfma_f32_16x16x32_bf16 v[30:33], v[174:177], v[216:219], v[30:33]
	v_mfma_f32_16x16x32_bf16 v[22:25], v[166:169], v[224:227], v[22:25]
	v_mfma_f32_16x16x32_bf16 v[14:17], v[174:177], v[224:227], v[14:17]
	v_mfma_f32_16x16x32_bf16 v[50:53], v[178:181], v[196:199], v[50:53]
	v_mfma_f32_16x16x32_bf16 v[42:45], v[188:191], v[196:199], v[42:45]
	v_mfma_f32_16x16x32_bf16 v[34:37], v[178:181], v[204:207], v[34:37]
	v_mfma_f32_16x16x32_bf16 v[26:29], v[188:191], v[204:207], v[26:29]
	v_mfma_f32_16x16x32_bf16 v[18:21], v[178:181], v[212:215], v[18:21]
	v_mfma_f32_16x16x32_bf16 v[10:13], v[188:191], v[212:215], v[10:13]
	v_mfma_f32_16x16x32_bf16 v[6:9], v[178:181], v[220:223], v[6:9]
	v_mfma_f32_16x16x32_bf16 v[2:5], v[188:191], v[220:223], v[2:5]
	v_mfma_f32_16x16x32_bf16 v[50:53], v[184:187], v[200:203], v[50:53]
	v_mfma_f32_16x16x32_bf16 v[42:45], v[192:195], v[200:203], v[42:45]
	v_mfma_f32_16x16x32_bf16 v[34:37], v[184:187], v[208:211], v[34:37]
	v_mfma_f32_16x16x32_bf16 v[26:29], v[192:195], v[208:211], v[26:29]
	v_mfma_f32_16x16x32_bf16 v[18:21], v[184:187], v[216:219], v[18:21]
	v_mfma_f32_16x16x32_bf16 v[10:13], v[192:195], v[216:219], v[10:13]
	v_mfma_f32_16x16x32_bf16 v[6:9], v[184:187], v[224:227], v[6:9]
	v_mfma_f32_16x16x32_bf16 v[2:5], v[192:195], v[224:227], v[2:5]
	s_barrier
; #define PG8_STAGE(bufoff, gbase, voff) do { _Pragma("unroll") for (int _i = 0; _i < 2; ++_i) \
;         __builtin_amdgcn_global_load_lds((const unsigned*)((const char*)(gbase) + (voff)[_i]), (LAS unsigned*)(lds + (bufoff) + ldsw + _i * 8192), 16, 0, 0); } while (0)
; #define PG8_LDA(dst, b, h) do { _Pragma("unroll") for (int m = 0; m < 4; ++m) _Pragma("unroll") for (int k = 0; k < 2; ++k) dst[m][k] = *(const LAS bf16x8*)(lds + PG8_SA(b, h) + aoff + m * 2048 + k * 1024); } while (0)
; #define PG8_LDB(dst, b, h) do { _Pragma("unroll") for (int n = 0; n < 2; ++n) _Pragma("unroll") for (int k = 0; k < 2; ++k) dst[n][k] = *(const LAS bf16x8*)(lds + PG8_SB(b, h) + boff + n * 2048 + k * 1024); } while (0)
; #define PG8_MMA(ai, bj, At, Bt) do { __builtin_amdgcn_s_setprio(1); _Pragma("unroll") for (int m = 0; m < 4; ++m) _Pragma("unroll") for (int n = 0; n < 2; ++n) _Pragma("unroll") for (int k = 0; k < 2; ++k) \
;         acc[ai][bj][m][n] = __builtin_amdgcn_mfma_f32_16x16x32_bf16(Bt[n][k], At[m][k], acc[ai][bj][m][n], 0, 0, 0); __builtin_amdgcn_s_setprio(0); } while (0)
; #define PG8_WAIT_V(n) asm volatile("s_waitcnt vmcnt(" #n ")" ::: "memory")
; #define PG8_WAIT_L(n) asm volatile("s_waitcnt lgkmcnt(" #n ")" ::: "memory")
; #define PG8_BAR __builtin_amdgcn_s_barrier()
; #define PG8_SCHED __builtin_amdgcn_sched_barrier(0)
; template <class Epi, bool ALIGN_EPI = PG8_ALIGN, bool SP2 = PG8_SP2>
; __device__ __forceinline__ void gemm_phase(LAS uchar* lds, const Gemm g, const StaticOrder& S, const Epi& E) {
;     ...
;             PG8_LDB(B0, 1, 0); PG8_LDB(B1, 1, 1); PG8_SCHED; PG8_LDA(At, 1, 0); PG8_STAGE(PG8_SA(0, 1), a2 + hstepA, voffA);
;             PG8_WAIT_V(8); PG8_WAIT_L(0); PG8_BAR; PG8_MMA(0, 0, At, B0); PG8_MMA(0, 1, At, B1); PG8_BAR; PG8_SCHED;
	s_setprio 0
	s_add_i32 s39, 0, 0x18000
	s_add_i32 s40, 0, 0x1c000
	v_add_u32_e32 v174, s39, v139
	v_add_u32_e32 v192, s40, v139
	ds_read_b128 v[160:163], v174
	ds_read_b128 v[166:169], v174 offset:1024
	ds_read_b128 v[170:173], v174 offset:2048
	ds_read_b128 v[174:177], v174 offset:3072
	ds_read_b128 v[178:181], v192
	ds_read_b128 v[184:187], v192 offset:1024
	ds_read_b128 v[188:191], v192 offset:2048
	ds_read_b128 v[192:195], v192 offset:3072
	s_add_u32 s12, s18, 0x44000
	s_addc_u32 s13, s19, 0
	s_mov_b32 m0, s25
	v_lshl_add_u64 v[236:237], s[12:13], 0, v[130:131]
	ds_read_b128 v[196:199], v165 offset:32768
	ds_read_b128 v[200:203], v165 offset:33792
	ds_read_b128 v[204:207], v165 offset:34816
	ds_read_b128 v[208:211], v165 offset:35840
	ds_read_b128 v[212:215], v165 offset:36864
	ds_read_b128 v[216:219], v165 offset:37888
	ds_read_b128 v[220:223], v165 offset:38912
	ds_read_b128 v[224:227], v165 offset:39936
	global_load_lds_dwordx4 v[236:237], off
	v_lshl_add_u64 v[236:237], s[12:13], 0, v[134:135]
	s_mov_b32 m0, s26
	s_nop 0
	global_load_lds_dwordx4 v[236:237], off
	s_waitcnt vmcnt(8)
	s_waitcnt lgkmcnt(0)
	s_setprio 1
	s_barrier
	v_mfma_f32_16x16x32_bf16 v[126:129], v[160:163], v[196:199], v[126:129]
	v_mfma_f32_16x16x32_bf16 v[122:125], v[170:173], v[196:199], v[122:125]
	v_mfma_f32_16x16x32_bf16 v[118:121], v[160:163], v[204:207], v[118:121]
	v_mfma_f32_16x16x32_bf16 v[110:113], v[170:173], v[204:207], v[110:113]
	v_mfma_f32_16x16x32_bf16 v[102:105], v[160:163], v[212:215], v[102:105]
	v_mfma_f32_16x16x32_bf16 v[94:97], v[170:173], v[212:215], v[94:97]
	v_mfma_f32_16x16x32_bf16 v[86:89], v[160:163], v[220:223], v[86:89]
	v_mfma_f32_16x16x32_bf16 v[78:81], v[170:173], v[220:223], v[78:81]
	v_mfma_f32_16x16x32_bf16 v[126:129], v[166:169], v[200:203], v[126:129]
	v_mfma_f32_16x16x32_bf16 v[122:125], v[174:177], v[200:203], v[122:125]
	v_mfma_f32_16x16x32_bf16 v[118:121], v[166:169], v[208:211], v[118:121]
	v_mfma_f32_16x16x32_bf16 v[110:113], v[174:177], v[208:211], v[110:113]
	v_mfma_f32_16x16x32_bf16 v[102:105], v[166:169], v[216:219], v[102:105]
	v_mfma_f32_16x16x32_bf16 v[94:97], v[174:177], v[216:219], v[94:97]
	v_mfma_f32_16x16x32_bf16 v[86:89], v[166:169], v[224:227], v[86:89]
	v_mfma_f32_16x16x32_bf16 v[78:81], v[174:177], v[224:227], v[78:81]
	v_mfma_f32_16x16x32_bf16 v[114:117], v[178:181], v[196:199], v[114:117]
	v_mfma_f32_16x16x32_bf16 v[106:109], v[188:191], v[196:199], v[106:109]
	v_mfma_f32_16x16x32_bf16 v[98:101], v[178:181], v[204:207], v[98:101]
	v_mfma_f32_16x16x32_bf16 v[90:93], v[188:191], v[204:207], v[90:93]
	v_mfma_f32_16x16x32_bf16 v[82:85], v[178:181], v[212:215], v[82:85]
	v_mfma_f32_16x16x32_bf16 v[74:77], v[188:191], v[212:215], v[74:77]
	v_mfma_f32_16x16x32_bf16 v[70:73], v[178:181], v[220:223], v[70:73]
	v_mfma_f32_16x16x32_bf16 v[66:69], v[188:191], v[220:223], v[66:69]
	v_mfma_f32_16x16x32_bf16 v[114:117], v[184:187], v[200:203], v[114:117]
	v_mfma_f32_16x16x32_bf16 v[106:109], v[192:195], v[200:203], v[106:109]
	v_mfma_f32_16x16x32_bf16 v[98:101], v[184:187], v[208:211], v[98:101]
	v_mfma_f32_16x16x32_bf16 v[90:93], v[192:195], v[208:211], v[90:93]
	v_mfma_f32_16x16x32_bf16 v[82:85], v[184:187], v[216:219], v[82:85]
	v_mfma_f32_16x16x32_bf16 v[74:77], v[192:195], v[216:219], v[74:77]
	v_mfma_f32_16x16x32_bf16 v[70:73], v[184:187], v[224:227], v[70:73]
	v_mfma_f32_16x16x32_bf16 v[66:69], v[192:195], v[224:227], v[66:69]
	s_barrier
; #define PG8_STAGE(bufoff, gbase, voff) do { _Pragma("unroll") for (int _i = 0; _i < 2; ++_i) \
;         __builtin_amdgcn_global_load_lds((const unsigned*)((const char*)(gbase) + (voff)[_i]), (LAS unsigned*)(lds + (bufoff) + ldsw + _i * 8192), 16, 0, 0); } while (0)
; #define PG8_LDA(dst, b, h) do { _Pragma("unroll") for (int m = 0; m < 4; ++m) _Pragma("unroll") for (int k = 0; k < 2; ++k) dst[m][k] = *(const LAS bf16x8*)(lds + PG8_SA(b, h) + aoff + m * 2048 + k * 1024); } while (0)
; #define PG8_MMA(ai, bj, At, Bt) do { __builtin_amdgcn_s_setprio(1); _Pragma("unroll") for (int m = 0; m < 4; ++m) _Pragma("unroll") for (int n = 0; n < 2; ++n) _Pragma("unroll") for (int k = 0; k < 2; ++k) \
;         acc[ai][bj][m][n] = __builtin_amdgcn_mfma_f32_16x16x32_bf16(Bt[n][k], At[m][k], acc[ai][bj][m][n], 0, 0, 0); __builtin_amdgcn_s_setprio(0); } while (0)
; #define PG8_WAIT_V(n) asm volatile("s_waitcnt vmcnt(" #n ")" ::: "memory")
; #define PG8_WAIT_L(n) asm volatile("s_waitcnt lgkmcnt(" #n ")" ::: "memory")
; #define PG8_BAR __builtin_amdgcn_s_barrier()
; #define PG8_SCHED __builtin_amdgcn_sched_barrier(0)
; template <class Epi, bool ALIGN_EPI = PG8_ALIGN, bool SP2 = PG8_SP2>
; __device__ __forceinline__ void gemm_phase(LAS uchar* lds, const Gemm g, const StaticOrder& S, const Epi& E) {
;     ...
;             PG8_LDA(At, 1, 1); PG8_STAGE(PG8_SB(1, 0), b3, voffB); PG8_STAGE(PG8_SB(1, 1), b3 + hstepB, voffB); PG8_STAGE(PG8_SA(1, 0), a3, voffA);
;             PG8_WAIT_V(8); PG8_WAIT_L(0); PG8_BAR; PG8_MMA(1, 0, At, B0); PG8_MMA(1, 1, At, B1); PG8_BAR; PG8_SCHED;
	s_setprio 0
	s_add_i32 s12, s39, s22
	v_lshl_add_u64 v[228:229], v[228:229], 0, s[84:85]
	s_mov_b32 m0, s12
	ds_read_b128 v[196:199], v165 offset:49152
	ds_read_b128 v[200:203], v165 offset:50176
	ds_read_b128 v[204:207], v165 offset:51200
	ds_read_b128 v[208:211], v165 offset:52224
	ds_read_b128 v[212:215], v165 offset:53248
	ds_read_b128 v[216:219], v165 offset:54272
	ds_read_b128 v[220:223], v165 offset:55296
	ds_read_b128 v[224:227], v165 offset:56320
	global_load_lds_dwordx4 v[228:229], off
	s_add_i32 m0, s12, 0x2000
	s_add_u32 s12, s16, 0x44080
	v_lshl_add_u64 v[228:229], v[230:231], 0, s[84:85]
	s_addc_u32 s13, s17, 0
	s_add_i32 s16, s40, s22
	global_load_lds_dwordx4 v[228:229], off
	v_lshl_add_u64 v[228:229], s[12:13], 0, v[132:133]
	s_mov_b32 m0, s16
	s_nop 0
	global_load_lds_dwordx4 v[228:229], off
	v_lshl_add_u64 v[228:229], s[12:13], 0, v[152:153]
	s_add_i32 m0, s16, 0x2000
	s_nop 0
	global_load_lds_dwordx4 v[228:229], off
	v_lshl_add_u64 v[228:229], v[232:233], 0, s[84:85]
	s_mov_b32 m0, s27
	s_nop 0
	global_load_lds_dwordx4 v[228:229], off
	v_lshl_add_u64 v[228:229], v[234:235], 0, s[84:85]
	s_mov_b32 m0, s28
	s_nop 0
	global_load_lds_dwordx4 v[228:229], off
	s_waitcnt vmcnt(8)
	s_waitcnt lgkmcnt(0)
	s_setprio 1
	s_barrier
	v_mfma_f32_16x16x32_bf16 v[62:65], v[160:163], v[196:199], v[62:65]
	v_mfma_f32_16x16x32_bf16 v[58:61], v[170:173], v[196:199], v[58:61]
	v_mfma_f32_16x16x32_bf16 v[54:57], v[160:163], v[204:207], v[54:57]
	v_mfma_f32_16x16x32_bf16 v[46:49], v[170:173], v[204:207], v[46:49]
	v_mfma_f32_16x16x32_bf16 v[38:41], v[160:163], v[212:215], v[38:41]
	v_mfma_f32_16x16x32_bf16 v[30:33], v[170:173], v[212:215], v[30:33]
	v_mfma_f32_16x16x32_bf16 v[22:25], v[160:163], v[220:223], v[22:25]
	v_mfma_f32_16x16x32_bf16 v[14:17], v[170:173], v[220:223], v[14:17]
	v_mfma_f32_16x16x32_bf16 v[62:65], v[166:169], v[200:203], v[62:65]
	v_mfma_f32_16x16x32_bf16 v[58:61], v[174:177], v[200:203], v[58:61]
	v_mfma_f32_16x16x32_bf16 v[54:57], v[166:169], v[208:211], v[54:57]
	v_mfma_f32_16x16x32_bf16 v[46:49], v[174:177], v[208:211], v[46:49]
	v_mfma_f32_16x16x32_bf16 v[38:41], v[166:169], v[216:219], v[38:41]
	v_mfma_f32_16x16x32_bf16 v[30:33], v[174:177], v[216:219], v[30:33]
	v_mfma_f32_16x16x32_bf16 v[22:25], v[166:169], v[224:227], v[22:25]
	v_mfma_f32_16x16x32_bf16 v[14:17], v[174:177], v[224:227], v[14:17]
	v_mfma_f32_16x16x32_bf16 v[50:53], v[178:181], v[196:199], v[50:53]
	v_mfma_f32_16x16x32_bf16 v[42:45], v[188:191], v[196:199], v[42:45]
	v_mfma_f32_16x16x32_bf16 v[34:37], v[178:181], v[204:207], v[34:37]
	v_mfma_f32_16x16x32_bf16 v[26:29], v[188:191], v[204:207], v[26:29]
	v_mfma_f32_16x16x32_bf16 v[18:21], v[178:181], v[212:215], v[18:21]
	v_mfma_f32_16x16x32_bf16 v[10:13], v[188:191], v[212:215], v[10:13]
	v_mfma_f32_16x16x32_bf16 v[6:9], v[178:181], v[220:223], v[6:9]
	v_mfma_f32_16x16x32_bf16 v[2:5], v[188:191], v[220:223], v[2:5]
	v_mfma_f32_16x16x32_bf16 v[50:53], v[184:187], v[200:203], v[50:53]
	v_mfma_f32_16x16x32_bf16 v[42:45], v[192:195], v[200:203], v[42:45]
	v_mfma_f32_16x16x32_bf16 v[34:37], v[184:187], v[208:211], v[34:37]
	v_mfma_f32_16x16x32_bf16 v[26:29], v[192:195], v[208:211], v[26:29]
	v_mfma_f32_16x16x32_bf16 v[18:21], v[184:187], v[216:219], v[18:21]
	v_mfma_f32_16x16x32_bf16 v[10:13], v[192:195], v[216:219], v[10:13]
	v_mfma_f32_16x16x32_bf16 v[6:9], v[184:187], v[224:227], v[6:9]
	v_mfma_f32_16x16x32_bf16 v[2:5], v[192:195], v[224:227], v[2:5]
	s_barrier
	s_setprio 0
	s_add_i32 s38, s38, 2
	s_add_u32 s36, s36, 0x100
	s_addc_u32 s37, s37, 0
	s_cmp_gt_u32 s38, 13
	s_mov_b64 s[12:13], s[14:15]
	s_cbranch_scc0 .LBB0_837
	s_and_b64 vcc, exec, s[8:9]
	s_cbranch_vccz .LBB0_840
	s_barrier

; #define PG8_STAGE(bufoff, gbase, voff) do { _Pragma("unroll") for (int _i = 0; _i < 2; ++_i) \
;         __builtin_amdgcn_global_load_lds((const unsigned*)((const char*)(gbase) + (voff)[_i]), (LAS unsigned*)(lds + (bufoff) + ldsw + _i * 8192), 16, 0, 0); } while (0)
; #define PG8_LDA(dst, b, h) do { _Pragma("unroll") for (int m = 0; m < 4; ++m) _Pragma("unroll") for (int k = 0; k < 2; ++k) dst[m][k] = *(const LAS bf16x8*)(lds + PG8_SA(b, h) + aoff + m * 2048 + k * 1024); } while (0)
; #define PG8_MMA(ai, bj, At, Bt) do { __builtin_amdgcn_s_setprio(1); _Pragma("unroll") for (int m = 0; m < 4; ++m) _Pragma("unroll") for (int n = 0; n < 2; ++n) _Pragma("unroll") for (int k = 0; k < 2; ++k) \
;         acc[ai][bj][m][n] = __builtin_amdgcn_mfma_f32_16x16x32_bf16(Bt[n][k], At[m][k], acc[ai][bj][m][n], 0, 0, 0); __builtin_amdgcn_s_setprio(0); } while (0)
; #define PG8_WAIT_V(n) asm volatile("s_waitcnt vmcnt(" #n ")" ::: "memory")
; #define PG8_WAIT_L(n) asm volatile("s_waitcnt lgkmcnt(" #n ")" ::: "memory")
; #define PG8_BAR __builtin_amdgcn_s_barrier()
; #define PG8_SCHED __builtin_amdgcn_sched_barrier(0)
; template <class Epi, bool ALIGN_EPI = PG8_ALIGN, bool SP2 = PG8_SP2>
; __device__ __forceinline__ void gemm_phase(LAS uchar* lds, const Gemm g, const StaticOrder& S, const Epi& E) {
;     ...
;             PG8_WAIT_V(8); PG8_WAIT_L(0); PG8_BAR; PG8_MMA(0, 0, At, B0); PG8_MMA(0, 1, At, B1); PG8_BAR; PG8_SCHED;
;             PG8_LDA(At, 0, 1); PG8_STAGE(PG8_SB(0, 0), b2, voffB); PG8_STAGE(PG8_SB(0, 1), b2 + hstepB, voffB); PG8_STAGE(PG8_SA(0, 0), a2, voffA);
;             PG8_WAIT_V(8); PG8_WAIT_L(0); PG8_BAR; PG8_MMA(1, 0, At, B0); PG8_MMA(1, 1, At, B1); PG8_BAR; PG8_SCHED;
.Lrw_done_1050_0_pl:
	s_waitcnt lgkmcnt(0)
	s_setprio 1
	s_barrier
	v_mfma_f32_16x16x32_bf16 v[126:129], v[164:167], v[200:203], 0
	v_mfma_f32_16x16x32_bf16 v[118:121], v[172:175], v[200:203], 0
	v_mfma_f32_16x16x32_bf16 v[110:113], v[164:167], v[208:211], 0
	v_mfma_f32_16x16x32_bf16 v[102:105], v[172:175], v[208:211], 0
	v_mfma_f32_16x16x32_bf16 v[94:97], v[164:167], v[216:219], 0
	v_mfma_f32_16x16x32_bf16 v[86:89], v[172:175], v[216:219], 0
	v_mfma_f32_16x16x32_bf16 v[78:81], v[164:167], v[224:227], 0
	v_mfma_f32_16x16x32_bf16 v[70:73], v[172:175], v[224:227], 0
	v_mfma_f32_16x16x32_bf16 v[126:129], v[168:171], v[204:207], v[126:129]
	v_mfma_f32_16x16x32_bf16 v[118:121], v[176:179], v[204:207], v[118:121]
	v_mfma_f32_16x16x32_bf16 v[110:113], v[168:171], v[212:215], v[110:113]
	v_mfma_f32_16x16x32_bf16 v[102:105], v[176:179], v[212:215], v[102:105]
	v_mfma_f32_16x16x32_bf16 v[94:97], v[168:171], v[220:223], v[94:97]
	v_mfma_f32_16x16x32_bf16 v[86:89], v[176:179], v[220:223], v[86:89]
	v_mfma_f32_16x16x32_bf16 v[78:81], v[168:171], v[228:231], v[78:81]
	v_mfma_f32_16x16x32_bf16 v[70:73], v[176:179], v[228:231], v[70:73]
	v_mfma_f32_16x16x32_bf16 v[122:125], v[184:187], v[200:203], 0
	v_mfma_f32_16x16x32_bf16 v[114:117], v[192:195], v[200:203], 0
	v_mfma_f32_16x16x32_bf16 v[106:109], v[184:187], v[208:211], 0
	v_mfma_f32_16x16x32_bf16 v[98:101], v[192:195], v[208:211], 0
	v_mfma_f32_16x16x32_bf16 v[90:93], v[184:187], v[216:219], 0
	v_mfma_f32_16x16x32_bf16 v[82:85], v[192:195], v[216:219], 0
	v_mfma_f32_16x16x32_bf16 v[74:77], v[184:187], v[224:227], 0
	v_mfma_f32_16x16x32_bf16 v[66:69], v[192:195], v[224:227], 0
	v_mfma_f32_16x16x32_bf16 v[122:125], v[188:191], v[204:207], v[122:125]
	v_mfma_f32_16x16x32_bf16 v[114:117], v[196:199], v[204:207], v[114:117]
	v_mfma_f32_16x16x32_bf16 v[106:109], v[188:191], v[212:215], v[106:109]
	v_mfma_f32_16x16x32_bf16 v[98:101], v[196:199], v[212:215], v[98:101]
	v_mfma_f32_16x16x32_bf16 v[90:93], v[188:191], v[220:223], v[90:93]
	v_mfma_f32_16x16x32_bf16 v[82:85], v[196:199], v[220:223], v[82:85]
	v_mfma_f32_16x16x32_bf16 v[74:77], v[188:191], v[228:231], v[74:77]
	v_mfma_f32_16x16x32_bf16 v[66:69], v[196:199], v[228:231], v[66:69]
	s_barrier
	s_setprio 0
	s_add_i32 s12, s39, s21
	v_lshl_add_u64 v[160:161], s[16:17], 0, v[134:135]
	s_mov_b32 m0, s12
	ds_read_b128 v[200:203], v163 offset:16384
	ds_read_b128 v[204:207], v163 offset:17408
	ds_read_b128 v[208:211], v163 offset:18432
	ds_read_b128 v[212:215], v163 offset:19456
	ds_read_b128 v[216:219], v163 offset:20480
	ds_read_b128 v[220:223], v163 offset:21504
	ds_read_b128 v[224:227], v163 offset:22528
	ds_read_b128 v[228:231], v163 offset:23552
	global_load_lds_dwordx4 v[160:161], off
	s_add_i32 m0, s12, 0x2000
	s_add_u32 s12, s16, 0x44000
	v_lshl_add_u64 v[180:181], s[16:17], 0, v[130:131]
	s_addc_u32 s13, s17, 0
	s_add_i32 s39, s40, s21
	global_load_lds_dwordx4 v[180:181], off
	v_lshl_add_u64 v[232:233], s[12:13], 0, v[134:135]
	s_mov_b32 m0, s39
	v_lshl_add_u64 v[234:235], s[18:19], 0, v[132:133]
	global_load_lds_dwordx4 v[232:233], off
	v_lshl_add_u64 v[232:233], s[12:13], 0, v[130:131]
	s_add_i32 m0, s39, 0x2000
	s_nop 0
	global_load_lds_dwordx4 v[232:233], off
	v_lshl_add_u64 v[232:233], s[18:19], 0, v[154:155]
	s_mov_b32 m0, s23
	s_nop 0
	global_load_lds_dwordx4 v[232:233], off
	s_mov_b32 m0, s24
	s_nop 0
	global_load_lds_dwordx4 v[234:235], off
	s_cmp_lt_u32 s29, 2
	s_cbranch_scc1 .Lrw_std_1050_1_pl
	s_waitcnt vmcnt(16)
	s_branch .Lrw_done_1050_1_pl

; #define PG8_STAGE(bufoff, gbase, voff) do { _Pragma("unroll") for (int _i = 0; _i < 2; ++_i) \
;         __builtin_amdgcn_global_load_lds((const unsigned*)((const char*)(gbase) + (voff)[_i]), (LAS unsigned*)(lds + (bufoff) + ldsw + _i * 8192), 16, 0, 0); } while (0)
; #define PG8_LDA(dst, b, h) do { _Pragma("unroll") for (int m = 0; m < 4; ++m) _Pragma("unroll") for (int k = 0; k < 2; ++k) dst[m][k] = *(const LAS bf16x8*)(lds + PG8_SA(b, h) + aoff + m * 2048 + k * 1024); } while (0)
; #define PG8_LDB(dst, b, h) do { _Pragma("unroll") for (int n = 0; n < 2; ++n) _Pragma("unroll") for (int k = 0; k < 2; ++k) dst[n][k] = *(const LAS bf16x8*)(lds + PG8_SB(b, h) + boff + n * 2048 + k * 1024); } while (0)
; #define PG8_MMA(ai, bj, At, Bt) do { __builtin_amdgcn_s_setprio(1); _Pragma("unroll") for (int m = 0; m < 4; ++m) _Pragma("unroll") for (int n = 0; n < 2; ++n) _Pragma("unroll") for (int k = 0; k < 2; ++k) \
;         acc[ai][bj][m][n] = __builtin_amdgcn_mfma_f32_16x16x32_bf16(Bt[n][k], At[m][k], acc[ai][bj][m][n], 0, 0, 0); __builtin_amdgcn_s_setprio(0); } while (0)
; #define PG8_WAIT_V(n) asm volatile("s_waitcnt vmcnt(" #n ")" ::: "memory")
; #define PG8_WAIT_L(n) asm volatile("s_waitcnt lgkmcnt(" #n ")" ::: "memory")
; #define PG8_BAR __builtin_amdgcn_s_barrier()
; #define PG8_SCHED __builtin_amdgcn_sched_barrier(0)
; template <class Epi, bool ALIGN_EPI = PG8_ALIGN, bool SP2 = PG8_SP2>
; __device__ __forceinline__ void gemm_phase(LAS uchar* lds, const Gemm g, const StaticOrder& S, const Epi& E) {
;     ...
;             PG8_WAIT_V(8); PG8_WAIT_L(0); PG8_BAR; PG8_MMA(1, 0, At, B0); PG8_MMA(1, 1, At, B1); PG8_BAR; PG8_SCHED;
;             PG8_LDB(B0, 1, 0); PG8_LDB(B1, 1, 1); PG8_SCHED; PG8_LDA(At, 1, 0); PG8_STAGE(PG8_SA(0, 1), a2 + hstepA, voffA);
;             PG8_WAIT_V(8); PG8_WAIT_L(0); PG8_BAR; PG8_MMA(0, 0, At, B0); PG8_MMA(0, 1, At, B1); PG8_BAR; PG8_SCHED;
.Lrw_done_1050_1_pl:
	s_waitcnt lgkmcnt(0)
	s_setprio 1
	s_barrier
	v_mfma_f32_16x16x32_bf16 v[62:65], v[164:167], v[200:203], 0
	v_mfma_f32_16x16x32_bf16 v[54:57], v[172:175], v[200:203], 0
	v_mfma_f32_16x16x32_bf16 v[46:49], v[164:167], v[208:211], 0
	v_mfma_f32_16x16x32_bf16 v[38:41], v[172:175], v[208:211], 0
	v_mfma_f32_16x16x32_bf16 v[30:33], v[164:167], v[216:219], 0
	v_mfma_f32_16x16x32_bf16 v[22:25], v[172:175], v[216:219], 0
	v_mfma_f32_16x16x32_bf16 v[14:17], v[164:167], v[224:227], 0
	v_mfma_f32_16x16x32_bf16 v[6:9], v[172:175], v[224:227], 0
	v_mfma_f32_16x16x32_bf16 v[62:65], v[168:171], v[204:207], v[62:65]
	v_mfma_f32_16x16x32_bf16 v[54:57], v[176:179], v[204:207], v[54:57]
	v_mfma_f32_16x16x32_bf16 v[46:49], v[168:171], v[212:215], v[46:49]
	v_mfma_f32_16x16x32_bf16 v[38:41], v[176:179], v[212:215], v[38:41]
	v_mfma_f32_16x16x32_bf16 v[30:33], v[168:171], v[220:223], v[30:33]
	v_mfma_f32_16x16x32_bf16 v[22:25], v[176:179], v[220:223], v[22:25]
	v_mfma_f32_16x16x32_bf16 v[14:17], v[168:171], v[228:231], v[14:17]
	v_mfma_f32_16x16x32_bf16 v[6:9], v[176:179], v[228:231], v[6:9]
	v_mfma_f32_16x16x32_bf16 v[58:61], v[184:187], v[200:203], 0
	v_mfma_f32_16x16x32_bf16 v[50:53], v[192:195], v[200:203], 0
	v_mfma_f32_16x16x32_bf16 v[42:45], v[184:187], v[208:211], 0
	v_mfma_f32_16x16x32_bf16 v[34:37], v[192:195], v[208:211], 0
	v_mfma_f32_16x16x32_bf16 v[26:29], v[184:187], v[216:219], 0
	v_mfma_f32_16x16x32_bf16 v[18:21], v[192:195], v[216:219], 0
	v_mfma_f32_16x16x32_bf16 v[10:13], v[184:187], v[224:227], 0
	v_mfma_f32_16x16x32_bf16 v[2:5], v[192:195], v[224:227], 0
	v_mfma_f32_16x16x32_bf16 v[58:61], v[188:191], v[204:207], v[58:61]
	v_mfma_f32_16x16x32_bf16 v[50:53], v[196:199], v[204:207], v[50:53]
	v_mfma_f32_16x16x32_bf16 v[42:45], v[188:191], v[212:215], v[42:45]
	v_mfma_f32_16x16x32_bf16 v[34:37], v[196:199], v[212:215], v[34:37]
	v_mfma_f32_16x16x32_bf16 v[26:29], v[188:191], v[220:223], v[26:29]
	v_mfma_f32_16x16x32_bf16 v[18:21], v[196:199], v[220:223], v[18:21]
	v_mfma_f32_16x16x32_bf16 v[10:13], v[188:191], v[228:231], v[10:13]
	v_mfma_f32_16x16x32_bf16 v[2:5], v[196:199], v[228:231], v[2:5]
	s_barrier
	s_setprio 0
	s_add_i32 s39, 0, 0x18000
	v_add_u32_e32 v144, s39, v139
	s_add_i32 s40, 0, 0x1c000
	ds_read_b128 v[164:167], v144
	ds_read_b128 v[168:171], v144 offset:1024
	ds_read_b128 v[172:175], v144 offset:2048
	ds_read_b128 v[176:179], v144 offset:3072
	v_add_u32_e32 v144, s40, v139
	ds_read_b128 v[184:187], v144
	ds_read_b128 v[188:191], v144 offset:1024
	ds_read_b128 v[192:195], v144 offset:2048
	ds_read_b128 v[196:199], v144 offset:3072
	s_add_u32 s12, s18, 0x44000
	s_addc_u32 s13, s19, 0
	s_mov_b32 m0, s25
	v_lshl_add_u64 v[236:237], s[12:13], 0, v[154:155]
	ds_read_b128 v[200:203], v163 offset:32768
	ds_read_b128 v[204:207], v163 offset:33792
	ds_read_b128 v[208:211], v163 offset:34816
	ds_read_b128 v[212:215], v163 offset:35840
	ds_read_b128 v[216:219], v163 offset:36864
	ds_read_b128 v[220:223], v163 offset:37888
	ds_read_b128 v[224:227], v163 offset:38912
	ds_read_b128 v[228:231], v163 offset:39936
	global_load_lds_dwordx4 v[236:237], off
	v_lshl_add_u64 v[236:237], s[12:13], 0, v[132:133]
	s_mov_b32 m0, s26
	s_nop 0
	global_load_lds_dwordx4 v[236:237], off
	s_waitcnt vmcnt(8)
	s_waitcnt lgkmcnt(0)
	s_setprio 1
	s_barrier
	v_mfma_f32_16x16x32_bf16 v[126:129], v[164:167], v[200:203], v[126:129]
	v_mfma_f32_16x16x32_bf16 v[118:121], v[172:175], v[200:203], v[118:121]
	v_mfma_f32_16x16x32_bf16 v[110:113], v[164:167], v[208:211], v[110:113]
	v_mfma_f32_16x16x32_bf16 v[102:105], v[172:175], v[208:211], v[102:105]
	v_mfma_f32_16x16x32_bf16 v[94:97], v[164:167], v[216:219], v[94:97]
	v_mfma_f32_16x16x32_bf16 v[86:89], v[172:175], v[216:219], v[86:89]
	v_mfma_f32_16x16x32_bf16 v[78:81], v[164:167], v[224:227], v[78:81]
	v_mfma_f32_16x16x32_bf16 v[70:73], v[172:175], v[224:227], v[70:73]
	v_mfma_f32_16x16x32_bf16 v[126:129], v[168:171], v[204:207], v[126:129]
	v_mfma_f32_16x16x32_bf16 v[118:121], v[176:179], v[204:207], v[118:121]
	v_mfma_f32_16x16x32_bf16 v[110:113], v[168:171], v[212:215], v[110:113]
	v_mfma_f32_16x16x32_bf16 v[102:105], v[176:179], v[212:215], v[102:105]
	v_mfma_f32_16x16x32_bf16 v[94:97], v[168:171], v[220:223], v[94:97]
	v_mfma_f32_16x16x32_bf16 v[86:89], v[176:179], v[220:223], v[86:89]
	v_mfma_f32_16x16x32_bf16 v[78:81], v[168:171], v[228:231], v[78:81]
	v_mfma_f32_16x16x32_bf16 v[70:73], v[176:179], v[228:231], v[70:73]
	v_mfma_f32_16x16x32_bf16 v[122:125], v[184:187], v[200:203], v[122:125]
	v_mfma_f32_16x16x32_bf16 v[114:117], v[192:195], v[200:203], v[114:117]
	v_mfma_f32_16x16x32_bf16 v[106:109], v[184:187], v[208:211], v[106:109]
	v_mfma_f32_16x16x32_bf16 v[98:101], v[192:195], v[208:211], v[98:101]
	v_mfma_f32_16x16x32_bf16 v[90:93], v[184:187], v[216:219], v[90:93]
	v_mfma_f32_16x16x32_bf16 v[82:85], v[192:195], v[216:219], v[82:85]
	v_mfma_f32_16x16x32_bf16 v[74:77], v[184:187], v[224:227], v[74:77]
	v_mfma_f32_16x16x32_bf16 v[66:69], v[192:195], v[224:227], v[66:69]
	v_mfma_f32_16x16x32_bf16 v[122:125], v[188:191], v[204:207], v[122:125]
	v_mfma_f32_16x16x32_bf16 v[114:117], v[196:199], v[204:207], v[114:117]
	v_mfma_f32_16x16x32_bf16 v[106:109], v[188:191], v[212:215], v[106:109]
	v_mfma_f32_16x16x32_bf16 v[98:101], v[196:199], v[212:215], v[98:101]
	v_mfma_f32_16x16x32_bf16 v[90:93], v[188:191], v[220:223], v[90:93]
	v_mfma_f32_16x16x32_bf16 v[82:85], v[196:199], v[220:223], v[82:85]
	v_mfma_f32_16x16x32_bf16 v[74:77], v[188:191], v[228:231], v[74:77]
	v_mfma_f32_16x16x32_bf16 v[66:69], v[196:199], v[228:231], v[66:69]
	s_barrier
; #define PG8_STAGE(bufoff, gbase, voff) do { _Pragma("unroll") for (int _i = 0; _i < 2; ++_i) \
;         __builtin_amdgcn_global_load_lds((const unsigned*)((const char*)(gbase) + (voff)[_i]), (LAS unsigned*)(lds + (bufoff) + ldsw + _i * 8192), 16, 0, 0); } while (0)
; #define PG8_LDA(dst, b, h) do { _Pragma("unroll") for (int m = 0; m < 4; ++m) _Pragma("unroll") for (int k = 0; k < 2; ++k) dst[m][k] = *(const LAS bf16x8*)(lds + PG8_SA(b, h) + aoff + m * 2048 + k * 1024); } while (0)
; #define PG8_LDB(dst, b, h) do { _Pragma("unroll") for (int n = 0; n < 2; ++n) _Pragma("unroll") for (int k = 0; k < 2; ++k) dst[n][k] = *(const LAS bf16x8*)(lds + PG8_SB(b, h) + boff + n * 2048 + k * 1024); } while (0)
; #define PG8_WAIT_V(n) asm volatile("s_waitcnt vmcnt(" #n ")" ::: "memory")
; #define PG8_BAR __builtin_amdgcn_s_barrier()
; template <class Epi, bool ALIGN_EPI = PG8_ALIGN, bool SP2 = PG8_SP2>
; __device__ __forceinline__ void gemm_phase(LAS uchar* lds, const Gemm g, const StaticOrder& S, const Epi& E) {
;     ...
;             const bool last = (t == nt - 2);
;             const char* a1 = cA + (size_t)(t + 1) * kstep;
;             const char* a2 = last ? nA : cA + (size_t)(t + 2) * kstep; const char* b2 = last ? nB : cB + (size_t)(t + 2) * kstep;
;             const char* a3 = a2 + kstep; const char* b3 = b2 + kstep;
;             if constexpr (SP2) {
;             PG8_LDB(B0, 0, 0); PG8_LDB(B1, 0, 1); PG8_SCHED; PG8_LDA(At, 0, 0); PG8_STAGE(PG8_SA(1, 1), a1 + hstepA, voffA);
;             PG8_WAIT_V(8); PG8_WAIT_L(0); PG8_BAR; PG8_MMA(0, 0, At, B0); PG8_MMA(0, 1, At, B1); PG8_BAR; PG8_SCHED;
;             PG8_LDA(At, 0, 1); PG8_STAGE(PG8_SB(0, 0), b2, voffB); PG8_STAGE(PG8_SB(0, 1), b2 + hstepB, voffB); PG8_STAGE(PG8_SA(0, 0), a2, voffA);
;             PG8_WAIT_V(8); PG8_WAIT_L(0); PG8_BAR; PG8_MMA(1, 0, At, B0); PG8_MMA(1, 1, At, B1); PG8_BAR; PG8_SCHED;
;             PG8_LDB(B0, 1, 0); PG8_LDB(B1, 1, 1); PG8_SCHED; PG8_LDA(At, 1, 0); PG8_STAGE(PG8_SA(0, 1), a2 + hstepA, voffA);
;             PG8_WAIT_V(8); PG8_WAIT_L(0); PG8_BAR; PG8_MMA(0, 0, At, B0); PG8_MMA(0, 1, At, B1); PG8_BAR; PG8_SCHED;
;             PG8_LDA(At, 1, 1); PG8_STAGE(PG8_SB(1, 0), b3, voffB); PG8_STAGE(PG8_SB(1, 1), b3 + hstepB, voffB); PG8_STAGE(PG8_SA(1, 0), a3, voffA);
;             PG8_WAIT_V(8); PG8_WAIT_L(0); PG8_BAR; PG8_MMA(1, 0, At, B0); PG8_MMA(1, 1, At, B1); PG8_BAR; PG8_SCHED;
	s_setprio 0
	s_add_i32 s12, s39, s21
	v_lshl_add_u64 v[160:161], v[160:161], 0, s[84:85]
	s_mov_b32 m0, s12
	ds_read_b128 v[200:203], v163 offset:49152
	ds_read_b128 v[204:207], v163 offset:50176
	ds_read_b128 v[208:211], v163 offset:51200
	ds_read_b128 v[212:215], v163 offset:52224
	ds_read_b128 v[216:219], v163 offset:53248
	ds_read_b128 v[220:223], v163 offset:54272
	ds_read_b128 v[224:227], v163 offset:55296
	ds_read_b128 v[228:231], v163 offset:56320
	global_load_lds_dwordx4 v[160:161], off
	s_add_i32 m0, s12, 0x2000
	s_add_u32 s12, s16, 0x44080
	v_lshl_add_u64 v[160:161], v[180:181], 0, s[84:85]
	s_addc_u32 s13, s17, 0
	s_add_i32 s16, s40, s21
	global_load_lds_dwordx4 v[160:161], off
	v_lshl_add_u64 v[160:161], s[12:13], 0, v[134:135]
	s_mov_b32 m0, s16
	s_nop 0
	global_load_lds_dwordx4 v[160:161], off
	v_lshl_add_u64 v[160:161], s[12:13], 0, v[130:131]
	s_add_i32 m0, s16, 0x2000
	s_nop 0
	global_load_lds_dwordx4 v[160:161], off
	v_lshl_add_u64 v[160:161], v[232:233], 0, s[84:85]
	s_mov_b32 m0, s27
	s_nop 0
	global_load_lds_dwordx4 v[160:161], off
	v_lshl_add_u64 v[160:161], v[234:235], 0, s[84:85]
	s_mov_b32 m0, s28
	s_nop 0
	global_load_lds_dwordx4 v[160:161], off
	s_waitcnt vmcnt(8)
	s_waitcnt lgkmcnt(0)
	s_setprio 1
	s_barrier
	v_mfma_f32_16x16x32_bf16 v[62:65], v[164:167], v[200:203], v[62:65]
	v_mfma_f32_16x16x32_bf16 v[54:57], v[172:175], v[200:203], v[54:57]
	v_mfma_f32_16x16x32_bf16 v[46:49], v[164:167], v[208:211], v[46:49]
	v_mfma_f32_16x16x32_bf16 v[38:41], v[172:175], v[208:211], v[38:41]
	v_mfma_f32_16x16x32_bf16 v[30:33], v[164:167], v[216:219], v[30:33]
	v_mfma_f32_16x16x32_bf16 v[22:25], v[172:175], v[216:219], v[22:25]
	v_mfma_f32_16x16x32_bf16 v[14:17], v[164:167], v[224:227], v[14:17]
	v_mfma_f32_16x16x32_bf16 v[6:9], v[172:175], v[224:227], v[6:9]
	v_mfma_f32_16x16x32_bf16 v[62:65], v[168:171], v[204:207], v[62:65]
	v_mfma_f32_16x16x32_bf16 v[54:57], v[176:179], v[204:207], v[54:57]
	v_mfma_f32_16x16x32_bf16 v[46:49], v[168:171], v[212:215], v[46:49]
	v_mfma_f32_16x16x32_bf16 v[38:41], v[176:179], v[212:215], v[38:41]
	v_mfma_f32_16x16x32_bf16 v[30:33], v[168:171], v[220:223], v[30:33]
	v_mfma_f32_16x16x32_bf16 v[22:25], v[176:179], v[220:223], v[22:25]
	v_mfma_f32_16x16x32_bf16 v[14:17], v[168:171], v[228:231], v[14:17]
	v_mfma_f32_16x16x32_bf16 v[6:9], v[176:179], v[228:231], v[6:9]
	v_mfma_f32_16x16x32_bf16 v[58:61], v[184:187], v[200:203], v[58:61]
	v_mfma_f32_16x16x32_bf16 v[50:53], v[192:195], v[200:203], v[50:53]
	v_mfma_f32_16x16x32_bf16 v[42:45], v[184:187], v[208:211], v[42:45]
	v_mfma_f32_16x16x32_bf16 v[34:37], v[192:195], v[208:211], v[34:37]
	v_mfma_f32_16x16x32_bf16 v[26:29], v[184:187], v[216:219], v[26:29]
	v_mfma_f32_16x16x32_bf16 v[18:21], v[192:195], v[216:219], v[18:21]
	v_mfma_f32_16x16x32_bf16 v[10:13], v[184:187], v[224:227], v[10:13]
	v_mfma_f32_16x16x32_bf16 v[2:5], v[192:195], v[224:227], v[2:5]
	v_mfma_f32_16x16x32_bf16 v[58:61], v[188:191], v[204:207], v[58:61]
	v_mfma_f32_16x16x32_bf16 v[50:53], v[196:199], v[204:207], v[50:53]
	v_mfma_f32_16x16x32_bf16 v[42:45], v[188:191], v[212:215], v[42:45]
	v_mfma_f32_16x16x32_bf16 v[34:37], v[196:199], v[212:215], v[34:37]
	v_mfma_f32_16x16x32_bf16 v[26:29], v[188:191], v[220:223], v[26:29]
	v_mfma_f32_16x16x32_bf16 v[18:21], v[196:199], v[220:223], v[18:21]
	v_mfma_f32_16x16x32_bf16 v[10:13], v[188:191], v[228:231], v[10:13]
	v_mfma_f32_16x16x32_bf16 v[2:5], v[196:199], v[228:231], v[2:5]
	s_barrier
	s_setprio 0
	s_add_i32 s38, s38, 2
	s_add_u32 s36, s36, 0x100
	s_addc_u32 s37, s37, 0
	s_cmp_gt_u32 s38, 13
	s_mov_b64 s[12:13], s[14:15]
.LBB0_1050:
	s_add_u32 s14, s12, 0x100
	s_addc_u32 s15, s13, 0
	s_add_i32 s39, 0, 0x10000
	s_cmp_eq_u32 s38, 12
	s_cselect_b32 s19, s1, s15
	s_cselect_b32 s18, s0, s14
	v_add_u32_e32 v144, s39, v139
	s_cselect_b32 s17, s11, s37
	s_cselect_b32 s16, s10, s36
	s_add_i32 s40, 0, 0x14000
	ds_read_b128 v[164:167], v144
	ds_read_b128 v[168:171], v144 offset:1024
	ds_read_b128 v[172:175], v144 offset:2048
	ds_read_b128 v[176:179], v144 offset:3072
	v_add_u32_e32 v144, s40, v139
	ds_read_b128 v[184:187], v144
	ds_read_b128 v[188:191], v144 offset:1024
	ds_read_b128 v[192:195], v144 offset:2048
	ds_read_b128 v[196:199], v144 offset:3072
	v_lshl_add_u64 v[160:161], s[12:13], 0, v[156:157]
	s_add_i32 m0, s23, 0xc000
	ds_read_b128 v[200:203], v163
	ds_read_b128 v[204:207], v163 offset:1024
	ds_read_b128 v[208:211], v163 offset:2048
	ds_read_b128 v[212:215], v163 offset:3072
	ds_read_b128 v[216:219], v163 offset:4096
	ds_read_b128 v[220:223], v163 offset:5120
	ds_read_b128 v[224:227], v163 offset:6144
	ds_read_b128 v[228:231], v163 offset:7168
	global_load_lds_dwordx4 v[160:161], off
	v_lshl_add_u64 v[160:161], s[12:13], 0, v[158:159]
	s_add_i32 m0, s23, 0xe000
	s_nop 0
	global_load_lds_dwordx4 v[160:161], off
	s_waitcnt vmcnt(8)
	s_waitcnt lgkmcnt(0)
	s_setprio 1
	s_barrier
; #define PG8_STAGE(bufoff, gbase, voff) do { _Pragma("unroll") for (int _i = 0; _i < 2; ++_i) \
;         __builtin_amdgcn_global_load_lds((const unsigned*)((const char*)(gbase) + (voff)[_i]), (LAS unsigned*)(lds + (bufoff) + ldsw + _i * 8192), 16, 0, 0); } while (0)
; #define PG8_LDA(dst, b, h) do { _Pragma("unroll") for (int m = 0; m < 4; ++m) _Pragma("unroll") for (int k = 0; k < 2; ++k) dst[m][k] = *(const LAS bf16x8*)(lds + PG8_SA(b, h) + aoff + m * 2048 + k * 1024); } while (0)
; #define PG8_MMA(ai, bj, At, Bt) do { __builtin_amdgcn_s_setprio(1); _Pragma("unroll") for (int m = 0; m < 4; ++m) _Pragma("unroll") for (int n = 0; n < 2; ++n) _Pragma("unroll") for (int k = 0; k < 2; ++k) \
;         acc[ai][bj][m][n] = __builtin_amdgcn_mfma_f32_16x16x32_bf16(Bt[n][k], At[m][k], acc[ai][bj][m][n], 0, 0, 0); __builtin_amdgcn_s_setprio(0); } while (0)
; #define PG8_WAIT_V(n) asm volatile("s_waitcnt vmcnt(" #n ")" ::: "memory")
; #define PG8_WAIT_L(n) asm volatile("s_waitcnt lgkmcnt(" #n ")" ::: "memory")
; #define PG8_BAR __builtin_amdgcn_s_barrier()
; #define PG8_SCHED __builtin_amdgcn_sched_barrier(0)
; template <class Epi, bool ALIGN_EPI = PG8_ALIGN, bool SP2 = PG8_SP2>
; __device__ __forceinline__ void gemm_phase(LAS uchar* lds, const Gemm g, const StaticOrder& S, const Epi& E) {
;     ...
;             PG8_WAIT_V(8); PG8_WAIT_L(0); PG8_BAR; PG8_MMA(0, 0, At, B0); PG8_MMA(0, 1, At, B1); PG8_BAR; PG8_SCHED;
;             PG8_LDA(At, 0, 1); PG8_STAGE(PG8_SB(0, 0), b2, voffB); PG8_STAGE(PG8_SB(0, 1), b2 + hstepB, voffB); PG8_STAGE(PG8_SA(0, 0), a2, voffA);
;             PG8_WAIT_V(8); PG8_WAIT_L(0); PG8_BAR; PG8_MMA(1, 0, At, B0); PG8_MMA(1, 1, At, B1); PG8_BAR; PG8_SCHED;
	v_mfma_f32_16x16x32_bf16 v[126:129], v[164:167], v[200:203], v[126:129]
	v_mfma_f32_16x16x32_bf16 v[118:121], v[172:175], v[200:203], v[118:121]
	v_mfma_f32_16x16x32_bf16 v[110:113], v[164:167], v[208:211], v[110:113]
	v_mfma_f32_16x16x32_bf16 v[102:105], v[172:175], v[208:211], v[102:105]
	v_mfma_f32_16x16x32_bf16 v[94:97], v[164:167], v[216:219], v[94:97]
	v_mfma_f32_16x16x32_bf16 v[86:89], v[172:175], v[216:219], v[86:89]
	v_mfma_f32_16x16x32_bf16 v[78:81], v[164:167], v[224:227], v[78:81]
	v_mfma_f32_16x16x32_bf16 v[70:73], v[172:175], v[224:227], v[70:73]
	v_mfma_f32_16x16x32_bf16 v[126:129], v[168:171], v[204:207], v[126:129]
	v_mfma_f32_16x16x32_bf16 v[118:121], v[176:179], v[204:207], v[118:121]
	v_mfma_f32_16x16x32_bf16 v[110:113], v[168:171], v[212:215], v[110:113]
	v_mfma_f32_16x16x32_bf16 v[102:105], v[176:179], v[212:215], v[102:105]
	v_mfma_f32_16x16x32_bf16 v[94:97], v[168:171], v[220:223], v[94:97]
	v_mfma_f32_16x16x32_bf16 v[86:89], v[176:179], v[220:223], v[86:89]
	v_mfma_f32_16x16x32_bf16 v[78:81], v[168:171], v[228:231], v[78:81]
	v_mfma_f32_16x16x32_bf16 v[70:73], v[176:179], v[228:231], v[70:73]
	v_mfma_f32_16x16x32_bf16 v[122:125], v[184:187], v[200:203], v[122:125]
	v_mfma_f32_16x16x32_bf16 v[114:117], v[192:195], v[200:203], v[114:117]
	v_mfma_f32_16x16x32_bf16 v[106:109], v[184:187], v[208:211], v[106:109]
	v_mfma_f32_16x16x32_bf16 v[98:101], v[192:195], v[208:211], v[98:101]
	v_mfma_f32_16x16x32_bf16 v[90:93], v[184:187], v[216:219], v[90:93]
	v_mfma_f32_16x16x32_bf16 v[82:85], v[192:195], v[216:219], v[82:85]
	v_mfma_f32_16x16x32_bf16 v[74:77], v[184:187], v[224:227], v[74:77]
	v_mfma_f32_16x16x32_bf16 v[66:69], v[192:195], v[224:227], v[66:69]
	v_mfma_f32_16x16x32_bf16 v[122:125], v[188:191], v[204:207], v[122:125]
	v_mfma_f32_16x16x32_bf16 v[114:117], v[196:199], v[204:207], v[114:117]
	v_mfma_f32_16x16x32_bf16 v[106:109], v[188:191], v[212:215], v[106:109]
	v_mfma_f32_16x16x32_bf16 v[98:101], v[196:199], v[212:215], v[98:101]
	v_mfma_f32_16x16x32_bf16 v[90:93], v[188:191], v[220:223], v[90:93]
	v_mfma_f32_16x16x32_bf16 v[82:85], v[196:199], v[220:223], v[82:85]
	v_mfma_f32_16x16x32_bf16 v[74:77], v[188:191], v[228:231], v[74:77]
	v_mfma_f32_16x16x32_bf16 v[66:69], v[196:199], v[228:231], v[66:69]
	s_barrier
	s_setprio 0
	s_add_i32 s12, s39, s21
	v_lshl_add_u64 v[160:161], s[16:17], 0, v[134:135]
	s_mov_b32 m0, s12
	ds_read_b128 v[200:203], v163 offset:16384
	ds_read_b128 v[204:207], v163 offset:17408
	ds_read_b128 v[208:211], v163 offset:18432
	ds_read_b128 v[212:215], v163 offset:19456
	ds_read_b128 v[216:219], v163 offset:20480
	ds_read_b128 v[220:223], v163 offset:21504
	ds_read_b128 v[224:227], v163 offset:22528
	ds_read_b128 v[228:231], v163 offset:23552
	global_load_lds_dwordx4 v[160:161], off
	s_add_i32 m0, s12, 0x2000
	s_add_u32 s12, s16, 0x44000
	v_lshl_add_u64 v[180:181], s[16:17], 0, v[130:131]
	s_addc_u32 s13, s17, 0
	s_add_i32 s39, s40, s21
	global_load_lds_dwordx4 v[180:181], off
	v_lshl_add_u64 v[232:233], s[12:13], 0, v[134:135]
	s_mov_b32 m0, s39
	v_lshl_add_u64 v[234:235], s[18:19], 0, v[132:133]
	global_load_lds_dwordx4 v[232:233], off
	v_lshl_add_u64 v[232:233], s[12:13], 0, v[130:131]
	s_add_i32 m0, s39, 0x2000
	s_nop 0
	global_load_lds_dwordx4 v[232:233], off
	v_lshl_add_u64 v[232:233], s[18:19], 0, v[154:155]
	s_mov_b32 m0, s23
	s_nop 0
	global_load_lds_dwordx4 v[232:233], off
	s_mov_b32 m0, s24
	s_nop 0
	global_load_lds_dwordx4 v[234:235], off
	s_waitcnt vmcnt(8)
	s_waitcnt lgkmcnt(0)
	s_setprio 1
	s_barrier
	v_mfma_f32_16x16x32_bf16 v[62:65], v[164:167], v[200:203], v[62:65]
	v_mfma_f32_16x16x32_bf16 v[54:57], v[172:175], v[200:203], v[54:57]
	v_mfma_f32_16x16x32_bf16 v[46:49], v[164:167], v[208:211], v[46:49]
	v_mfma_f32_16x16x32_bf16 v[38:41], v[172:175], v[208:211], v[38:41]
	v_mfma_f32_16x16x32_bf16 v[30:33], v[164:167], v[216:219], v[30:33]
	v_mfma_f32_16x16x32_bf16 v[22:25], v[172:175], v[216:219], v[22:25]
	v_mfma_f32_16x16x32_bf16 v[14:17], v[164:167], v[224:227], v[14:17]
	v_mfma_f32_16x16x32_bf16 v[6:9], v[172:175], v[224:227], v[6:9]
	v_mfma_f32_16x16x32_bf16 v[62:65], v[168:171], v[204:207], v[62:65]
	v_mfma_f32_16x16x32_bf16 v[54:57], v[176:179], v[204:207], v[54:57]
	v_mfma_f32_16x16x32_bf16 v[46:49], v[168:171], v[212:215], v[46:49]
	v_mfma_f32_16x16x32_bf16 v[38:41], v[176:179], v[212:215], v[38:41]
	v_mfma_f32_16x16x32_bf16 v[30:33], v[168:171], v[220:223], v[30:33]
	v_mfma_f32_16x16x32_bf16 v[22:25], v[176:179], v[220:223], v[22:25]
	v_mfma_f32_16x16x32_bf16 v[14:17], v[168:171], v[228:231], v[14:17]
	v_mfma_f32_16x16x32_bf16 v[6:9], v[176:179], v[228:231], v[6:9]
	v_mfma_f32_16x16x32_bf16 v[58:61], v[184:187], v[200:203], v[58:61]
	v_mfma_f32_16x16x32_bf16 v[50:53], v[192:195], v[200:203], v[50:53]
	v_mfma_f32_16x16x32_bf16 v[42:45], v[184:187], v[208:211], v[42:45]
	v_mfma_f32_16x16x32_bf16 v[34:37], v[192:195], v[208:211], v[34:37]
	v_mfma_f32_16x16x32_bf16 v[26:29], v[184:187], v[216:219], v[26:29]
	v_mfma_f32_16x16x32_bf16 v[18:21], v[192:195], v[216:219], v[18:21]
	v_mfma_f32_16x16x32_bf16 v[10:13], v[184:187], v[224:227], v[10:13]
	v_mfma_f32_16x16x32_bf16 v[2:5], v[192:195], v[224:227], v[2:5]
	v_mfma_f32_16x16x32_bf16 v[58:61], v[188:191], v[204:207], v[58:61]
	v_mfma_f32_16x16x32_bf16 v[50:53], v[196:199], v[204:207], v[50:53]
	v_mfma_f32_16x16x32_bf16 v[42:45], v[188:191], v[212:215], v[42:45]
	v_mfma_f32_16x16x32_bf16 v[34:37], v[196:199], v[212:215], v[34:37]
	v_mfma_f32_16x16x32_bf16 v[26:29], v[188:191], v[220:223], v[26:29]
	v_mfma_f32_16x16x32_bf16 v[18:21], v[196:199], v[220:223], v[18:21]
	v_mfma_f32_16x16x32_bf16 v[10:13], v[188:191], v[228:231], v[10:13]
	v_mfma_f32_16x16x32_bf16 v[2:5], v[196:199], v[228:231], v[2:5]
	s_barrier
; #define PG8_STAGE(bufoff, gbase, voff) do { _Pragma("unroll") for (int _i = 0; _i < 2; ++_i) \
;         __builtin_amdgcn_global_load_lds((const unsigned*)((const char*)(gbase) + (voff)[_i]), (LAS unsigned*)(lds + (bufoff) + ldsw + _i * 8192), 16, 0, 0); } while (0)
; #define PG8_LDA(dst, b, h) do { _Pragma("unroll") for (int m = 0; m < 4; ++m) _Pragma("unroll") for (int k = 0; k < 2; ++k) dst[m][k] = *(const LAS bf16x8*)(lds + PG8_SA(b, h) + aoff + m * 2048 + k * 1024); } while (0)
; #define PG8_LDB(dst, b, h) do { _Pragma("unroll") for (int n = 0; n < 2; ++n) _Pragma("unroll") for (int k = 0; k < 2; ++k) dst[n][k] = *(const LAS bf16x8*)(lds + PG8_SB(b, h) + boff + n * 2048 + k * 1024); } while (0)
; #define PG8_MMA(ai, bj, At, Bt) do { __builtin_amdgcn_s_setprio(1); _Pragma("unroll") for (int m = 0; m < 4; ++m) _Pragma("unroll") for (int n = 0; n < 2; ++n) _Pragma("unroll") for (int k = 0; k < 2; ++k) \
;         acc[ai][bj][m][n] = __builtin_amdgcn_mfma_f32_16x16x32_bf16(Bt[n][k], At[m][k], acc[ai][bj][m][n], 0, 0, 0); __builtin_amdgcn_s_setprio(0); } while (0)
; #define PG8_WAIT_V(n) asm volatile("s_waitcnt vmcnt(" #n ")" ::: "memory")
; #define PG8_WAIT_L(n) asm volatile("s_waitcnt lgkmcnt(" #n ")" ::: "memory")
; #define PG8_BAR __builtin_amdgcn_s_barrier()
; #define PG8_SCHED __builtin_amdgcn_sched_barrier(0)
; template <class Epi, bool ALIGN_EPI = PG8_ALIGN, bool SP2 = PG8_SP2>
; __device__ __forceinline__ void gemm_phase(LAS uchar* lds, const Gemm g, const StaticOrder& S, const Epi& E) {
;     ...
;             PG8_LDB(B0, 1, 0); PG8_LDB(B1, 1, 1); PG8_SCHED; PG8_LDA(At, 1, 0); PG8_STAGE(PG8_SA(0, 1), a2 + hstepA, voffA);
;             PG8_WAIT_V(8); PG8_WAIT_L(0); PG8_BAR; PG8_MMA(0, 0, At, B0); PG8_MMA(0, 1, At, B1); PG8_BAR; PG8_SCHED;
	s_setprio 0
	s_add_i32 s39, 0, 0x18000
	v_add_u32_e32 v144, s39, v139
	s_add_i32 s40, 0, 0x1c000
	ds_read_b128 v[164:167], v144
	ds_read_b128 v[168:171], v144 offset:1024
	ds_read_b128 v[172:175], v144 offset:2048
	ds_read_b128 v[176:179], v144 offset:3072
	v_add_u32_e32 v144, s40, v139
	ds_read_b128 v[184:187], v144
	ds_read_b128 v[188:191], v144 offset:1024
	ds_read_b128 v[192:195], v144 offset:2048
	ds_read_b128 v[196:199], v144 offset:3072
	s_add_u32 s12, s18, 0x44000
	s_addc_u32 s13, s19, 0
	s_mov_b32 m0, s25
	v_lshl_add_u64 v[236:237], s[12:13], 0, v[154:155]
	ds_read_b128 v[200:203], v163 offset:32768
	ds_read_b128 v[204:207], v163 offset:33792
	ds_read_b128 v[208:211], v163 offset:34816
	ds_read_b128 v[212:215], v163 offset:35840
	ds_read_b128 v[216:219], v163 offset:36864
	ds_read_b128 v[220:223], v163 offset:37888
	ds_read_b128 v[224:227], v163 offset:38912
	ds_read_b128 v[228:231], v163 offset:39936
	global_load_lds_dwordx4 v[236:237], off
	v_lshl_add_u64 v[236:237], s[12:13], 0, v[132:133]
	s_mov_b32 m0, s26
	s_nop 0
	global_load_lds_dwordx4 v[236:237], off
	s_waitcnt vmcnt(8)
	s_waitcnt lgkmcnt(0)
	s_setprio 1
	s_barrier
	v_mfma_f32_16x16x32_bf16 v[126:129], v[164:167], v[200:203], v[126:129]
	v_mfma_f32_16x16x32_bf16 v[118:121], v[172:175], v[200:203], v[118:121]
	v_mfma_f32_16x16x32_bf16 v[110:113], v[164:167], v[208:211], v[110:113]
	v_mfma_f32_16x16x32_bf16 v[102:105], v[172:175], v[208:211], v[102:105]
	v_mfma_f32_16x16x32_bf16 v[94:97], v[164:167], v[216:219], v[94:97]
	v_mfma_f32_16x16x32_bf16 v[86:89], v[172:175], v[216:219], v[86:89]
	v_mfma_f32_16x16x32_bf16 v[78:81], v[164:167], v[224:227], v[78:81]
	v_mfma_f32_16x16x32_bf16 v[70:73], v[172:175], v[224:227], v[70:73]
	v_mfma_f32_16x16x32_bf16 v[126:129], v[168:171], v[204:207], v[126:129]
	v_mfma_f32_16x16x32_bf16 v[118:121], v[176:179], v[204:207], v[118:121]
	v_mfma_f32_16x16x32_bf16 v[110:113], v[168:171], v[212:215], v[110:113]
	v_mfma_f32_16x16x32_bf16 v[102:105], v[176:179], v[212:215], v[102:105]
	v_mfma_f32_16x16x32_bf16 v[94:97], v[168:171], v[220:223], v[94:97]
	v_mfma_f32_16x16x32_bf16 v[86:89], v[176:179], v[220:223], v[86:89]
	v_mfma_f32_16x16x32_bf16 v[78:81], v[168:171], v[228:231], v[78:81]
	v_mfma_f32_16x16x32_bf16 v[70:73], v[176:179], v[228:231], v[70:73]
	v_mfma_f32_16x16x32_bf16 v[122:125], v[184:187], v[200:203], v[122:125]
	v_mfma_f32_16x16x32_bf16 v[114:117], v[192:195], v[200:203], v[114:117]
	v_mfma_f32_16x16x32_bf16 v[106:109], v[184:187], v[208:211], v[106:109]
	v_mfma_f32_16x16x32_bf16 v[98:101], v[192:195], v[208:211], v[98:101]
	v_mfma_f32_16x16x32_bf16 v[90:93], v[184:187], v[216:219], v[90:93]
	v_mfma_f32_16x16x32_bf16 v[82:85], v[192:195], v[216:219], v[82:85]
	v_mfma_f32_16x16x32_bf16 v[74:77], v[184:187], v[224:227], v[74:77]
	v_mfma_f32_16x16x32_bf16 v[66:69], v[192:195], v[224:227], v[66:69]
	v_mfma_f32_16x16x32_bf16 v[122:125], v[188:191], v[204:207], v[122:125]
	v_mfma_f32_16x16x32_bf16 v[114:117], v[196:199], v[204:207], v[114:117]
	v_mfma_f32_16x16x32_bf16 v[106:109], v[188:191], v[212:215], v[106:109]
	v_mfma_f32_16x16x32_bf16 v[98:101], v[196:199], v[212:215], v[98:101]
	v_mfma_f32_16x16x32_bf16 v[90:93], v[188:191], v[220:223], v[90:93]
	v_mfma_f32_16x16x32_bf16 v[82:85], v[196:199], v[220:223], v[82:85]
	v_mfma_f32_16x16x32_bf16 v[74:77], v[188:191], v[228:231], v[74:77]
	v_mfma_f32_16x16x32_bf16 v[66:69], v[196:199], v[228:231], v[66:69]
	s_barrier
; #define PG8_STAGE(bufoff, gbase, voff) do { _Pragma("unroll") for (int _i = 0; _i < 2; ++_i) \
;         __builtin_amdgcn_global_load_lds((const unsigned*)((const char*)(gbase) + (voff)[_i]), (LAS unsigned*)(lds + (bufoff) + ldsw + _i * 8192), 16, 0, 0); } while (0)
; #define PG8_LDA(dst, b, h) do { _Pragma("unroll") for (int m = 0; m < 4; ++m) _Pragma("unroll") for (int k = 0; k < 2; ++k) dst[m][k] = *(const LAS bf16x8*)(lds + PG8_SA(b, h) + aoff + m * 2048 + k * 1024); } while (0)
; #define PG8_MMA(ai, bj, At, Bt) do { __builtin_amdgcn_s_setprio(1); _Pragma("unroll") for (int m = 0; m < 4; ++m) _Pragma("unroll") for (int n = 0; n < 2; ++n) _Pragma("unroll") for (int k = 0; k < 2; ++k) \
;         acc[ai][bj][m][n] = __builtin_amdgcn_mfma_f32_16x16x32_bf16(Bt[n][k], At[m][k], acc[ai][bj][m][n], 0, 0, 0); __builtin_amdgcn_s_setprio(0); } while (0)
; #define PG8_WAIT_V(n) asm volatile("s_waitcnt vmcnt(" #n ")" ::: "memory")
; #define PG8_WAIT_L(n) asm volatile("s_waitcnt lgkmcnt(" #n ")" ::: "memory")
; #define PG8_BAR __builtin_amdgcn_s_barrier()
; #define PG8_SCHED __builtin_amdgcn_sched_barrier(0)
; template <class Epi, bool ALIGN_EPI = PG8_ALIGN, bool SP2 = PG8_SP2>
; __device__ __forceinline__ void gemm_phase(LAS uchar* lds, const Gemm g, const StaticOrder& S, const Epi& E) {
;     ...
;             PG8_LDA(At, 1, 1); PG8_STAGE(PG8_SB(1, 0), b3, voffB); PG8_STAGE(PG8_SB(1, 1), b3 + hstepB, voffB); PG8_STAGE(PG8_SA(1, 0), a3, voffA);
;             PG8_WAIT_V(8); PG8_WAIT_L(0); PG8_BAR; PG8_MMA(1, 0, At, B0); PG8_MMA(1, 1, At, B1); PG8_BAR; PG8_SCHED;
	s_setprio 0
	s_add_i32 s12, s39, s21
	v_lshl_add_u64 v[160:161], v[160:161], 0, s[84:85]
	s_mov_b32 m0, s12
	ds_read_b128 v[200:203], v163 offset:49152
	ds_read_b128 v[204:207], v163 offset:50176
	ds_read_b128 v[208:211], v163 offset:51200
	ds_read_b128 v[212:215], v163 offset:52224
	ds_read_b128 v[216:219], v163 offset:53248
	ds_read_b128 v[220:223], v163 offset:54272
	ds_read_b128 v[224:227], v163 offset:55296
	ds_read_b128 v[228:231], v163 offset:56320
	global_load_lds_dwordx4 v[160:161], off
	s_add_i32 m0, s12, 0x2000
	s_add_u32 s12, s16, 0x44080
	v_lshl_add_u64 v[160:161], v[180:181], 0, s[84:85]
	s_addc_u32 s13, s17, 0
	s_add_i32 s16, s40, s21
	global_load_lds_dwordx4 v[160:161], off
	v_lshl_add_u64 v[160:161], s[12:13], 0, v[134:135]
	s_mov_b32 m0, s16
	s_nop 0
	global_load_lds_dwordx4 v[160:161], off
	v_lshl_add_u64 v[160:161], s[12:13], 0, v[130:131]
	s_add_i32 m0, s16, 0x2000
	s_nop 0
	global_load_lds_dwordx4 v[160:161], off
	v_lshl_add_u64 v[160:161], v[232:233], 0, s[84:85]
	s_mov_b32 m0, s27
	s_nop 0
	global_load_lds_dwordx4 v[160:161], off
	v_lshl_add_u64 v[160:161], v[234:235], 0, s[84:85]
	s_mov_b32 m0, s28
	s_nop 0
	global_load_lds_dwordx4 v[160:161], off
	s_waitcnt vmcnt(8)
	s_waitcnt lgkmcnt(0)
	s_setprio 1
	s_barrier
	v_mfma_f32_16x16x32_bf16 v[62:65], v[164:167], v[200:203], v[62:65]
	v_mfma_f32_16x16x32_bf16 v[54:57], v[172:175], v[200:203], v[54:57]
	v_mfma_f32_16x16x32_bf16 v[46:49], v[164:167], v[208:211], v[46:49]
	v_mfma_f32_16x16x32_bf16 v[38:41], v[172:175], v[208:211], v[38:41]
	v_mfma_f32_16x16x32_bf16 v[30:33], v[164:167], v[216:219], v[30:33]
	v_mfma_f32_16x16x32_bf16 v[22:25], v[172:175], v[216:219], v[22:25]
	v_mfma_f32_16x16x32_bf16 v[14:17], v[164:167], v[224:227], v[14:17]
	v_mfma_f32_16x16x32_bf16 v[6:9], v[172:175], v[224:227], v[6:9]
	v_mfma_f32_16x16x32_bf16 v[62:65], v[168:171], v[204:207], v[62:65]
	v_mfma_f32_16x16x32_bf16 v[54:57], v[176:179], v[204:207], v[54:57]
	v_mfma_f32_16x16x32_bf16 v[46:49], v[168:171], v[212:215], v[46:49]
	v_mfma_f32_16x16x32_bf16 v[38:41], v[176:179], v[212:215], v[38:41]
	v_mfma_f32_16x16x32_bf16 v[30:33], v[168:171], v[220:223], v[30:33]
	v_mfma_f32_16x16x32_bf16 v[22:25], v[176:179], v[220:223], v[22:25]
	v_mfma_f32_16x16x32_bf16 v[14:17], v[168:171], v[228:231], v[14:17]
	v_mfma_f32_16x16x32_bf16 v[6:9], v[176:179], v[228:231], v[6:9]
	v_mfma_f32_16x16x32_bf16 v[58:61], v[184:187], v[200:203], v[58:61]
	v_mfma_f32_16x16x32_bf16 v[50:53], v[192:195], v[200:203], v[50:53]
	v_mfma_f32_16x16x32_bf16 v[42:45], v[184:187], v[208:211], v[42:45]
	v_mfma_f32_16x16x32_bf16 v[34:37], v[192:195], v[208:211], v[34:37]
	v_mfma_f32_16x16x32_bf16 v[26:29], v[184:187], v[216:219], v[26:29]
	v_mfma_f32_16x16x32_bf16 v[18:21], v[192:195], v[216:219], v[18:21]
	v_mfma_f32_16x16x32_bf16 v[10:13], v[184:187], v[224:227], v[10:13]
	v_mfma_f32_16x16x32_bf16 v[2:5], v[192:195], v[224:227], v[2:5]
	v_mfma_f32_16x16x32_bf16 v[58:61], v[188:191], v[204:207], v[58:61]
	v_mfma_f32_16x16x32_bf16 v[50:53], v[196:199], v[204:207], v[50:53]
	v_mfma_f32_16x16x32_bf16 v[42:45], v[188:191], v[212:215], v[42:45]
	v_mfma_f32_16x16x32_bf16 v[34:37], v[196:199], v[212:215], v[34:37]
	v_mfma_f32_16x16x32_bf16 v[26:29], v[188:191], v[220:223], v[26:29]
	v_mfma_f32_16x16x32_bf16 v[18:21], v[196:199], v[220:223], v[18:21]
	v_mfma_f32_16x16x32_bf16 v[10:13], v[188:191], v[228:231], v[10:13]
	v_mfma_f32_16x16x32_bf16 v[2:5], v[196:199], v[228:231], v[2:5]
	s_barrier
	s_setprio 0
	s_add_i32 s38, s38, 2
	s_add_u32 s36, s36, 0x100
	s_addc_u32 s37, s37, 0
	s_cmp_gt_u32 s38, 13
	s_mov_b64 s[12:13], s[14:15]
	s_cbranch_scc0 .LBB0_1050
	s_and_b64 vcc, exec, s[8:9]
	s_cbranch_vccz .LBB0_1053
	s_barrier

; #define PG8_STAGE(bufoff, gbase, voff) do { _Pragma("unroll") for (int _i = 0; _i < 2; ++_i) \
;         __builtin_amdgcn_global_load_lds((const unsigned*)((const char*)(gbase) + (voff)[_i]), (LAS unsigned*)(lds + (bufoff) + ldsw + _i * 8192), 16, 0, 0); } while (0)
; #define PG8_LDA(dst, b, h) do { _Pragma("unroll") for (int m = 0; m < 4; ++m) _Pragma("unroll") for (int k = 0; k < 2; ++k) dst[m][k] = *(const LAS bf16x8*)(lds + PG8_SA(b, h) + aoff + m * 2048 + k * 1024); } while (0)
; #define PG8_LDB(dst, b, h) do { _Pragma("unroll") for (int n = 0; n < 2; ++n) _Pragma("unroll") for (int k = 0; k < 2; ++k) dst[n][k] = *(const LAS bf16x8*)(lds + PG8_SB(b, h) + boff + n * 2048 + k * 1024); } while (0)
; #define PG8_MMA(ai, bj, At, Bt) do { __builtin_amdgcn_s_setprio(1); _Pragma("unroll") for (int m = 0; m < 4; ++m) _Pragma("unroll") for (int n = 0; n < 2; ++n) _Pragma("unroll") for (int k = 0; k < 2; ++k) \
;         acc[ai][bj][m][n] = __builtin_amdgcn_mfma_f32_16x16x32_bf16(Bt[n][k], At[m][k], acc[ai][bj][m][n], 0, 0, 0); __builtin_amdgcn_s_setprio(0); } while (0)
; #define PG8_WAIT_V(n) asm volatile("s_waitcnt vmcnt(" #n ")" ::: "memory")
; #define PG8_WAIT_L(n) asm volatile("s_waitcnt lgkmcnt(" #n ")" ::: "memory")
; #define PG8_BAR __builtin_amdgcn_s_barrier()
; #define PG8_SCHED __builtin_amdgcn_sched_barrier(0)
; template <class Epi, bool ALIGN_EPI = PG8_ALIGN, bool SP2 = PG8_SP2>
; __device__ __forceinline__ void gemm_phase(LAS uchar* lds, const Gemm g, const StaticOrder& S, const Epi& E) {
;     ...
;             const bool last = (t == nt - 2);
;             const char* a1 = cA + (size_t)(t + 1) * kstep;
;             const char* a2 = last ? nA : cA + (size_t)(t + 2) * kstep; const char* b2 = last ? nB : cB + (size_t)(t + 2) * kstep;
;             const char* a3 = a2 + kstep; const char* b3 = b2 + kstep;
;             if constexpr (SP2) {
;             PG8_LDB(B0, 0, 0); PG8_LDB(B1, 0, 1); PG8_SCHED; PG8_LDA(At, 0, 0); PG8_STAGE(PG8_SA(1, 1), a1 + hstepA, voffA);
;             PG8_WAIT_V(8); PG8_WAIT_L(0); PG8_BAR; PG8_MMA(0, 0, At, B0); PG8_MMA(0, 1, At, B1); PG8_BAR; PG8_SCHED;
;             PG8_LDA(At, 0, 1); PG8_STAGE(PG8_SB(0, 0), b2, voffB); PG8_STAGE(PG8_SB(0, 1), b2 + hstepB, voffB); PG8_STAGE(PG8_SA(0, 0), a2, voffA);
;             PG8_WAIT_V(8); PG8_WAIT_L(0); PG8_BAR; PG8_MMA(1, 0, At, B0); PG8_MMA(1, 1, At, B1); PG8_BAR; PG8_SCHED;
.LBB0_1142:
	s_add_u32 s38, s16, 0x100
	s_addc_u32 s39, s17, 0
	s_mov_b32 s40, -2
	s_add_u32 s16, s14, 0x100
	s_addc_u32 s17, s15, 0
	s_add_i32 s41, 0, 0x10000
	s_cmp_eq_u32 s40, 40
	s_cselect_b32 s21, s5, s17
	s_cselect_b32 s20, s4, s16
	v_add_u32_e32 v144, s41, v139
	s_cselect_b32 s19, s13, s39
	s_cselect_b32 s18, s12, s38
	s_add_i32 s42, 0, 0x14000
	ds_read_b128 v[160:163], v144
	ds_read_b128 v[166:169], v144 offset:1024
	ds_read_b128 v[170:173], v144 offset:2048
	ds_read_b128 v[174:177], v144 offset:3072
	v_add_u32_e32 v144, s42, v139
	ds_read_b128 v[178:181], v144
	ds_read_b128 v[184:187], v144 offset:1024
	ds_read_b128 v[188:191], v144 offset:2048
	ds_read_b128 v[192:195], v144 offset:3072
	v_lshl_add_u64 v[228:229], s[14:15], 0, v[156:157]
	s_add_i32 m0, s25, 0xc000
	ds_read_b128 v[196:199], v165
	ds_read_b128 v[200:203], v165 offset:1024
	ds_read_b128 v[204:207], v165 offset:2048
	ds_read_b128 v[208:211], v165 offset:3072
	ds_read_b128 v[212:215], v165 offset:4096
	ds_read_b128 v[216:219], v165 offset:5120
	ds_read_b128 v[220:223], v165 offset:6144
	ds_read_b128 v[224:227], v165 offset:7168
	global_load_lds_dwordx4 v[228:229], off
	v_lshl_add_u64 v[228:229], s[14:15], 0, v[158:159]
	s_add_i32 m0, s25, 0xe000
	s_nop 0
	global_load_lds_dwordx4 v[228:229], off
	s_waitcnt vmcnt(8)
	s_waitcnt lgkmcnt(0)
	s_setprio 1
	s_barrier
	v_mfma_f32_16x16x32_bf16 v[126:129], v[160:163], v[196:199], 0
	v_mfma_f32_16x16x32_bf16 v[122:125], v[170:173], v[196:199], 0
	v_mfma_f32_16x16x32_bf16 v[118:121], v[160:163], v[204:207], 0
	v_mfma_f32_16x16x32_bf16 v[110:113], v[170:173], v[204:207], 0
	v_mfma_f32_16x16x32_bf16 v[102:105], v[160:163], v[212:215], 0
	v_mfma_f32_16x16x32_bf16 v[94:97], v[170:173], v[212:215], 0
	v_mfma_f32_16x16x32_bf16 v[86:89], v[160:163], v[220:223], 0
	v_mfma_f32_16x16x32_bf16 v[78:81], v[170:173], v[220:223], 0
	v_mfma_f32_16x16x32_bf16 v[126:129], v[166:169], v[200:203], v[126:129]
	v_mfma_f32_16x16x32_bf16 v[122:125], v[174:177], v[200:203], v[122:125]
	v_mfma_f32_16x16x32_bf16 v[118:121], v[166:169], v[208:211], v[118:121]
	v_mfma_f32_16x16x32_bf16 v[110:113], v[174:177], v[208:211], v[110:113]
	v_mfma_f32_16x16x32_bf16 v[102:105], v[166:169], v[216:219], v[102:105]
	v_mfma_f32_16x16x32_bf16 v[94:97], v[174:177], v[216:219], v[94:97]
	v_mfma_f32_16x16x32_bf16 v[86:89], v[166:169], v[224:227], v[86:89]
	v_mfma_f32_16x16x32_bf16 v[78:81], v[174:177], v[224:227], v[78:81]
	v_mfma_f32_16x16x32_bf16 v[114:117], v[178:181], v[196:199], 0
	v_mfma_f32_16x16x32_bf16 v[106:109], v[188:191], v[196:199], 0
	v_mfma_f32_16x16x32_bf16 v[98:101], v[178:181], v[204:207], 0
	v_mfma_f32_16x16x32_bf16 v[90:93], v[188:191], v[204:207], 0
	v_mfma_f32_16x16x32_bf16 v[82:85], v[178:181], v[212:215], 0
	v_mfma_f32_16x16x32_bf16 v[74:77], v[188:191], v[212:215], 0
	v_mfma_f32_16x16x32_bf16 v[70:73], v[178:181], v[220:223], 0
	v_mfma_f32_16x16x32_bf16 v[66:69], v[188:191], v[220:223], 0
	v_mfma_f32_16x16x32_bf16 v[114:117], v[184:187], v[200:203], v[114:117]
	v_mfma_f32_16x16x32_bf16 v[106:109], v[192:195], v[200:203], v[106:109]
	v_mfma_f32_16x16x32_bf16 v[98:101], v[184:187], v[208:211], v[98:101]
	v_mfma_f32_16x16x32_bf16 v[90:93], v[192:195], v[208:211], v[90:93]
	v_mfma_f32_16x16x32_bf16 v[82:85], v[184:187], v[216:219], v[82:85]
	v_mfma_f32_16x16x32_bf16 v[74:77], v[192:195], v[216:219], v[74:77]
	v_mfma_f32_16x16x32_bf16 v[70:73], v[184:187], v[224:227], v[70:73]
	v_mfma_f32_16x16x32_bf16 v[66:69], v[192:195], v[224:227], v[66:69]
	s_barrier
	s_setprio 0
	s_add_i32 s14, s41, s24
	v_lshl_add_u64 v[228:229], s[18:19], 0, v[132:133]
	s_mov_b32 m0, s14
	ds_read_b128 v[196:199], v165 offset:16384
	ds_read_b128 v[200:203], v165 offset:17408
	ds_read_b128 v[204:207], v165 offset:18432
	ds_read_b128 v[208:211], v165 offset:19456
	ds_read_b128 v[212:215], v165 offset:20480
	ds_read_b128 v[216:219], v165 offset:21504
	ds_read_b128 v[220:223], v165 offset:22528
	ds_read_b128 v[224:227], v165 offset:23552
	global_load_lds_dwordx4 v[228:229], off
	s_add_i32 m0, s14, 0x2000
	s_add_u32 s14, s18, 0xb0000
	v_lshl_add_u64 v[230:231], s[18:19], 0, v[154:155]
	s_addc_u32 s15, s19, 0
	s_add_i32 s41, s42, s24
	global_load_lds_dwordx4 v[230:231], off
	v_lshl_add_u64 v[232:233], s[14:15], 0, v[132:133]
	s_mov_b32 m0, s41
	v_lshl_add_u64 v[234:235], s[20:21], 0, v[134:135]
	global_load_lds_dwordx4 v[232:233], off
	v_lshl_add_u64 v[232:233], s[14:15], 0, v[154:155]
	s_add_i32 m0, s41, 0x2000
	s_nop 0
	global_load_lds_dwordx4 v[232:233], off
	v_lshl_add_u64 v[232:233], s[20:21], 0, v[130:131]
	s_mov_b32 m0, s25
	s_nop 0
	global_load_lds_dwordx4 v[232:233], off
	s_mov_b32 m0, s26
	s_nop 0
	global_load_lds_dwordx4 v[234:235], off
	s_waitcnt vmcnt(8)
	s_waitcnt lgkmcnt(0)
	s_setprio 1
	s_barrier
; #define PG8_STAGE(bufoff, gbase, voff) do { _Pragma("unroll") for (int _i = 0; _i < 2; ++_i) \
;         __builtin_amdgcn_global_load_lds((const unsigned*)((const char*)(gbase) + (voff)[_i]), (LAS unsigned*)(lds + (bufoff) + ldsw + _i * 8192), 16, 0, 0); } while (0)
; #define PG8_LDA(dst, b, h) do { _Pragma("unroll") for (int m = 0; m < 4; ++m) _Pragma("unroll") for (int k = 0; k < 2; ++k) dst[m][k] = *(const LAS bf16x8*)(lds + PG8_SA(b, h) + aoff + m * 2048 + k * 1024); } while (0)
; #define PG8_LDB(dst, b, h) do { _Pragma("unroll") for (int n = 0; n < 2; ++n) _Pragma("unroll") for (int k = 0; k < 2; ++k) dst[n][k] = *(const LAS bf16x8*)(lds + PG8_SB(b, h) + boff + n * 2048 + k * 1024); } while (0)
; #define PG8_MMA(ai, bj, At, Bt) do { __builtin_amdgcn_s_setprio(1); _Pragma("unroll") for (int m = 0; m < 4; ++m) _Pragma("unroll") for (int n = 0; n < 2; ++n) _Pragma("unroll") for (int k = 0; k < 2; ++k) \
;         acc[ai][bj][m][n] = __builtin_amdgcn_mfma_f32_16x16x32_bf16(Bt[n][k], At[m][k], acc[ai][bj][m][n], 0, 0, 0); __builtin_amdgcn_s_setprio(0); } while (0)
; #define PG8_WAIT_V(n) asm volatile("s_waitcnt vmcnt(" #n ")" ::: "memory")
; #define PG8_WAIT_L(n) asm volatile("s_waitcnt lgkmcnt(" #n ")" ::: "memory")
; #define PG8_BAR __builtin_amdgcn_s_barrier()
; #define PG8_SCHED __builtin_amdgcn_sched_barrier(0)
; template <class Epi, bool ALIGN_EPI = PG8_ALIGN, bool SP2 = PG8_SP2>
; __device__ __forceinline__ void gemm_phase(LAS uchar* lds, const Gemm g, const StaticOrder& S, const Epi& E) {
;     ...
;             PG8_WAIT_V(8); PG8_WAIT_L(0); PG8_BAR; PG8_MMA(1, 0, At, B0); PG8_MMA(1, 1, At, B1); PG8_BAR; PG8_SCHED;
;             PG8_LDB(B0, 1, 0); PG8_LDB(B1, 1, 1); PG8_SCHED; PG8_LDA(At, 1, 0); PG8_STAGE(PG8_SA(0, 1), a2 + hstepA, voffA);
;             PG8_WAIT_V(8); PG8_WAIT_L(0); PG8_BAR; PG8_MMA(0, 0, At, B0); PG8_MMA(0, 1, At, B1); PG8_BAR; PG8_SCHED;
	v_mfma_f32_16x16x32_bf16 v[62:65], v[160:163], v[196:199], 0
	v_mfma_f32_16x16x32_bf16 v[58:61], v[170:173], v[196:199], 0
	v_mfma_f32_16x16x32_bf16 v[54:57], v[160:163], v[204:207], 0
	v_mfma_f32_16x16x32_bf16 v[46:49], v[170:173], v[204:207], 0
	v_mfma_f32_16x16x32_bf16 v[38:41], v[160:163], v[212:215], 0
	v_mfma_f32_16x16x32_bf16 v[30:33], v[170:173], v[212:215], 0
	v_mfma_f32_16x16x32_bf16 v[22:25], v[160:163], v[220:223], 0
	v_mfma_f32_16x16x32_bf16 v[14:17], v[170:173], v[220:223], 0
	v_mfma_f32_16x16x32_bf16 v[62:65], v[166:169], v[200:203], v[62:65]
	v_mfma_f32_16x16x32_bf16 v[58:61], v[174:177], v[200:203], v[58:61]
	v_mfma_f32_16x16x32_bf16 v[54:57], v[166:169], v[208:211], v[54:57]
	v_mfma_f32_16x16x32_bf16 v[46:49], v[174:177], v[208:211], v[46:49]
	v_mfma_f32_16x16x32_bf16 v[38:41], v[166:169], v[216:219], v[38:41]
	v_mfma_f32_16x16x32_bf16 v[30:33], v[174:177], v[216:219], v[30:33]
	v_mfma_f32_16x16x32_bf16 v[22:25], v[166:169], v[224:227], v[22:25]
	v_mfma_f32_16x16x32_bf16 v[14:17], v[174:177], v[224:227], v[14:17]
	v_mfma_f32_16x16x32_bf16 v[50:53], v[178:181], v[196:199], 0
	v_mfma_f32_16x16x32_bf16 v[42:45], v[188:191], v[196:199], 0
	v_mfma_f32_16x16x32_bf16 v[34:37], v[178:181], v[204:207], 0
	v_mfma_f32_16x16x32_bf16 v[26:29], v[188:191], v[204:207], 0
	v_mfma_f32_16x16x32_bf16 v[18:21], v[178:181], v[212:215], 0
	v_mfma_f32_16x16x32_bf16 v[10:13], v[188:191], v[212:215], 0
	v_mfma_f32_16x16x32_bf16 v[6:9], v[178:181], v[220:223], 0
	v_mfma_f32_16x16x32_bf16 v[2:5], v[188:191], v[220:223], 0
	v_mfma_f32_16x16x32_bf16 v[50:53], v[184:187], v[200:203], v[50:53]
	v_mfma_f32_16x16x32_bf16 v[42:45], v[192:195], v[200:203], v[42:45]
	v_mfma_f32_16x16x32_bf16 v[34:37], v[184:187], v[208:211], v[34:37]
	v_mfma_f32_16x16x32_bf16 v[26:29], v[192:195], v[208:211], v[26:29]
	v_mfma_f32_16x16x32_bf16 v[18:21], v[184:187], v[216:219], v[18:21]
	v_mfma_f32_16x16x32_bf16 v[10:13], v[192:195], v[216:219], v[10:13]
	v_mfma_f32_16x16x32_bf16 v[6:9], v[184:187], v[224:227], v[6:9]
	v_mfma_f32_16x16x32_bf16 v[2:5], v[192:195], v[224:227], v[2:5]
	s_barrier
	s_setprio 0
	s_add_i32 s41, 0, 0x18000
	v_add_u32_e32 v144, s41, v139
	s_add_i32 s42, 0, 0x1c000
	ds_read_b128 v[160:163], v144
	ds_read_b128 v[166:169], v144 offset:1024
	ds_read_b128 v[170:173], v144 offset:2048
	ds_read_b128 v[174:177], v144 offset:3072
	v_add_u32_e32 v144, s42, v139
	ds_read_b128 v[178:181], v144
	ds_read_b128 v[184:187], v144 offset:1024
	ds_read_b128 v[188:191], v144 offset:2048
	ds_read_b128 v[192:195], v144 offset:3072
	s_add_u32 s14, s20, 0xb0000
	s_addc_u32 s15, s21, 0
	s_mov_b32 m0, s27
	v_lshl_add_u64 v[236:237], s[14:15], 0, v[130:131]
	ds_read_b128 v[196:199], v165 offset:32768
	ds_read_b128 v[200:203], v165 offset:33792
	ds_read_b128 v[204:207], v165 offset:34816
	ds_read_b128 v[208:211], v165 offset:35840
	ds_read_b128 v[212:215], v165 offset:36864
	ds_read_b128 v[216:219], v165 offset:37888
	ds_read_b128 v[220:223], v165 offset:38912
	ds_read_b128 v[224:227], v165 offset:39936
	global_load_lds_dwordx4 v[236:237], off
	v_lshl_add_u64 v[236:237], s[14:15], 0, v[134:135]
	s_mov_b32 m0, s28
	s_nop 0
	global_load_lds_dwordx4 v[236:237], off
	s_waitcnt vmcnt(8)
	s_waitcnt lgkmcnt(0)
	s_setprio 1
	s_barrier
	v_mfma_f32_16x16x32_bf16 v[126:129], v[160:163], v[196:199], v[126:129]
	v_mfma_f32_16x16x32_bf16 v[122:125], v[170:173], v[196:199], v[122:125]
	v_mfma_f32_16x16x32_bf16 v[118:121], v[160:163], v[204:207], v[118:121]
	v_mfma_f32_16x16x32_bf16 v[110:113], v[170:173], v[204:207], v[110:113]
	v_mfma_f32_16x16x32_bf16 v[102:105], v[160:163], v[212:215], v[102:105]
	v_mfma_f32_16x16x32_bf16 v[94:97], v[170:173], v[212:215], v[94:97]
	v_mfma_f32_16x16x32_bf16 v[86:89], v[160:163], v[220:223], v[86:89]
	v_mfma_f32_16x16x32_bf16 v[78:81], v[170:173], v[220:223], v[78:81]
	v_mfma_f32_16x16x32_bf16 v[126:129], v[166:169], v[200:203], v[126:129]
	v_mfma_f32_16x16x32_bf16 v[122:125], v[174:177], v[200:203], v[122:125]
	v_mfma_f32_16x16x32_bf16 v[118:121], v[166:169], v[208:211], v[118:121]
	v_mfma_f32_16x16x32_bf16 v[110:113], v[174:177], v[208:211], v[110:113]
	v_mfma_f32_16x16x32_bf16 v[102:105], v[166:169], v[216:219], v[102:105]
	v_mfma_f32_16x16x32_bf16 v[94:97], v[174:177], v[216:219], v[94:97]
	v_mfma_f32_16x16x32_bf16 v[86:89], v[166:169], v[224:227], v[86:89]
	v_mfma_f32_16x16x32_bf16 v[78:81], v[174:177], v[224:227], v[78:81]
	v_mfma_f32_16x16x32_bf16 v[114:117], v[178:181], v[196:199], v[114:117]
	v_mfma_f32_16x16x32_bf16 v[106:109], v[188:191], v[196:199], v[106:109]
	v_mfma_f32_16x16x32_bf16 v[98:101], v[178:181], v[204:207], v[98:101]
	v_mfma_f32_16x16x32_bf16 v[90:93], v[188:191], v[204:207], v[90:93]
	v_mfma_f32_16x16x32_bf16 v[82:85], v[178:181], v[212:215], v[82:85]
	v_mfma_f32_16x16x32_bf16 v[74:77], v[188:191], v[212:215], v[74:77]
	v_mfma_f32_16x16x32_bf16 v[70:73], v[178:181], v[220:223], v[70:73]
	v_mfma_f32_16x16x32_bf16 v[66:69], v[188:191], v[220:223], v[66:69]
	v_mfma_f32_16x16x32_bf16 v[114:117], v[184:187], v[200:203], v[114:117]
	v_mfma_f32_16x16x32_bf16 v[106:109], v[192:195], v[200:203], v[106:109]
	v_mfma_f32_16x16x32_bf16 v[98:101], v[184:187], v[208:211], v[98:101]
	v_mfma_f32_16x16x32_bf16 v[90:93], v[192:195], v[208:211], v[90:93]
	v_mfma_f32_16x16x32_bf16 v[82:85], v[184:187], v[216:219], v[82:85]
	v_mfma_f32_16x16x32_bf16 v[74:77], v[192:195], v[216:219], v[74:77]
	v_mfma_f32_16x16x32_bf16 v[70:73], v[184:187], v[224:227], v[70:73]
	v_mfma_f32_16x16x32_bf16 v[66:69], v[192:195], v[224:227], v[66:69]
	s_barrier
; #define PG8_STAGE(bufoff, gbase, voff) do { _Pragma("unroll") for (int _i = 0; _i < 2; ++_i) \
;         __builtin_amdgcn_global_load_lds((const unsigned*)((const char*)(gbase) + (voff)[_i]), (LAS unsigned*)(lds + (bufoff) + ldsw + _i * 8192), 16, 0, 0); } while (0)
; #define PG8_LDA(dst, b, h) do { _Pragma("unroll") for (int m = 0; m < 4; ++m) _Pragma("unroll") for (int k = 0; k < 2; ++k) dst[m][k] = *(const LAS bf16x8*)(lds + PG8_SA(b, h) + aoff + m * 2048 + k * 1024); } while (0)
; #define PG8_LDB(dst, b, h) do { _Pragma("unroll") for (int n = 0; n < 2; ++n) _Pragma("unroll") for (int k = 0; k < 2; ++k) dst[n][k] = *(const LAS bf16x8*)(lds + PG8_SB(b, h) + boff + n * 2048 + k * 1024); } while (0)
; #define PG8_WAIT_V(n) asm volatile("s_waitcnt vmcnt(" #n ")" ::: "memory")
; #define PG8_BAR __builtin_amdgcn_s_barrier()
; template <class Epi, bool ALIGN_EPI = PG8_ALIGN, bool SP2 = PG8_SP2>
; __device__ __forceinline__ void gemm_phase(LAS uchar* lds, const Gemm g, const StaticOrder& S, const Epi& E) {
;     ...
;             const bool last = (t == nt - 2);
;             const char* a1 = cA + (size_t)(t + 1) * kstep;
;             const char* a2 = last ? nA : cA + (size_t)(t + 2) * kstep; const char* b2 = last ? nB : cB + (size_t)(t + 2) * kstep;
;             const char* a3 = a2 + kstep; const char* b3 = b2 + kstep;
;             if constexpr (SP2) {
;             PG8_LDB(B0, 0, 0); PG8_LDB(B1, 0, 1); PG8_SCHED; PG8_LDA(At, 0, 0); PG8_STAGE(PG8_SA(1, 1), a1 + hstepA, voffA);
;             PG8_WAIT_V(8); PG8_WAIT_L(0); PG8_BAR; PG8_MMA(0, 0, At, B0); PG8_MMA(0, 1, At, B1); PG8_BAR; PG8_SCHED;
;             PG8_LDA(At, 0, 1); PG8_STAGE(PG8_SB(0, 0), b2, voffB); PG8_STAGE(PG8_SB(0, 1), b2 + hstepB, voffB); PG8_STAGE(PG8_SA(0, 0), a2, voffA);
;             PG8_WAIT_V(8); PG8_WAIT_L(0); PG8_BAR; PG8_MMA(1, 0, At, B0); PG8_MMA(1, 1, At, B1); PG8_BAR; PG8_SCHED;
;             PG8_LDB(B0, 1, 0); PG8_LDB(B1, 1, 1); PG8_SCHED; PG8_LDA(At, 1, 0); PG8_STAGE(PG8_SA(0, 1), a2 + hstepA, voffA);
;             PG8_WAIT_V(8); PG8_WAIT_L(0); PG8_BAR; PG8_MMA(0, 0, At, B0); PG8_MMA(0, 1, At, B1); PG8_BAR; PG8_SCHED;
;             PG8_LDA(At, 1, 1); PG8_STAGE(PG8_SB(1, 0), b3, voffB); PG8_STAGE(PG8_SB(1, 1), b3 + hstepB, voffB); PG8_STAGE(PG8_SA(1, 0), a3, voffA);
;             PG8_WAIT_V(8); PG8_WAIT_L(0); PG8_BAR; PG8_MMA(1, 0, At, B0); PG8_MMA(1, 1, At, B1); PG8_BAR; PG8_SCHED;
	s_setprio 0
	s_add_i32 s14, s41, s24
	v_lshl_add_u64 v[228:229], v[228:229], 0, s[84:85]
	s_mov_b32 m0, s14
	ds_read_b128 v[196:199], v165 offset:49152
	ds_read_b128 v[200:203], v165 offset:50176
	ds_read_b128 v[204:207], v165 offset:51200
	ds_read_b128 v[208:211], v165 offset:52224
	ds_read_b128 v[212:215], v165 offset:53248
	ds_read_b128 v[216:219], v165 offset:54272
	ds_read_b128 v[220:223], v165 offset:55296
	ds_read_b128 v[224:227], v165 offset:56320
	global_load_lds_dwordx4 v[228:229], off
	s_add_i32 m0, s14, 0x2000
	s_add_u32 s14, s18, 0xb0080
	v_lshl_add_u64 v[228:229], v[230:231], 0, s[84:85]
	s_addc_u32 s15, s19, 0
	s_add_i32 s18, s42, s24
	global_load_lds_dwordx4 v[228:229], off
	v_lshl_add_u64 v[228:229], s[14:15], 0, v[132:133]
	s_mov_b32 m0, s18
	s_nop 0
	global_load_lds_dwordx4 v[228:229], off
	v_lshl_add_u64 v[228:229], s[14:15], 0, v[154:155]
	s_add_i32 m0, s18, 0x2000
	s_nop 0
	global_load_lds_dwordx4 v[228:229], off
	v_lshl_add_u64 v[228:229], v[232:233], 0, s[84:85]
	s_mov_b32 m0, s29
	s_nop 0
	global_load_lds_dwordx4 v[228:229], off
	v_lshl_add_u64 v[228:229], v[234:235], 0, s[84:85]
	s_mov_b32 m0, s30
	s_nop 0
	global_load_lds_dwordx4 v[228:229], off
	s_waitcnt vmcnt(8)
	s_waitcnt lgkmcnt(0)
	s_setprio 1
	s_barrier
	v_mfma_f32_16x16x32_bf16 v[62:65], v[160:163], v[196:199], v[62:65]
	v_mfma_f32_16x16x32_bf16 v[58:61], v[170:173], v[196:199], v[58:61]
	v_mfma_f32_16x16x32_bf16 v[54:57], v[160:163], v[204:207], v[54:57]
	v_mfma_f32_16x16x32_bf16 v[46:49], v[170:173], v[204:207], v[46:49]
	v_mfma_f32_16x16x32_bf16 v[38:41], v[160:163], v[212:215], v[38:41]
	v_mfma_f32_16x16x32_bf16 v[30:33], v[170:173], v[212:215], v[30:33]
	v_mfma_f32_16x16x32_bf16 v[22:25], v[160:163], v[220:223], v[22:25]
	v_mfma_f32_16x16x32_bf16 v[14:17], v[170:173], v[220:223], v[14:17]
	v_mfma_f32_16x16x32_bf16 v[62:65], v[166:169], v[200:203], v[62:65]
	v_mfma_f32_16x16x32_bf16 v[58:61], v[174:177], v[200:203], v[58:61]
	v_mfma_f32_16x16x32_bf16 v[54:57], v[166:169], v[208:211], v[54:57]
	v_mfma_f32_16x16x32_bf16 v[46:49], v[174:177], v[208:211], v[46:49]
	v_mfma_f32_16x16x32_bf16 v[38:41], v[166:169], v[216:219], v[38:41]
	v_mfma_f32_16x16x32_bf16 v[30:33], v[174:177], v[216:219], v[30:33]
	v_mfma_f32_16x16x32_bf16 v[22:25], v[166:169], v[224:227], v[22:25]
	v_mfma_f32_16x16x32_bf16 v[14:17], v[174:177], v[224:227], v[14:17]
	v_mfma_f32_16x16x32_bf16 v[50:53], v[178:181], v[196:199], v[50:53]
	v_mfma_f32_16x16x32_bf16 v[42:45], v[188:191], v[196:199], v[42:45]
	v_mfma_f32_16x16x32_bf16 v[34:37], v[178:181], v[204:207], v[34:37]
	v_mfma_f32_16x16x32_bf16 v[26:29], v[188:191], v[204:207], v[26:29]
	v_mfma_f32_16x16x32_bf16 v[18:21], v[178:181], v[212:215], v[18:21]
	v_mfma_f32_16x16x32_bf16 v[10:13], v[188:191], v[212:215], v[10:13]
	v_mfma_f32_16x16x32_bf16 v[6:9], v[178:181], v[220:223], v[6:9]
	v_mfma_f32_16x16x32_bf16 v[2:5], v[188:191], v[220:223], v[2:5]
	v_mfma_f32_16x16x32_bf16 v[50:53], v[184:187], v[200:203], v[50:53]
	v_mfma_f32_16x16x32_bf16 v[42:45], v[192:195], v[200:203], v[42:45]
	v_mfma_f32_16x16x32_bf16 v[34:37], v[184:187], v[208:211], v[34:37]
	v_mfma_f32_16x16x32_bf16 v[26:29], v[192:195], v[208:211], v[26:29]
	v_mfma_f32_16x16x32_bf16 v[18:21], v[184:187], v[216:219], v[18:21]
	v_mfma_f32_16x16x32_bf16 v[10:13], v[192:195], v[216:219], v[10:13]
	v_mfma_f32_16x16x32_bf16 v[6:9], v[184:187], v[224:227], v[6:9]
	v_mfma_f32_16x16x32_bf16 v[2:5], v[192:195], v[224:227], v[2:5]
	s_barrier
	s_setprio 0
	s_add_i32 s40, s40, 2
	s_add_u32 s38, s38, 0x100
	s_addc_u32 s39, s39, 0
	s_cmp_gt_u32 s40, 41
	s_mov_b64 s[14:15], s[16:17]
.LBB0_1143:
	s_add_u32 s16, s14, 0x100
	s_addc_u32 s17, s15, 0
	s_add_i32 s41, 0, 0x10000
	s_cmp_eq_u32 s40, 40
	s_cselect_b32 s21, s5, s17
	s_cselect_b32 s20, s4, s16
	v_add_u32_e32 v144, s41, v139
	s_cselect_b32 s19, s13, s39
	s_cselect_b32 s18, s12, s38
	s_add_i32 s42, 0, 0x14000
	ds_read_b128 v[160:163], v144
	ds_read_b128 v[166:169], v144 offset:1024
	ds_read_b128 v[170:173], v144 offset:2048
	ds_read_b128 v[174:177], v144 offset:3072
	v_add_u32_e32 v144, s42, v139
	ds_read_b128 v[178:181], v144
	ds_read_b128 v[184:187], v144 offset:1024
	ds_read_b128 v[188:191], v144 offset:2048
	ds_read_b128 v[192:195], v144 offset:3072
	v_lshl_add_u64 v[228:229], s[14:15], 0, v[156:157]
	s_add_i32 m0, s25, 0xc000
	ds_read_b128 v[196:199], v165
	ds_read_b128 v[200:203], v165 offset:1024
	ds_read_b128 v[204:207], v165 offset:2048
	ds_read_b128 v[208:211], v165 offset:3072
	ds_read_b128 v[212:215], v165 offset:4096
	ds_read_b128 v[216:219], v165 offset:5120
	ds_read_b128 v[220:223], v165 offset:6144
	ds_read_b128 v[224:227], v165 offset:7168
	global_load_lds_dwordx4 v[228:229], off
	v_lshl_add_u64 v[228:229], s[14:15], 0, v[158:159]
	s_add_i32 m0, s25, 0xe000
	s_nop 0
	global_load_lds_dwordx4 v[228:229], off
	s_waitcnt vmcnt(8)
	s_waitcnt lgkmcnt(0)
	s_setprio 1
	s_barrier
; #define PG8_STAGE(bufoff, gbase, voff) do { _Pragma("unroll") for (int _i = 0; _i < 2; ++_i) \
;         __builtin_amdgcn_global_load_lds((const unsigned*)((const char*)(gbase) + (voff)[_i]), (LAS unsigned*)(lds + (bufoff) + ldsw + _i * 8192), 16, 0, 0); } while (0)
; #define PG8_LDA(dst, b, h) do { _Pragma("unroll") for (int m = 0; m < 4; ++m) _Pragma("unroll") for (int k = 0; k < 2; ++k) dst[m][k] = *(const LAS bf16x8*)(lds + PG8_SA(b, h) + aoff + m * 2048 + k * 1024); } while (0)
; #define PG8_MMA(ai, bj, At, Bt) do { __builtin_amdgcn_s_setprio(1); _Pragma("unroll") for (int m = 0; m < 4; ++m) _Pragma("unroll") for (int n = 0; n < 2; ++n) _Pragma("unroll") for (int k = 0; k < 2; ++k) \
;         acc[ai][bj][m][n] = __builtin_amdgcn_mfma_f32_16x16x32_bf16(Bt[n][k], At[m][k], acc[ai][bj][m][n], 0, 0, 0); __builtin_amdgcn_s_setprio(0); } while (0)
; #define PG8_WAIT_V(n) asm volatile("s_waitcnt vmcnt(" #n ")" ::: "memory")
; #define PG8_WAIT_L(n) asm volatile("s_waitcnt lgkmcnt(" #n ")" ::: "memory")
; #define PG8_BAR __builtin_amdgcn_s_barrier()
; #define PG8_SCHED __builtin_amdgcn_sched_barrier(0)
; template <class Epi, bool ALIGN_EPI = PG8_ALIGN, bool SP2 = PG8_SP2>
; __device__ __forceinline__ void gemm_phase(LAS uchar* lds, const Gemm g, const StaticOrder& S, const Epi& E) {
;     ...
;             PG8_WAIT_V(8); PG8_WAIT_L(0); PG8_BAR; PG8_MMA(0, 0, At, B0); PG8_MMA(0, 1, At, B1); PG8_BAR; PG8_SCHED;
;             PG8_LDA(At, 0, 1); PG8_STAGE(PG8_SB(0, 0), b2, voffB); PG8_STAGE(PG8_SB(0, 1), b2 + hstepB, voffB); PG8_STAGE(PG8_SA(0, 0), a2, voffA);
;             PG8_WAIT_V(8); PG8_WAIT_L(0); PG8_BAR; PG8_MMA(1, 0, At, B0); PG8_MMA(1, 1, At, B1); PG8_BAR; PG8_SCHED;
	v_mfma_f32_16x16x32_bf16 v[126:129], v[160:163], v[196:199], v[126:129]
	v_mfma_f32_16x16x32_bf16 v[122:125], v[170:173], v[196:199], v[122:125]
	v_mfma_f32_16x16x32_bf16 v[118:121], v[160:163], v[204:207], v[118:121]
	v_mfma_f32_16x16x32_bf16 v[110:113], v[170:173], v[204:207], v[110:113]
	v_mfma_f32_16x16x32_bf16 v[102:105], v[160:163], v[212:215], v[102:105]
	v_mfma_f32_16x16x32_bf16 v[94:97], v[170:173], v[212:215], v[94:97]
	v_mfma_f32_16x16x32_bf16 v[86:89], v[160:163], v[220:223], v[86:89]
	v_mfma_f32_16x16x32_bf16 v[78:81], v[170:173], v[220:223], v[78:81]
	v_mfma_f32_16x16x32_bf16 v[126:129], v[166:169], v[200:203], v[126:129]
	v_mfma_f32_16x16x32_bf16 v[122:125], v[174:177], v[200:203], v[122:125]
	v_mfma_f32_16x16x32_bf16 v[118:121], v[166:169], v[208:211], v[118:121]
	v_mfma_f32_16x16x32_bf16 v[110:113], v[174:177], v[208:211], v[110:113]
	v_mfma_f32_16x16x32_bf16 v[102:105], v[166:169], v[216:219], v[102:105]
	v_mfma_f32_16x16x32_bf16 v[94:97], v[174:177], v[216:219], v[94:97]
	v_mfma_f32_16x16x32_bf16 v[86:89], v[166:169], v[224:227], v[86:89]
	v_mfma_f32_16x16x32_bf16 v[78:81], v[174:177], v[224:227], v[78:81]
	v_mfma_f32_16x16x32_bf16 v[114:117], v[178:181], v[196:199], v[114:117]
	v_mfma_f32_16x16x32_bf16 v[106:109], v[188:191], v[196:199], v[106:109]
	v_mfma_f32_16x16x32_bf16 v[98:101], v[178:181], v[204:207], v[98:101]
	v_mfma_f32_16x16x32_bf16 v[90:93], v[188:191], v[204:207], v[90:93]
	v_mfma_f32_16x16x32_bf16 v[82:85], v[178:181], v[212:215], v[82:85]
	v_mfma_f32_16x16x32_bf16 v[74:77], v[188:191], v[212:215], v[74:77]
	v_mfma_f32_16x16x32_bf16 v[70:73], v[178:181], v[220:223], v[70:73]
	v_mfma_f32_16x16x32_bf16 v[66:69], v[188:191], v[220:223], v[66:69]
	v_mfma_f32_16x16x32_bf16 v[114:117], v[184:187], v[200:203], v[114:117]
	v_mfma_f32_16x16x32_bf16 v[106:109], v[192:195], v[200:203], v[106:109]
	v_mfma_f32_16x16x32_bf16 v[98:101], v[184:187], v[208:211], v[98:101]
	v_mfma_f32_16x16x32_bf16 v[90:93], v[192:195], v[208:211], v[90:93]
	v_mfma_f32_16x16x32_bf16 v[82:85], v[184:187], v[216:219], v[82:85]
	v_mfma_f32_16x16x32_bf16 v[74:77], v[192:195], v[216:219], v[74:77]
	v_mfma_f32_16x16x32_bf16 v[70:73], v[184:187], v[224:227], v[70:73]
	v_mfma_f32_16x16x32_bf16 v[66:69], v[192:195], v[224:227], v[66:69]
	s_barrier
	s_setprio 0
	s_add_i32 s14, s41, s24
	v_lshl_add_u64 v[228:229], s[18:19], 0, v[132:133]
	s_mov_b32 m0, s14
	ds_read_b128 v[196:199], v165 offset:16384
	ds_read_b128 v[200:203], v165 offset:17408
	ds_read_b128 v[204:207], v165 offset:18432
	ds_read_b128 v[208:211], v165 offset:19456
	ds_read_b128 v[212:215], v165 offset:20480
	ds_read_b128 v[216:219], v165 offset:21504
	ds_read_b128 v[220:223], v165 offset:22528
	ds_read_b128 v[224:227], v165 offset:23552
	global_load_lds_dwordx4 v[228:229], off
	s_add_i32 m0, s14, 0x2000
	s_add_u32 s14, s18, 0xb0000
	v_lshl_add_u64 v[230:231], s[18:19], 0, v[154:155]
	s_addc_u32 s15, s19, 0
	s_add_i32 s41, s42, s24
	global_load_lds_dwordx4 v[230:231], off
	v_lshl_add_u64 v[232:233], s[14:15], 0, v[132:133]
	s_mov_b32 m0, s41
	v_lshl_add_u64 v[234:235], s[20:21], 0, v[134:135]
	global_load_lds_dwordx4 v[232:233], off
	v_lshl_add_u64 v[232:233], s[14:15], 0, v[154:155]
	s_add_i32 m0, s41, 0x2000
	s_nop 0
	global_load_lds_dwordx4 v[232:233], off
	v_lshl_add_u64 v[232:233], s[20:21], 0, v[130:131]
	s_mov_b32 m0, s25
	s_nop 0
	global_load_lds_dwordx4 v[232:233], off
	s_mov_b32 m0, s26
	s_nop 0
	global_load_lds_dwordx4 v[234:235], off
	s_waitcnt vmcnt(8)
	s_waitcnt lgkmcnt(0)
	s_setprio 1
	s_barrier
	v_mfma_f32_16x16x32_bf16 v[62:65], v[160:163], v[196:199], v[62:65]
	v_mfma_f32_16x16x32_bf16 v[58:61], v[170:173], v[196:199], v[58:61]
	v_mfma_f32_16x16x32_bf16 v[54:57], v[160:163], v[204:207], v[54:57]
	v_mfma_f32_16x16x32_bf16 v[46:49], v[170:173], v[204:207], v[46:49]
	v_mfma_f32_16x16x32_bf16 v[38:41], v[160:163], v[212:215], v[38:41]
	v_mfma_f32_16x16x32_bf16 v[30:33], v[170:173], v[212:215], v[30:33]
	v_mfma_f32_16x16x32_bf16 v[22:25], v[160:163], v[220:223], v[22:25]
	v_mfma_f32_16x16x32_bf16 v[14:17], v[170:173], v[220:223], v[14:17]
	v_mfma_f32_16x16x32_bf16 v[62:65], v[166:169], v[200:203], v[62:65]
	v_mfma_f32_16x16x32_bf16 v[58:61], v[174:177], v[200:203], v[58:61]
	v_mfma_f32_16x16x32_bf16 v[54:57], v[166:169], v[208:211], v[54:57]
	v_mfma_f32_16x16x32_bf16 v[46:49], v[174:177], v[208:211], v[46:49]
	v_mfma_f32_16x16x32_bf16 v[38:41], v[166:169], v[216:219], v[38:41]
	v_mfma_f32_16x16x32_bf16 v[30:33], v[174:177], v[216:219], v[30:33]
	v_mfma_f32_16x16x32_bf16 v[22:25], v[166:169], v[224:227], v[22:25]
	v_mfma_f32_16x16x32_bf16 v[14:17], v[174:177], v[224:227], v[14:17]
	v_mfma_f32_16x16x32_bf16 v[50:53], v[178:181], v[196:199], v[50:53]
	v_mfma_f32_16x16x32_bf16 v[42:45], v[188:191], v[196:199], v[42:45]
	v_mfma_f32_16x16x32_bf16 v[34:37], v[178:181], v[204:207], v[34:37]
	v_mfma_f32_16x16x32_bf16 v[26:29], v[188:191], v[204:207], v[26:29]
	v_mfma_f32_16x16x32_bf16 v[18:21], v[178:181], v[212:215], v[18:21]
	v_mfma_f32_16x16x32_bf16 v[10:13], v[188:191], v[212:215], v[10:13]
	v_mfma_f32_16x16x32_bf16 v[6:9], v[178:181], v[220:223], v[6:9]
	v_mfma_f32_16x16x32_bf16 v[2:5], v[188:191], v[220:223], v[2:5]
	v_mfma_f32_16x16x32_bf16 v[50:53], v[184:187], v[200:203], v[50:53]
	v_mfma_f32_16x16x32_bf16 v[42:45], v[192:195], v[200:203], v[42:45]
	v_mfma_f32_16x16x32_bf16 v[34:37], v[184:187], v[208:211], v[34:37]
	v_mfma_f32_16x16x32_bf16 v[26:29], v[192:195], v[208:211], v[26:29]
	v_mfma_f32_16x16x32_bf16 v[18:21], v[184:187], v[216:219], v[18:21]
	v_mfma_f32_16x16x32_bf16 v[10:13], v[192:195], v[216:219], v[10:13]
	v_mfma_f32_16x16x32_bf16 v[6:9], v[184:187], v[224:227], v[6:9]
	v_mfma_f32_16x16x32_bf16 v[2:5], v[192:195], v[224:227], v[2:5]
	s_barrier
; #define PG8_STAGE(bufoff, gbase, voff) do { _Pragma("unroll") for (int _i = 0; _i < 2; ++_i) \
;         __builtin_amdgcn_global_load_lds((const unsigned*)((const char*)(gbase) + (voff)[_i]), (LAS unsigned*)(lds + (bufoff) + ldsw + _i * 8192), 16, 0, 0); } while (0)
; #define PG8_LDA(dst, b, h) do { _Pragma("unroll") for (int m = 0; m < 4; ++m) _Pragma("unroll") for (int k = 0; k < 2; ++k) dst[m][k] = *(const LAS bf16x8*)(lds + PG8_SA(b, h) + aoff + m * 2048 + k * 1024); } while (0)
; #define PG8_LDB(dst, b, h) do { _Pragma("unroll") for (int n = 0; n < 2; ++n) _Pragma("unroll") for (int k = 0; k < 2; ++k) dst[n][k] = *(const LAS bf16x8*)(lds + PG8_SB(b, h) + boff + n * 2048 + k * 1024); } while (0)
; #define PG8_MMA(ai, bj, At, Bt) do { __builtin_amdgcn_s_setprio(1); _Pragma("unroll") for (int m = 0; m < 4; ++m) _Pragma("unroll") for (int n = 0; n < 2; ++n) _Pragma("unroll") for (int k = 0; k < 2; ++k) \
;         acc[ai][bj][m][n] = __builtin_amdgcn_mfma_f32_16x16x32_bf16(Bt[n][k], At[m][k], acc[ai][bj][m][n], 0, 0, 0); __builtin_amdgcn_s_setprio(0); } while (0)
; #define PG8_WAIT_V(n) asm volatile("s_waitcnt vmcnt(" #n ")" ::: "memory")
; #define PG8_WAIT_L(n) asm volatile("s_waitcnt lgkmcnt(" #n ")" ::: "memory")
; #define PG8_BAR __builtin_amdgcn_s_barrier()
; #define PG8_SCHED __builtin_amdgcn_sched_barrier(0)
; template <class Epi, bool ALIGN_EPI = PG8_ALIGN, bool SP2 = PG8_SP2>
; __device__ __forceinline__ void gemm_phase(LAS uchar* lds, const Gemm g, const StaticOrder& S, const Epi& E) {
;     ...
;             PG8_LDB(B0, 1, 0); PG8_LDB(B1, 1, 1); PG8_SCHED; PG8_LDA(At, 1, 0); PG8_STAGE(PG8_SA(0, 1), a2 + hstepA, voffA);
;             PG8_WAIT_V(8); PG8_WAIT_L(0); PG8_BAR; PG8_MMA(0, 0, At, B0); PG8_MMA(0, 1, At, B1); PG8_BAR; PG8_SCHED;
	s_setprio 0
	s_add_i32 s41, 0, 0x18000
	v_add_u32_e32 v144, s41, v139
	s_add_i32 s42, 0, 0x1c000
	ds_read_b128 v[160:163], v144
	ds_read_b128 v[166:169], v144 offset:1024
	ds_read_b128 v[170:173], v144 offset:2048
	ds_read_b128 v[174:177], v144 offset:3072
	v_add_u32_e32 v144, s42, v139
	ds_read_b128 v[178:181], v144
	ds_read_b128 v[184:187], v144 offset:1024
	ds_read_b128 v[188:191], v144 offset:2048
	ds_read_b128 v[192:195], v144 offset:3072
	s_add_u32 s14, s20, 0xb0000
	s_addc_u32 s15, s21, 0
	s_mov_b32 m0, s27
	v_lshl_add_u64 v[236:237], s[14:15], 0, v[130:131]
	ds_read_b128 v[196:199], v165 offset:32768
	ds_read_b128 v[200:203], v165 offset:33792
	ds_read_b128 v[204:207], v165 offset:34816
	ds_read_b128 v[208:211], v165 offset:35840
	ds_read_b128 v[212:215], v165 offset:36864
	ds_read_b128 v[216:219], v165 offset:37888
	ds_read_b128 v[220:223], v165 offset:38912
	ds_read_b128 v[224:227], v165 offset:39936
	global_load_lds_dwordx4 v[236:237], off
	v_lshl_add_u64 v[236:237], s[14:15], 0, v[134:135]
	s_mov_b32 m0, s28
	s_nop 0
	global_load_lds_dwordx4 v[236:237], off
	s_waitcnt vmcnt(8)
	s_waitcnt lgkmcnt(0)
	s_setprio 1
	s_barrier
	v_mfma_f32_16x16x32_bf16 v[126:129], v[160:163], v[196:199], v[126:129]
	v_mfma_f32_16x16x32_bf16 v[122:125], v[170:173], v[196:199], v[122:125]
	v_mfma_f32_16x16x32_bf16 v[118:121], v[160:163], v[204:207], v[118:121]
	v_mfma_f32_16x16x32_bf16 v[110:113], v[170:173], v[204:207], v[110:113]
	v_mfma_f32_16x16x32_bf16 v[102:105], v[160:163], v[212:215], v[102:105]
	v_mfma_f32_16x16x32_bf16 v[94:97], v[170:173], v[212:215], v[94:97]
	v_mfma_f32_16x16x32_bf16 v[86:89], v[160:163], v[220:223], v[86:89]
	v_mfma_f32_16x16x32_bf16 v[78:81], v[170:173], v[220:223], v[78:81]
	v_mfma_f32_16x16x32_bf16 v[126:129], v[166:169], v[200:203], v[126:129]
	v_mfma_f32_16x16x32_bf16 v[122:125], v[174:177], v[200:203], v[122:125]
	v_mfma_f32_16x16x32_bf16 v[118:121], v[166:169], v[208:211], v[118:121]
	v_mfma_f32_16x16x32_bf16 v[110:113], v[174:177], v[208:211], v[110:113]
	v_mfma_f32_16x16x32_bf16 v[102:105], v[166:169], v[216:219], v[102:105]
	v_mfma_f32_16x16x32_bf16 v[94:97], v[174:177], v[216:219], v[94:97]
	v_mfma_f32_16x16x32_bf16 v[86:89], v[166:169], v[224:227], v[86:89]
	v_mfma_f32_16x16x32_bf16 v[78:81], v[174:177], v[224:227], v[78:81]
	v_mfma_f32_16x16x32_bf16 v[114:117], v[178:181], v[196:199], v[114:117]
	v_mfma_f32_16x16x32_bf16 v[106:109], v[188:191], v[196:199], v[106:109]
	v_mfma_f32_16x16x32_bf16 v[98:101], v[178:181], v[204:207], v[98:101]
	v_mfma_f32_16x16x32_bf16 v[90:93], v[188:191], v[204:207], v[90:93]
	v_mfma_f32_16x16x32_bf16 v[82:85], v[178:181], v[212:215], v[82:85]
	v_mfma_f32_16x16x32_bf16 v[74:77], v[188:191], v[212:215], v[74:77]
	v_mfma_f32_16x16x32_bf16 v[70:73], v[178:181], v[220:223], v[70:73]
	v_mfma_f32_16x16x32_bf16 v[66:69], v[188:191], v[220:223], v[66:69]
	v_mfma_f32_16x16x32_bf16 v[114:117], v[184:187], v[200:203], v[114:117]
	v_mfma_f32_16x16x32_bf16 v[106:109], v[192:195], v[200:203], v[106:109]
	v_mfma_f32_16x16x32_bf16 v[98:101], v[184:187], v[208:211], v[98:101]
	v_mfma_f32_16x16x32_bf16 v[90:93], v[192:195], v[208:211], v[90:93]
	v_mfma_f32_16x16x32_bf16 v[82:85], v[184:187], v[216:219], v[82:85]
	v_mfma_f32_16x16x32_bf16 v[74:77], v[192:195], v[216:219], v[74:77]
	v_mfma_f32_16x16x32_bf16 v[70:73], v[184:187], v[224:227], v[70:73]
	v_mfma_f32_16x16x32_bf16 v[66:69], v[192:195], v[224:227], v[66:69]
	s_barrier
; #define PG8_STAGE(bufoff, gbase, voff) do { _Pragma("unroll") for (int _i = 0; _i < 2; ++_i) \
;         __builtin_amdgcn_global_load_lds((const unsigned*)((const char*)(gbase) + (voff)[_i]), (LAS unsigned*)(lds + (bufoff) + ldsw + _i * 8192), 16, 0, 0); } while (0)
; #define PG8_LDA(dst, b, h) do { _Pragma("unroll") for (int m = 0; m < 4; ++m) _Pragma("unroll") for (int k = 0; k < 2; ++k) dst[m][k] = *(const LAS bf16x8*)(lds + PG8_SA(b, h) + aoff + m * 2048 + k * 1024); } while (0)
; #define PG8_MMA(ai, bj, At, Bt) do { __builtin_amdgcn_s_setprio(1); _Pragma("unroll") for (int m = 0; m < 4; ++m) _Pragma("unroll") for (int n = 0; n < 2; ++n) _Pragma("unroll") for (int k = 0; k < 2; ++k) \
;         acc[ai][bj][m][n] = __builtin_amdgcn_mfma_f32_16x16x32_bf16(Bt[n][k], At[m][k], acc[ai][bj][m][n], 0, 0, 0); __builtin_amdgcn_s_setprio(0); } while (0)
; #define PG8_WAIT_V(n) asm volatile("s_waitcnt vmcnt(" #n ")" ::: "memory")
; #define PG8_WAIT_L(n) asm volatile("s_waitcnt lgkmcnt(" #n ")" ::: "memory")
; #define PG8_BAR __builtin_amdgcn_s_barrier()
; #define PG8_SCHED __builtin_amdgcn_sched_barrier(0)
; template <class Epi, bool ALIGN_EPI = PG8_ALIGN, bool SP2 = PG8_SP2>
; __device__ __forceinline__ void gemm_phase(LAS uchar* lds, const Gemm g, const StaticOrder& S, const Epi& E) {
;     ...
;             PG8_LDA(At, 1, 1); PG8_STAGE(PG8_SB(1, 0), b3, voffB); PG8_STAGE(PG8_SB(1, 1), b3 + hstepB, voffB); PG8_STAGE(PG8_SA(1, 0), a3, voffA);
;             PG8_WAIT_V(8); PG8_WAIT_L(0); PG8_BAR; PG8_MMA(1, 0, At, B0); PG8_MMA(1, 1, At, B1); PG8_BAR; PG8_SCHED;
	s_setprio 0
	s_add_i32 s14, s41, s24
	v_lshl_add_u64 v[228:229], v[228:229], 0, s[84:85]
	s_mov_b32 m0, s14
	ds_read_b128 v[196:199], v165 offset:49152
	ds_read_b128 v[200:203], v165 offset:50176
	ds_read_b128 v[204:207], v165 offset:51200
	ds_read_b128 v[208:211], v165 offset:52224
	ds_read_b128 v[212:215], v165 offset:53248
	ds_read_b128 v[216:219], v165 offset:54272
	ds_read_b128 v[220:223], v165 offset:55296
	ds_read_b128 v[224:227], v165 offset:56320
	global_load_lds_dwordx4 v[228:229], off
	s_add_i32 m0, s14, 0x2000
	s_add_u32 s14, s18, 0xb0080
	v_lshl_add_u64 v[228:229], v[230:231], 0, s[84:85]
	s_addc_u32 s15, s19, 0
	s_add_i32 s18, s42, s24
	global_load_lds_dwordx4 v[228:229], off
	v_lshl_add_u64 v[228:229], s[14:15], 0, v[132:133]
	s_mov_b32 m0, s18
	s_nop 0
	global_load_lds_dwordx4 v[228:229], off
	v_lshl_add_u64 v[228:229], s[14:15], 0, v[154:155]
	s_add_i32 m0, s18, 0x2000
	s_nop 0
	global_load_lds_dwordx4 v[228:229], off
	v_lshl_add_u64 v[228:229], v[232:233], 0, s[84:85]
	s_mov_b32 m0, s29
	s_nop 0
	global_load_lds_dwordx4 v[228:229], off
	v_lshl_add_u64 v[228:229], v[234:235], 0, s[84:85]
	s_mov_b32 m0, s30
	s_nop 0
	global_load_lds_dwordx4 v[228:229], off
	s_waitcnt vmcnt(8)
	s_waitcnt lgkmcnt(0)
	s_setprio 1
	s_barrier
	v_mfma_f32_16x16x32_bf16 v[62:65], v[160:163], v[196:199], v[62:65]
	v_mfma_f32_16x16x32_bf16 v[58:61], v[170:173], v[196:199], v[58:61]
	v_mfma_f32_16x16x32_bf16 v[54:57], v[160:163], v[204:207], v[54:57]
	v_mfma_f32_16x16x32_bf16 v[46:49], v[170:173], v[204:207], v[46:49]
	v_mfma_f32_16x16x32_bf16 v[38:41], v[160:163], v[212:215], v[38:41]
	v_mfma_f32_16x16x32_bf16 v[30:33], v[170:173], v[212:215], v[30:33]
	v_mfma_f32_16x16x32_bf16 v[22:25], v[160:163], v[220:223], v[22:25]
	v_mfma_f32_16x16x32_bf16 v[14:17], v[170:173], v[220:223], v[14:17]
	v_mfma_f32_16x16x32_bf16 v[62:65], v[166:169], v[200:203], v[62:65]
	v_mfma_f32_16x16x32_bf16 v[58:61], v[174:177], v[200:203], v[58:61]
	v_mfma_f32_16x16x32_bf16 v[54:57], v[166:169], v[208:211], v[54:57]
	v_mfma_f32_16x16x32_bf16 v[46:49], v[174:177], v[208:211], v[46:49]
	v_mfma_f32_16x16x32_bf16 v[38:41], v[166:169], v[216:219], v[38:41]
	v_mfma_f32_16x16x32_bf16 v[30:33], v[174:177], v[216:219], v[30:33]
	v_mfma_f32_16x16x32_bf16 v[22:25], v[166:169], v[224:227], v[22:25]
	v_mfma_f32_16x16x32_bf16 v[14:17], v[174:177], v[224:227], v[14:17]
	v_mfma_f32_16x16x32_bf16 v[50:53], v[178:181], v[196:199], v[50:53]
	v_mfma_f32_16x16x32_bf16 v[42:45], v[188:191], v[196:199], v[42:45]
	v_mfma_f32_16x16x32_bf16 v[34:37], v[178:181], v[204:207], v[34:37]
	v_mfma_f32_16x16x32_bf16 v[26:29], v[188:191], v[204:207], v[26:29]
	v_mfma_f32_16x16x32_bf16 v[18:21], v[178:181], v[212:215], v[18:21]
	v_mfma_f32_16x16x32_bf16 v[10:13], v[188:191], v[212:215], v[10:13]
	v_mfma_f32_16x16x32_bf16 v[6:9], v[178:181], v[220:223], v[6:9]
	v_mfma_f32_16x16x32_bf16 v[2:5], v[188:191], v[220:223], v[2:5]
	v_mfma_f32_16x16x32_bf16 v[50:53], v[184:187], v[200:203], v[50:53]
	v_mfma_f32_16x16x32_bf16 v[42:45], v[192:195], v[200:203], v[42:45]
	v_mfma_f32_16x16x32_bf16 v[34:37], v[184:187], v[208:211], v[34:37]
	v_mfma_f32_16x16x32_bf16 v[26:29], v[192:195], v[208:211], v[26:29]
	v_mfma_f32_16x16x32_bf16 v[18:21], v[184:187], v[216:219], v[18:21]
	v_mfma_f32_16x16x32_bf16 v[10:13], v[192:195], v[216:219], v[10:13]
	v_mfma_f32_16x16x32_bf16 v[6:9], v[184:187], v[224:227], v[6:9]
	v_mfma_f32_16x16x32_bf16 v[2:5], v[192:195], v[224:227], v[2:5]
	s_barrier
	s_setprio 0
	s_add_i32 s40, s40, 2
	s_add_u32 s38, s38, 0x100
	s_addc_u32 s39, s39, 0
	s_cmp_gt_u32 s40, 41
	s_mov_b64 s[14:15], s[16:17]
	s_cbranch_scc0 .LBB0_1143
	s_and_b64 vcc, exec, s[10:11]
	s_cbranch_vccz .LBB0_1146
	s_barrier
